# segment-edge cleanup: removed back-to-back s_setprio 0/1 pairs between the two MFMA blocks of each GEMM super-phase
# speedup vs baseline: 1.0015x; 1.0015x over previous
; #define PG8_STAGE(bufoff, gbase, voff) do { _Pragma("unroll") for (int _i = 0; _i < 2; ++_i) \
;         __builtin_amdgcn_global_load_lds((const unsigned*)((const char*)(gbase) + (voff)[_i]), (PG8_LAS unsigned*)(lds + (bufoff) + ldsw + _i * 8192), 16, 0, 0); } while (0)
; #define PG8_LDA(dst, b, h) do { _Pragma("unroll") for (int m = 0; m < 4; ++m) _Pragma("unroll") for (int k = 0; k < 2; ++k) dst[m][k] = *(const PG8_LAS bf16x8*)(lds + PG8_SA(b, h) + aoff + m * 2048 + k * 1024); } while (0)
; #define PG8_LDB(dst, b, h) do { _Pragma("unroll") for (int n = 0; n < 2; ++n) _Pragma("unroll") for (int k = 0; k < 2; ++k) dst[n][k] = *(const PG8_LAS bf16x8*)(lds + PG8_SB(b, h) + boff + n * 2048 + k * 1024); } while (0)
; #define PG8_MMA(ai, bj, At, Bt) do { __builtin_amdgcn_s_setprio(1); _Pragma("unroll") for (int m = 0; m < 4; ++m) _Pragma("unroll") for (int n = 0; n < 2; ++n) _Pragma("unroll") for (int k = 0; k < 2; ++k) \
;         acc[ai][bj][m][n] = __builtin_amdgcn_mfma_f32_16x16x32_bf16(Bt[n][k], At[m][k], acc[ai][bj][m][n], 0, 0, 0); __builtin_amdgcn_s_setprio(0); } while (0)
; #define PG8_WAIT_V(n) asm volatile("s_waitcnt vmcnt(" #n ")" ::: "memory")
; #define PG8_WAIT_L(n) asm volatile("s_waitcnt lgkmcnt(" #n ")" ::: "memory")
; #define PG8_BAR __builtin_amdgcn_s_barrier()
; #define PG8_SCHED __builtin_amdgcn_sched_barrier(0)
; template <class Epi, class Sched, bool ALIGN_EPI = false, bool SP2 = false>
; __device__ __forceinline__ void gemm_phase(PG8_LAS unsigned char* lds, const Gemm g, const Sched& S, const Epi& E) {
;     ...
;             PG8_LDB(B0, 0, 0); PG8_LDB(B1, 0, 1); PG8_SCHED; PG8_LDA(At, 0, 0); PG8_STAGE(PG8_SA(1, 1), a1 + hstep, voffA);
;             PG8_WAIT_V(8); PG8_WAIT_L(0); PG8_BAR; PG8_MMA(0, 0, At, B0); PG8_MMA(0, 1, At, B1); PG8_BAR; PG8_SCHED;
;             PG8_LDA(At, 0, 1); PG8_STAGE(PG8_SB(0, 0), b2, voffB); PG8_STAGE(PG8_SB(0, 1), b2 + hstep, voffB); PG8_STAGE(PG8_SA(0, 0), a2, voffA);
;             PG8_WAIT_V(8); PG8_WAIT_L(0); PG8_BAR; PG8_MMA(1, 0, At, B0); PG8_MMA(1, 1, At, B1); PG8_BAR; PG8_SCHED;
.LBB0_128:
	s_add_u32 s34, s8, 0xfff80080
	s_addc_u32 s35, s9, -1
	s_add_i32 s83, 0, 0x10000
	s_cmp_eq_u32 s82, 28
	s_cselect_b32 s41, s27, s35
	s_cselect_b32 s40, s78, s34
	v_add_u32_e32 v146, s83, v147
	s_cselect_b32 s35, s25, s81
	s_cselect_b32 s34, s79, s80
	s_add_i32 s84, 0, 0x14000
	ds_read_b128 v[142:145], v146
	ds_read_b128 v[162:165], v146 offset:1024
	ds_read_b128 v[166:169], v146 offset:2048
	ds_read_b128 v[170:173], v146 offset:3072
	v_add_u32_e32 v146, s84, v147
	ds_read_b128 v[174:177], v146
	ds_read_b128 v[178:181], v146 offset:1024
	ds_read_b128 v[182:185], v146 offset:2048
	ds_read_b128 v[186:189], v146 offset:3072
	s_add_i32 m0, s49, 0xc000
	ds_read_b128 v[190:193], v152
	ds_read_b128 v[194:197], v152 offset:1024
	ds_read_b128 v[198:201], v152 offset:2048
	ds_read_b128 v[202:205], v152 offset:3072
	ds_read_b128 v[230:233], v152 offset:4096
	ds_read_b128 v[234:237], v152 offset:5120
	ds_read_b128 v[238:241], v152 offset:6144
	ds_read_b128 v[242:245], v152 offset:7168
	global_load_lds_dwordx4 v140, s[8:9]
	s_add_i32 m0, s49, 0xe000
	s_nop 0
	global_load_lds_dwordx4 v138, s[8:9]
	s_waitcnt vmcnt(8)
	s_waitcnt lgkmcnt(0)
	s_barrier
	s_setprio 1
	s_waitcnt lgkmcnt(0)
	v_mfma_f32_16x16x32_bf16 v[130:133], v[142:145], v[190:193], v[130:133]
	v_mfma_f32_16x16x32_bf16 v[122:125], v[166:169], v[190:193], v[122:125]
	v_mfma_f32_16x16x32_bf16 v[114:117], v[142:145], v[198:201], v[114:117]
	v_mfma_f32_16x16x32_bf16 v[106:109], v[166:169], v[198:201], v[106:109]
	v_mfma_f32_16x16x32_bf16 v[98:101], v[142:145], v[230:233], v[98:101]
	v_mfma_f32_16x16x32_bf16 v[90:93], v[166:169], v[230:233], v[90:93]
	v_mfma_f32_16x16x32_bf16 v[82:85], v[142:145], v[238:241], v[82:85]
	v_mfma_f32_16x16x32_bf16 v[74:77], v[166:169], v[238:241], v[74:77]
	v_mfma_f32_16x16x32_bf16 v[130:133], v[162:165], v[194:197], v[130:133]
	v_mfma_f32_16x16x32_bf16 v[122:125], v[170:173], v[194:197], v[122:125]
	v_mfma_f32_16x16x32_bf16 v[114:117], v[162:165], v[202:205], v[114:117]
	v_mfma_f32_16x16x32_bf16 v[106:109], v[170:173], v[202:205], v[106:109]
	v_mfma_f32_16x16x32_bf16 v[98:101], v[162:165], v[234:237], v[98:101]
	v_mfma_f32_16x16x32_bf16 v[90:93], v[170:173], v[234:237], v[90:93]
	v_mfma_f32_16x16x32_bf16 v[82:85], v[162:165], v[242:245], v[82:85]
	v_mfma_f32_16x16x32_bf16 v[74:77], v[170:173], v[242:245], v[74:77]
	v_mfma_f32_16x16x32_bf16 v[126:129], v[174:177], v[190:193], v[126:129]
	v_mfma_f32_16x16x32_bf16 v[118:121], v[182:185], v[190:193], v[118:121]
	v_mfma_f32_16x16x32_bf16 v[110:113], v[174:177], v[198:201], v[110:113]
	v_mfma_f32_16x16x32_bf16 v[102:105], v[182:185], v[198:201], v[102:105]
	v_mfma_f32_16x16x32_bf16 v[94:97], v[174:177], v[230:233], v[94:97]
	v_mfma_f32_16x16x32_bf16 v[86:89], v[182:185], v[230:233], v[86:89]
	v_mfma_f32_16x16x32_bf16 v[78:81], v[174:177], v[238:241], v[78:81]
	v_mfma_f32_16x16x32_bf16 v[70:73], v[182:185], v[238:241], v[70:73]
	v_mfma_f32_16x16x32_bf16 v[126:129], v[178:181], v[194:197], v[126:129]
	v_mfma_f32_16x16x32_bf16 v[118:121], v[186:189], v[194:197], v[118:121]
	v_mfma_f32_16x16x32_bf16 v[110:113], v[178:181], v[202:205], v[110:113]
	v_mfma_f32_16x16x32_bf16 v[102:105], v[186:189], v[202:205], v[102:105]
	v_mfma_f32_16x16x32_bf16 v[94:97], v[178:181], v[234:237], v[94:97]
	v_mfma_f32_16x16x32_bf16 v[86:89], v[186:189], v[234:237], v[86:89]
	v_mfma_f32_16x16x32_bf16 v[78:81], v[178:181], v[242:245], v[78:81]
	v_mfma_f32_16x16x32_bf16 v[70:73], v[186:189], v[242:245], v[70:73]
	s_setprio 0
	s_barrier
	s_add_i32 s83, s83, s48
	s_mov_b32 m0, s83
	ds_read_b128 v[190:193], v152 offset:16384
	ds_read_b128 v[194:197], v152 offset:17408
	ds_read_b128 v[198:201], v152 offset:18432
	ds_read_b128 v[202:205], v152 offset:19456
	ds_read_b128 v[230:233], v152 offset:20480
	ds_read_b128 v[234:237], v152 offset:21504
	ds_read_b128 v[238:241], v152 offset:22528
	ds_read_b128 v[242:245], v152 offset:23552
	global_load_lds_dwordx4 v2, s[34:35]
	s_add_i32 m0, s83, 0x2000
	s_add_u32 s86, s34, 0x80000
	s_addc_u32 s87, s35, 0
	s_add_i32 s83, s84, s48
	global_load_lds_dwordx4 v0, s[34:35]
	s_mov_b32 m0, s83
	v_lshl_add_u64 v[250:251], s[40:41], 0, v[134:135]
	global_load_lds_dwordx4 v2, s[86:87]
	s_add_i32 m0, s83, 0x2000
	s_nop 0
	global_load_lds_dwordx4 v0, s[86:87]
	v_lshl_add_u64 v[248:249], s[40:41], 0, v[136:137]
	s_mov_b32 m0, s49
	s_nop 0
	global_load_lds_dwordx4 v136, s[40:41]
	s_mov_b32 m0, s51
	s_nop 0
	global_load_lds_dwordx4 v134, s[40:41]
	s_waitcnt vmcnt(8)
	s_waitcnt lgkmcnt(0)
	s_barrier
	s_setprio 1
	s_waitcnt lgkmcnt(0)
	v_mfma_f32_16x16x32_bf16 v[66:69], v[142:145], v[190:193], v[66:69]
	v_mfma_f32_16x16x32_bf16 v[58:61], v[166:169], v[190:193], v[58:61]
	v_mfma_f32_16x16x32_bf16 v[50:53], v[142:145], v[198:201], v[50:53]
	v_mfma_f32_16x16x32_bf16 v[42:45], v[166:169], v[198:201], v[42:45]
	v_mfma_f32_16x16x32_bf16 v[34:37], v[142:145], v[230:233], v[34:37]
	v_mfma_f32_16x16x32_bf16 v[26:29], v[166:169], v[230:233], v[26:29]
	v_mfma_f32_16x16x32_bf16 v[18:21], v[142:145], v[238:241], v[18:21]
	v_mfma_f32_16x16x32_bf16 v[10:13], v[166:169], v[238:241], v[10:13]
	v_mfma_f32_16x16x32_bf16 v[66:69], v[162:165], v[194:197], v[66:69]
	v_mfma_f32_16x16x32_bf16 v[58:61], v[170:173], v[194:197], v[58:61]
	v_mfma_f32_16x16x32_bf16 v[50:53], v[162:165], v[202:205], v[50:53]
	v_mfma_f32_16x16x32_bf16 v[42:45], v[170:173], v[202:205], v[42:45]
	v_mfma_f32_16x16x32_bf16 v[34:37], v[162:165], v[234:237], v[34:37]
	v_mfma_f32_16x16x32_bf16 v[26:29], v[170:173], v[234:237], v[26:29]
	v_mfma_f32_16x16x32_bf16 v[18:21], v[162:165], v[242:245], v[18:21]
	v_mfma_f32_16x16x32_bf16 v[10:13], v[170:173], v[242:245], v[10:13]
	v_mfma_f32_16x16x32_bf16 v[62:65], v[174:177], v[190:193], v[62:65]
	v_mfma_f32_16x16x32_bf16 v[54:57], v[182:185], v[190:193], v[54:57]
	v_mfma_f32_16x16x32_bf16 v[46:49], v[174:177], v[198:201], v[46:49]
	v_mfma_f32_16x16x32_bf16 v[38:41], v[182:185], v[198:201], v[38:41]
	v_mfma_f32_16x16x32_bf16 v[30:33], v[174:177], v[230:233], v[30:33]
	v_mfma_f32_16x16x32_bf16 v[22:25], v[182:185], v[230:233], v[22:25]
	v_mfma_f32_16x16x32_bf16 v[14:17], v[174:177], v[238:241], v[14:17]
	v_mfma_f32_16x16x32_bf16 v[6:9], v[182:185], v[238:241], v[6:9]
	v_mfma_f32_16x16x32_bf16 v[62:65], v[178:181], v[194:197], v[62:65]
	v_mfma_f32_16x16x32_bf16 v[54:57], v[186:189], v[194:197], v[54:57]
	v_mfma_f32_16x16x32_bf16 v[46:49], v[178:181], v[202:205], v[46:49]
	v_mfma_f32_16x16x32_bf16 v[38:41], v[186:189], v[202:205], v[38:41]
	v_mfma_f32_16x16x32_bf16 v[30:33], v[178:181], v[234:237], v[30:33]
	v_mfma_f32_16x16x32_bf16 v[22:25], v[186:189], v[234:237], v[22:25]
	v_mfma_f32_16x16x32_bf16 v[14:17], v[178:181], v[242:245], v[14:17]
	v_mfma_f32_16x16x32_bf16 v[6:9], v[186:189], v[242:245], v[6:9]
	s_setprio 0
	s_barrier
; #define PG8_STAGE(bufoff, gbase, voff) do { _Pragma("unroll") for (int _i = 0; _i < 2; ++_i) \
;         __builtin_amdgcn_global_load_lds((const unsigned*)((const char*)(gbase) + (voff)[_i]), (PG8_LAS unsigned*)(lds + (bufoff) + ldsw + _i * 8192), 16, 0, 0); } while (0)
; #define PG8_LDA(dst, b, h) do { _Pragma("unroll") for (int m = 0; m < 4; ++m) _Pragma("unroll") for (int k = 0; k < 2; ++k) dst[m][k] = *(const PG8_LAS bf16x8*)(lds + PG8_SA(b, h) + aoff + m * 2048 + k * 1024); } while (0)
; #define PG8_LDB(dst, b, h) do { _Pragma("unroll") for (int n = 0; n < 2; ++n) _Pragma("unroll") for (int k = 0; k < 2; ++k) dst[n][k] = *(const PG8_LAS bf16x8*)(lds + PG8_SB(b, h) + boff + n * 2048 + k * 1024); } while (0)
; #define PG8_MMA(ai, bj, At, Bt) do { __builtin_amdgcn_s_setprio(1); _Pragma("unroll") for (int m = 0; m < 4; ++m) _Pragma("unroll") for (int n = 0; n < 2; ++n) _Pragma("unroll") for (int k = 0; k < 2; ++k) \
;         acc[ai][bj][m][n] = __builtin_amdgcn_mfma_f32_16x16x32_bf16(Bt[n][k], At[m][k], acc[ai][bj][m][n], 0, 0, 0); __builtin_amdgcn_s_setprio(0); } while (0)
; #define PG8_WAIT_V(n) asm volatile("s_waitcnt vmcnt(" #n ")" ::: "memory")
; #define PG8_WAIT_L(n) asm volatile("s_waitcnt lgkmcnt(" #n ")" ::: "memory")
; #define PG8_BAR __builtin_amdgcn_s_barrier()
; #define PG8_SCHED __builtin_amdgcn_sched_barrier(0)
; template <class Epi, class Sched, bool ALIGN_EPI = false, bool SP2 = false>
; __device__ __forceinline__ void gemm_phase(PG8_LAS unsigned char* lds, const Gemm g, const Sched& S, const Epi& E) {
;     ...
;             PG8_LDB(B0, 1, 0); PG8_LDB(B1, 1, 1); PG8_SCHED; PG8_LDA(At, 1, 0); PG8_STAGE(PG8_SA(0, 1), a2 + hstep, voffA);
;             PG8_WAIT_V(8); PG8_WAIT_L(0); PG8_BAR; PG8_MMA(0, 0, At, B0); PG8_MMA(0, 1, At, B1); PG8_BAR; PG8_SCHED;
;             PG8_LDA(At, 1, 1); PG8_STAGE(PG8_SB(1, 0), b3, voffB); PG8_STAGE(PG8_SB(1, 1), b3 + hstep, voffB); PG8_STAGE(PG8_SA(1, 0), a3, voffA);
;             PG8_WAIT_V(8); PG8_WAIT_L(0); PG8_BAR; PG8_MMA(1, 0, At, B0); PG8_MMA(1, 1, At, B1); PG8_BAR; PG8_SCHED;
;     ...
;         if constexpr (ALIGN_EPI) { if (wr == 0) PG8_BAR; }
	s_add_i32 s83, 0, 0x18000
	v_add_u32_e32 v146, s83, v147
	s_add_i32 s84, 0, 0x1c000
	ds_read_b128 v[142:145], v146
	ds_read_b128 v[162:165], v146 offset:1024
	ds_read_b128 v[166:169], v146 offset:2048
	ds_read_b128 v[170:173], v146 offset:3072
	v_add_u32_e32 v146, s84, v147
	ds_read_b128 v[174:177], v146
	ds_read_b128 v[178:181], v146 offset:1024
	ds_read_b128 v[182:185], v146 offset:2048
	ds_read_b128 v[186:189], v146 offset:3072
	s_add_u32 s40, s40, 0x80000
	s_addc_u32 s41, s41, 0
	s_mov_b32 m0, s52
	ds_read_b128 v[190:193], v152 offset:32768
	ds_read_b128 v[194:197], v152 offset:33792
	ds_read_b128 v[198:201], v152 offset:34816
	ds_read_b128 v[202:205], v152 offset:35840
	ds_read_b128 v[230:233], v152 offset:36864
	ds_read_b128 v[234:237], v152 offset:37888
	ds_read_b128 v[238:241], v152 offset:38912
	ds_read_b128 v[242:245], v152 offset:39936
	global_load_lds_dwordx4 v136, s[40:41]
	s_mov_b32 m0, s53
	s_nop 0
	global_load_lds_dwordx4 v134, s[40:41]
	s_waitcnt vmcnt(8)
	s_waitcnt lgkmcnt(0)
	s_barrier
	s_setprio 1
	s_waitcnt lgkmcnt(0)
	v_mfma_f32_16x16x32_bf16 v[130:133], v[142:145], v[190:193], v[130:133]
	v_mfma_f32_16x16x32_bf16 v[122:125], v[166:169], v[190:193], v[122:125]
	v_mfma_f32_16x16x32_bf16 v[114:117], v[142:145], v[198:201], v[114:117]
	v_mfma_f32_16x16x32_bf16 v[106:109], v[166:169], v[198:201], v[106:109]
	v_mfma_f32_16x16x32_bf16 v[98:101], v[142:145], v[230:233], v[98:101]
	v_mfma_f32_16x16x32_bf16 v[90:93], v[166:169], v[230:233], v[90:93]
	v_mfma_f32_16x16x32_bf16 v[82:85], v[142:145], v[238:241], v[82:85]
	v_mfma_f32_16x16x32_bf16 v[74:77], v[166:169], v[238:241], v[74:77]
	v_mfma_f32_16x16x32_bf16 v[130:133], v[162:165], v[194:197], v[130:133]
	v_mfma_f32_16x16x32_bf16 v[122:125], v[170:173], v[194:197], v[122:125]
	v_mfma_f32_16x16x32_bf16 v[114:117], v[162:165], v[202:205], v[114:117]
	v_mfma_f32_16x16x32_bf16 v[106:109], v[170:173], v[202:205], v[106:109]
	v_mfma_f32_16x16x32_bf16 v[98:101], v[162:165], v[234:237], v[98:101]
	v_mfma_f32_16x16x32_bf16 v[90:93], v[170:173], v[234:237], v[90:93]
	v_mfma_f32_16x16x32_bf16 v[82:85], v[162:165], v[242:245], v[82:85]
	v_mfma_f32_16x16x32_bf16 v[74:77], v[170:173], v[242:245], v[74:77]
	v_mfma_f32_16x16x32_bf16 v[126:129], v[174:177], v[190:193], v[126:129]
	v_mfma_f32_16x16x32_bf16 v[118:121], v[182:185], v[190:193], v[118:121]
	v_mfma_f32_16x16x32_bf16 v[110:113], v[174:177], v[198:201], v[110:113]
	v_mfma_f32_16x16x32_bf16 v[102:105], v[182:185], v[198:201], v[102:105]
	v_mfma_f32_16x16x32_bf16 v[94:97], v[174:177], v[230:233], v[94:97]
	v_mfma_f32_16x16x32_bf16 v[86:89], v[182:185], v[230:233], v[86:89]
	v_mfma_f32_16x16x32_bf16 v[78:81], v[174:177], v[238:241], v[78:81]
	v_mfma_f32_16x16x32_bf16 v[70:73], v[182:185], v[238:241], v[70:73]
	v_mfma_f32_16x16x32_bf16 v[126:129], v[178:181], v[194:197], v[126:129]
	v_mfma_f32_16x16x32_bf16 v[118:121], v[186:189], v[194:197], v[118:121]
	v_mfma_f32_16x16x32_bf16 v[110:113], v[178:181], v[202:205], v[110:113]
	v_mfma_f32_16x16x32_bf16 v[102:105], v[186:189], v[202:205], v[102:105]
	v_mfma_f32_16x16x32_bf16 v[94:97], v[178:181], v[234:237], v[94:97]
	v_mfma_f32_16x16x32_bf16 v[86:89], v[186:189], v[234:237], v[86:89]
	v_mfma_f32_16x16x32_bf16 v[78:81], v[178:181], v[242:245], v[78:81]
	v_mfma_f32_16x16x32_bf16 v[70:73], v[186:189], v[242:245], v[70:73]
	s_setprio 0
	s_barrier
	s_add_u32 vcc_lo, s34, s2
	s_addc_u32 vcc_hi, s35, s3
	s_add_i32 s40, s83, s48
	s_mov_b32 m0, s40
	ds_read_b128 v[190:193], v152 offset:49152
	ds_read_b128 v[194:197], v152 offset:50176
	ds_read_b128 v[198:201], v152 offset:51200
	ds_read_b128 v[202:205], v152 offset:52224
	ds_read_b128 v[230:233], v152 offset:53248
	ds_read_b128 v[234:237], v152 offset:54272
	ds_read_b128 v[238:241], v152 offset:55296
	ds_read_b128 v[242:245], v152 offset:56320
	global_load_lds_dwordx4 v2, vcc
	s_add_i32 m0, s40, 0x2000
	s_add_u32 s34, s34, 0x80080
	s_addc_u32 s35, s35, 0
	s_add_i32 s40, s84, s48
	global_load_lds_dwordx4 v0, vcc
	s_mov_b32 m0, s40
	s_nop 0
	global_load_lds_dwordx4 v2, s[34:35]
	s_add_i32 m0, s40, 0x2000
	s_nop 0
	global_load_lds_dwordx4 v0, s[34:35]
	v_lshl_add_u64 v[158:159], v[248:249], 0, s[2:3]
	s_mov_b32 m0, s66
	s_nop 0
	global_load_lds_dwordx4 v[158:159], off
	v_lshl_add_u64 v[158:159], v[250:251], 0, s[2:3]
	s_mov_b32 m0, s67
	s_nop 0
	global_load_lds_dwordx4 v[158:159], off
	s_waitcnt vmcnt(8)
	s_waitcnt lgkmcnt(0)
	s_barrier
	s_setprio 1
	s_waitcnt lgkmcnt(0)
	v_mfma_f32_16x16x32_bf16 v[66:69], v[142:145], v[190:193], v[66:69]
	v_mfma_f32_16x16x32_bf16 v[58:61], v[166:169], v[190:193], v[58:61]
	v_mfma_f32_16x16x32_bf16 v[50:53], v[142:145], v[198:201], v[50:53]
	v_mfma_f32_16x16x32_bf16 v[42:45], v[166:169], v[198:201], v[42:45]
	v_mfma_f32_16x16x32_bf16 v[34:37], v[142:145], v[230:233], v[34:37]
	v_mfma_f32_16x16x32_bf16 v[26:29], v[166:169], v[230:233], v[26:29]
	v_mfma_f32_16x16x32_bf16 v[18:21], v[142:145], v[238:241], v[18:21]
	v_mfma_f32_16x16x32_bf16 v[10:13], v[166:169], v[238:241], v[10:13]
	v_mfma_f32_16x16x32_bf16 v[66:69], v[162:165], v[194:197], v[66:69]
	v_mfma_f32_16x16x32_bf16 v[58:61], v[170:173], v[194:197], v[58:61]
	v_mfma_f32_16x16x32_bf16 v[50:53], v[162:165], v[202:205], v[50:53]
	v_mfma_f32_16x16x32_bf16 v[42:45], v[170:173], v[202:205], v[42:45]
	v_mfma_f32_16x16x32_bf16 v[34:37], v[162:165], v[234:237], v[34:37]
	v_mfma_f32_16x16x32_bf16 v[26:29], v[170:173], v[234:237], v[26:29]
	v_mfma_f32_16x16x32_bf16 v[18:21], v[162:165], v[242:245], v[18:21]
	v_mfma_f32_16x16x32_bf16 v[10:13], v[170:173], v[242:245], v[10:13]
	v_mfma_f32_16x16x32_bf16 v[62:65], v[174:177], v[190:193], v[62:65]
	v_mfma_f32_16x16x32_bf16 v[54:57], v[182:185], v[190:193], v[54:57]
	v_mfma_f32_16x16x32_bf16 v[46:49], v[174:177], v[198:201], v[46:49]
	v_mfma_f32_16x16x32_bf16 v[38:41], v[182:185], v[198:201], v[38:41]
	v_mfma_f32_16x16x32_bf16 v[30:33], v[174:177], v[230:233], v[30:33]
	v_mfma_f32_16x16x32_bf16 v[22:25], v[182:185], v[230:233], v[22:25]
	v_mfma_f32_16x16x32_bf16 v[14:17], v[174:177], v[238:241], v[14:17]
	v_mfma_f32_16x16x32_bf16 v[6:9], v[182:185], v[238:241], v[6:9]
	v_mfma_f32_16x16x32_bf16 v[62:65], v[178:181], v[194:197], v[62:65]
	v_mfma_f32_16x16x32_bf16 v[54:57], v[186:189], v[194:197], v[54:57]
	v_mfma_f32_16x16x32_bf16 v[46:49], v[178:181], v[202:205], v[46:49]
	v_mfma_f32_16x16x32_bf16 v[38:41], v[186:189], v[202:205], v[38:41]
	v_mfma_f32_16x16x32_bf16 v[30:33], v[178:181], v[234:237], v[30:33]
	v_mfma_f32_16x16x32_bf16 v[22:25], v[186:189], v[234:237], v[22:25]
	v_mfma_f32_16x16x32_bf16 v[14:17], v[178:181], v[242:245], v[14:17]
	v_mfma_f32_16x16x32_bf16 v[6:9], v[186:189], v[242:245], v[6:9]
	s_setprio 0
	s_barrier
	s_add_i32 s82, s82, 2
	s_add_u32 s80, s80, 0x100
	s_addc_u32 s81, s81, 0
	s_add_u32 s8, s8, 0x100
	s_addc_u32 s9, s9, 0
	s_cmp_gt_u32 s82, 29
	s_cbranch_scc0 .LBB0_128
	s_and_b64 vcc, exec, s[22:23]
	s_cbranch_vccz .LBB0_131
	s_barrier

; #define PG8_STAGE(bufoff, gbase, voff) do { _Pragma("unroll") for (int _i = 0; _i < 2; ++_i) \
;         __builtin_amdgcn_global_load_lds((const unsigned*)((const char*)(gbase) + (voff)[_i]), (PG8_LAS unsigned*)(lds + (bufoff) + ldsw + _i * 8192), 16, 0, 0); } while (0)
; #define PG8_LDA(dst, b, h) do { _Pragma("unroll") for (int m = 0; m < 4; ++m) _Pragma("unroll") for (int k = 0; k < 2; ++k) dst[m][k] = *(const PG8_LAS bf16x8*)(lds + PG8_SA(b, h) + aoff + m * 2048 + k * 1024); } while (0)
; #define PG8_LDB(dst, b, h) do { _Pragma("unroll") for (int n = 0; n < 2; ++n) _Pragma("unroll") for (int k = 0; k < 2; ++k) dst[n][k] = *(const PG8_LAS bf16x8*)(lds + PG8_SB(b, h) + boff + n * 2048 + k * 1024); } while (0)
; #define PG8_MMA(ai, bj, At, Bt) do { __builtin_amdgcn_s_setprio(1); _Pragma("unroll") for (int m = 0; m < 4; ++m) _Pragma("unroll") for (int n = 0; n < 2; ++n) _Pragma("unroll") for (int k = 0; k < 2; ++k) \
;         acc[ai][bj][m][n] = __builtin_amdgcn_mfma_f32_16x16x32_bf16(Bt[n][k], At[m][k], acc[ai][bj][m][n], 0, 0, 0); __builtin_amdgcn_s_setprio(0); } while (0)
; #define PG8_WAIT_V(n) asm volatile("s_waitcnt vmcnt(" #n ")" ::: "memory")
; #define PG8_WAIT_L(n) asm volatile("s_waitcnt lgkmcnt(" #n ")" ::: "memory")
; #define PG8_BAR __builtin_amdgcn_s_barrier()
; #define PG8_SCHED __builtin_amdgcn_sched_barrier(0)
; template <class Epi, class Sched, bool ALIGN_EPI = false, bool SP2 = false>
; __device__ __forceinline__ void gemm_phase(PG8_LAS unsigned char* lds, const Gemm g, const Sched& S, const Epi& E) {
;     ...
;             PG8_LDB(B0, 0, 0); PG8_LDB(B1, 0, 1); PG8_SCHED; PG8_LDA(At, 0, 0); PG8_STAGE(PG8_SA(1, 1), a1 + hstep, voffA);
;             PG8_WAIT_V(8); PG8_WAIT_L(0); PG8_BAR; PG8_MMA(0, 0, At, B0); PG8_MMA(0, 1, At, B1); PG8_BAR; PG8_SCHED;
;             PG8_LDA(At, 0, 1); PG8_STAGE(PG8_SB(0, 0), b2, voffB); PG8_STAGE(PG8_SB(0, 1), b2 + hstep, voffB); PG8_STAGE(PG8_SA(0, 0), a2, voffA);
;             PG8_WAIT_V(8); PG8_WAIT_L(0); PG8_BAR; PG8_MMA(1, 0, At, B0); PG8_MMA(1, 1, At, B1); PG8_BAR; PG8_SCHED;
.LBB0_235:
	s_add_u32 s10, s30, 0x100
	s_addc_u32 s11, s31, 0
	s_add_i32 s84, 0, 0x10000
	s_cmpk_eq_i32 s83, 0x54
	s_cselect_b32 s41, s29, s11
	s_cselect_b32 s40, s28, s10
	s_cselect_b32 s35, s1, s82
	s_cselect_b32 s34, s0, s81
	s_add_i32 s86, 0, 0x14000
	v_add_u32_e32 v62, s84, v152
	v_add_u32_e32 v158, s86, v152
	ds_read_b128 v[50:53], v62
	ds_read_b128 v[54:57], v62 offset:1024
	ds_read_b128 v[58:61], v62 offset:2048
	ds_read_b128 v[62:65], v62 offset:3072
	ds_read_b128 v[166:169], v158
	ds_read_b128 v[170:173], v158 offset:1024
	ds_read_b128 v[178:181], v158 offset:2048
	ds_read_b128 v[182:185], v158 offset:3072
	s_add_i32 m0, s51, 0xc000
	ds_read_b128 v[186:189], v177
	ds_read_b128 v[190:193], v177 offset:1024
	ds_read_b128 v[194:197], v177 offset:2048
	ds_read_b128 v[198:201], v177 offset:3072
	ds_read_b128 v[202:205], v177 offset:4096
	ds_read_b128 v[230:233], v177 offset:5120
	ds_read_b128 v[234:237], v177 offset:6144
	ds_read_b128 v[238:241], v177 offset:7168
	global_load_lds_dwordx4 v164, s[30:31]
	s_add_i32 m0, s51, 0xe000
	s_nop 0
	global_load_lds_dwordx4 v162, s[30:31]
	s_waitcnt vmcnt(8)
	s_waitcnt lgkmcnt(0)
	s_barrier
	s_setprio 1
	s_waitcnt lgkmcnt(0)
	v_mfma_f32_16x16x32_bf16 v[146:149], v[50:53], v[186:189], v[146:149]
	v_mfma_f32_16x16x32_bf16 v[142:145], v[58:61], v[186:189], v[142:145]
	v_mfma_f32_16x16x32_bf16 v[130:133], v[50:53], v[194:197], v[130:133]
	v_mfma_f32_16x16x32_bf16 v[126:129], v[58:61], v[194:197], v[126:129]
	v_mfma_f32_16x16x32_bf16 v[114:117], v[50:53], v[202:205], v[114:117]
	v_mfma_f32_16x16x32_bf16 v[110:113], v[58:61], v[202:205], v[110:113]
	v_mfma_f32_16x16x32_bf16 v[98:101], v[50:53], v[234:237], v[98:101]
	v_mfma_f32_16x16x32_bf16 v[94:97], v[58:61], v[234:237], v[94:97]
	v_mfma_f32_16x16x32_bf16 v[146:149], v[54:57], v[190:193], v[146:149]
	v_mfma_f32_16x16x32_bf16 v[142:145], v[62:65], v[190:193], v[142:145]
	v_mfma_f32_16x16x32_bf16 v[130:133], v[54:57], v[198:201], v[130:133]
	v_mfma_f32_16x16x32_bf16 v[126:129], v[62:65], v[198:201], v[126:129]
	v_mfma_f32_16x16x32_bf16 v[114:117], v[54:57], v[230:233], v[114:117]
	v_mfma_f32_16x16x32_bf16 v[110:113], v[62:65], v[230:233], v[110:113]
	v_mfma_f32_16x16x32_bf16 v[98:101], v[54:57], v[238:241], v[98:101]
	v_mfma_f32_16x16x32_bf16 v[94:97], v[62:65], v[238:241], v[94:97]
	v_mfma_f32_16x16x32_bf16 v[138:141], v[166:169], v[186:189], v[138:141]
	v_mfma_f32_16x16x32_bf16 v[134:137], v[178:181], v[186:189], v[134:137]
	v_mfma_f32_16x16x32_bf16 v[122:125], v[166:169], v[194:197], v[122:125]
	v_mfma_f32_16x16x32_bf16 v[118:121], v[178:181], v[194:197], v[118:121]
	v_mfma_f32_16x16x32_bf16 v[106:109], v[166:169], v[202:205], v[106:109]
	v_mfma_f32_16x16x32_bf16 v[102:105], v[178:181], v[202:205], v[102:105]
	v_mfma_f32_16x16x32_bf16 v[90:93], v[166:169], v[234:237], v[90:93]
	v_mfma_f32_16x16x32_bf16 v[86:89], v[178:181], v[234:237], v[86:89]
	v_mfma_f32_16x16x32_bf16 v[138:141], v[170:173], v[190:193], v[138:141]
	v_mfma_f32_16x16x32_bf16 v[134:137], v[182:185], v[190:193], v[134:137]
	v_mfma_f32_16x16x32_bf16 v[122:125], v[170:173], v[198:201], v[122:125]
	v_mfma_f32_16x16x32_bf16 v[118:121], v[182:185], v[198:201], v[118:121]
	v_mfma_f32_16x16x32_bf16 v[106:109], v[170:173], v[230:233], v[106:109]
	v_mfma_f32_16x16x32_bf16 v[102:105], v[182:185], v[230:233], v[102:105]
	v_mfma_f32_16x16x32_bf16 v[90:93], v[170:173], v[238:241], v[90:93]
	v_mfma_f32_16x16x32_bf16 v[86:89], v[182:185], v[238:241], v[86:89]
	s_setprio 0
	s_barrier
	s_add_i32 s30, s84, s49
	s_mov_b32 m0, s30
	ds_read_b128 v[186:189], v177 offset:16384
	ds_read_b128 v[190:193], v177 offset:17408
	ds_read_b128 v[194:197], v177 offset:18432
	ds_read_b128 v[198:201], v177 offset:19456
	ds_read_b128 v[202:205], v177 offset:20480
	ds_read_b128 v[230:233], v177 offset:21504
	ds_read_b128 v[234:237], v177 offset:22528
	ds_read_b128 v[238:241], v177 offset:23552
	global_load_lds_dwordx4 v2, s[34:35]
	s_add_i32 m0, s30, 0x2000
	s_add_u32 s30, s34, 0x160000
	s_addc_u32 s31, s35, 0
	s_add_i32 s84, s86, s49
	global_load_lds_dwordx4 v0, s[34:35]
	s_mov_b32 m0, s84
	s_nop 0
	global_load_lds_dwordx4 v2, s[30:31]
	s_add_i32 m0, s84, 0x2000
	s_nop 0
	global_load_lds_dwordx4 v0, s[30:31]
	s_mov_b32 m0, s51
	s_nop 0
	global_load_lds_dwordx4 v2, s[40:41]
	s_mov_b32 m0, s52
	s_nop 0
	global_load_lds_dwordx4 v0, s[40:41]
	s_waitcnt vmcnt(8)
	s_waitcnt lgkmcnt(0)
	s_barrier
	s_setprio 1
	s_waitcnt lgkmcnt(0)
	v_mfma_f32_16x16x32_bf16 v[82:85], v[50:53], v[186:189], v[82:85]
	v_mfma_f32_16x16x32_bf16 v[78:81], v[58:61], v[186:189], v[78:81]
	v_mfma_f32_16x16x32_bf16 v[66:69], v[50:53], v[194:197], v[66:69]
	v_mfma_f32_16x16x32_bf16 v[46:49], v[58:61], v[194:197], v[46:49]
	v_mfma_f32_16x16x32_bf16 v[34:37], v[50:53], v[202:205], v[34:37]
	v_mfma_f32_16x16x32_bf16 v[30:33], v[58:61], v[202:205], v[30:33]
	v_mfma_f32_16x16x32_bf16 v[18:21], v[50:53], v[234:237], v[18:21]
	v_mfma_f32_16x16x32_bf16 v[14:17], v[58:61], v[234:237], v[14:17]
	v_mfma_f32_16x16x32_bf16 v[82:85], v[54:57], v[190:193], v[82:85]
	v_mfma_f32_16x16x32_bf16 v[78:81], v[62:65], v[190:193], v[78:81]
	v_mfma_f32_16x16x32_bf16 v[66:69], v[54:57], v[198:201], v[66:69]
	v_mfma_f32_16x16x32_bf16 v[46:49], v[62:65], v[198:201], v[46:49]
	v_mfma_f32_16x16x32_bf16 v[34:37], v[54:57], v[230:233], v[34:37]
	v_mfma_f32_16x16x32_bf16 v[30:33], v[62:65], v[230:233], v[30:33]
	v_mfma_f32_16x16x32_bf16 v[18:21], v[54:57], v[238:241], v[18:21]
	v_mfma_f32_16x16x32_bf16 v[14:17], v[62:65], v[238:241], v[14:17]
	v_mfma_f32_16x16x32_bf16 v[42:45], v[166:169], v[194:197], v[42:45]
	v_mfma_f32_16x16x32_bf16 v[38:41], v[178:181], v[194:197], v[38:41]
	v_mfma_f32_16x16x32_bf16 v[26:29], v[166:169], v[202:205], v[26:29]
	v_mfma_f32_16x16x32_bf16 v[22:25], v[178:181], v[202:205], v[22:25]
	v_mfma_f32_16x16x32_bf16 v[10:13], v[166:169], v[234:237], v[10:13]
	v_mfma_f32_16x16x32_bf16 v[6:9], v[178:181], v[234:237], v[6:9]
	v_mfma_f32_16x16x32_bf16 v[50:53], v[166:169], v[186:189], v[74:77]
	v_mfma_f32_16x16x32_bf16 v[54:57], v[178:181], v[186:189], v[70:73]
	v_mfma_f32_16x16x32_bf16 v[42:45], v[170:173], v[198:201], v[42:45]
	v_mfma_f32_16x16x32_bf16 v[38:41], v[182:185], v[198:201], v[38:41]
	v_mfma_f32_16x16x32_bf16 v[26:29], v[170:173], v[230:233], v[26:29]
	v_mfma_f32_16x16x32_bf16 v[22:25], v[182:185], v[230:233], v[22:25]
	v_mfma_f32_16x16x32_bf16 v[10:13], v[170:173], v[238:241], v[10:13]
	v_mfma_f32_16x16x32_bf16 v[6:9], v[182:185], v[238:241], v[6:9]
	v_mfma_f32_16x16x32_bf16 v[50:53], v[170:173], v[190:193], v[50:53]
	v_mfma_f32_16x16x32_bf16 v[54:57], v[182:185], v[190:193], v[54:57]
	s_setprio 0
	s_barrier
; #define PG8_STAGE(bufoff, gbase, voff) do { _Pragma("unroll") for (int _i = 0; _i < 2; ++_i) \
;         __builtin_amdgcn_global_load_lds((const unsigned*)((const char*)(gbase) + (voff)[_i]), (PG8_LAS unsigned*)(lds + (bufoff) + ldsw + _i * 8192), 16, 0, 0); } while (0)
; #define PG8_LDA(dst, b, h) do { _Pragma("unroll") for (int m = 0; m < 4; ++m) _Pragma("unroll") for (int k = 0; k < 2; ++k) dst[m][k] = *(const PG8_LAS bf16x8*)(lds + PG8_SA(b, h) + aoff + m * 2048 + k * 1024); } while (0)
; #define PG8_LDB(dst, b, h) do { _Pragma("unroll") for (int n = 0; n < 2; ++n) _Pragma("unroll") for (int k = 0; k < 2; ++k) dst[n][k] = *(const PG8_LAS bf16x8*)(lds + PG8_SB(b, h) + boff + n * 2048 + k * 1024); } while (0)
; #define PG8_MMA(ai, bj, At, Bt) do { __builtin_amdgcn_s_setprio(1); _Pragma("unroll") for (int m = 0; m < 4; ++m) _Pragma("unroll") for (int n = 0; n < 2; ++n) _Pragma("unroll") for (int k = 0; k < 2; ++k) \
;         acc[ai][bj][m][n] = __builtin_amdgcn_mfma_f32_16x16x32_bf16(Bt[n][k], At[m][k], acc[ai][bj][m][n], 0, 0, 0); __builtin_amdgcn_s_setprio(0); } while (0)
; #define PG8_WAIT_V(n) asm volatile("s_waitcnt vmcnt(" #n ")" ::: "memory")
; #define PG8_WAIT_L(n) asm volatile("s_waitcnt lgkmcnt(" #n ")" ::: "memory")
; #define PG8_BAR __builtin_amdgcn_s_barrier()
; #define PG8_SCHED __builtin_amdgcn_sched_barrier(0)
; template <class Epi, class Sched, bool ALIGN_EPI = false, bool SP2 = false>
; __device__ __forceinline__ void gemm_phase(PG8_LAS unsigned char* lds, const Gemm g, const Sched& S, const Epi& E) {
;     ...
;             PG8_LDB(B0, 1, 0); PG8_LDB(B1, 1, 1); PG8_SCHED; PG8_LDA(At, 1, 0); PG8_STAGE(PG8_SA(0, 1), a2 + hstep, voffA);
;             PG8_WAIT_V(8); PG8_WAIT_L(0); PG8_BAR; PG8_MMA(0, 0, At, B0); PG8_MMA(0, 1, At, B1); PG8_BAR; PG8_SCHED;
	s_add_i32 s84, 0, 0x18000
	s_add_i32 s86, 0, 0x1c000
	v_add_u32_e32 v74, s84, v152
	v_add_u32_e32 v160, s86, v152
	ds_read_b128 v[58:61], v74
	ds_read_b128 v[62:65], v74 offset:1024
	ds_read_b128 v[70:73], v74 offset:2048
	ds_read_b128 v[74:77], v74 offset:3072
	ds_read_b128 v[166:169], v160
	ds_read_b128 v[170:173], v160 offset:1024
	ds_read_b128 v[178:181], v160 offset:2048
	ds_read_b128 v[182:185], v160 offset:3072
	s_add_u32 s30, s40, 0x160000
	s_addc_u32 s31, s41, 0
	s_mov_b32 m0, s53
	ds_read_b128 v[186:189], v177 offset:32768
	ds_read_b128 v[190:193], v177 offset:33792
	ds_read_b128 v[194:197], v177 offset:34816
	ds_read_b128 v[198:201], v177 offset:35840
	ds_read_b128 v[202:205], v177 offset:36864
	ds_read_b128 v[230:233], v177 offset:37888
	ds_read_b128 v[234:237], v177 offset:38912
	ds_read_b128 v[238:241], v177 offset:39936
	global_load_lds_dwordx4 v2, s[30:31]
	s_mov_b32 m0, s66
	s_nop 0
	global_load_lds_dwordx4 v0, s[30:31]
	s_waitcnt vmcnt(8)
	s_waitcnt lgkmcnt(0)
	s_barrier
	s_setprio 1
	s_waitcnt lgkmcnt(0)
	v_mfma_f32_16x16x32_bf16 v[146:149], v[58:61], v[186:189], v[146:149]
	v_mfma_f32_16x16x32_bf16 v[142:145], v[70:73], v[186:189], v[142:145]
	v_mfma_f32_16x16x32_bf16 v[130:133], v[58:61], v[194:197], v[130:133]
	v_mfma_f32_16x16x32_bf16 v[126:129], v[70:73], v[194:197], v[126:129]
	v_mfma_f32_16x16x32_bf16 v[114:117], v[58:61], v[202:205], v[114:117]
	v_mfma_f32_16x16x32_bf16 v[110:113], v[70:73], v[202:205], v[110:113]
	v_mfma_f32_16x16x32_bf16 v[98:101], v[58:61], v[234:237], v[98:101]
	v_mfma_f32_16x16x32_bf16 v[94:97], v[70:73], v[234:237], v[94:97]
	v_mfma_f32_16x16x32_bf16 v[146:149], v[62:65], v[190:193], v[146:149]
	v_mfma_f32_16x16x32_bf16 v[142:145], v[74:77], v[190:193], v[142:145]
	v_mfma_f32_16x16x32_bf16 v[130:133], v[62:65], v[198:201], v[130:133]
	v_mfma_f32_16x16x32_bf16 v[126:129], v[74:77], v[198:201], v[126:129]
	v_mfma_f32_16x16x32_bf16 v[114:117], v[62:65], v[230:233], v[114:117]
	v_mfma_f32_16x16x32_bf16 v[110:113], v[74:77], v[230:233], v[110:113]
	v_mfma_f32_16x16x32_bf16 v[98:101], v[62:65], v[238:241], v[98:101]
	v_mfma_f32_16x16x32_bf16 v[94:97], v[74:77], v[238:241], v[94:97]
	v_mfma_f32_16x16x32_bf16 v[138:141], v[166:169], v[186:189], v[138:141]
	v_mfma_f32_16x16x32_bf16 v[134:137], v[178:181], v[186:189], v[134:137]
	v_mfma_f32_16x16x32_bf16 v[122:125], v[166:169], v[194:197], v[122:125]
	v_mfma_f32_16x16x32_bf16 v[118:121], v[178:181], v[194:197], v[118:121]
	v_mfma_f32_16x16x32_bf16 v[106:109], v[166:169], v[202:205], v[106:109]
	v_mfma_f32_16x16x32_bf16 v[102:105], v[178:181], v[202:205], v[102:105]
	v_mfma_f32_16x16x32_bf16 v[90:93], v[166:169], v[234:237], v[90:93]
	v_mfma_f32_16x16x32_bf16 v[86:89], v[178:181], v[234:237], v[86:89]
	v_mfma_f32_16x16x32_bf16 v[138:141], v[170:173], v[190:193], v[138:141]
	v_mfma_f32_16x16x32_bf16 v[134:137], v[182:185], v[190:193], v[134:137]
	v_mfma_f32_16x16x32_bf16 v[122:125], v[170:173], v[198:201], v[122:125]
	v_mfma_f32_16x16x32_bf16 v[118:121], v[182:185], v[198:201], v[118:121]
	v_mfma_f32_16x16x32_bf16 v[106:109], v[170:173], v[230:233], v[106:109]
	v_mfma_f32_16x16x32_bf16 v[102:105], v[182:185], v[230:233], v[102:105]
	v_mfma_f32_16x16x32_bf16 v[90:93], v[170:173], v[238:241], v[90:93]
	v_mfma_f32_16x16x32_bf16 v[86:89], v[182:185], v[238:241], v[86:89]
	s_setprio 0
	s_barrier
; #define PG8_STAGE(bufoff, gbase, voff) do { _Pragma("unroll") for (int _i = 0; _i < 2; ++_i) \
;         __builtin_amdgcn_global_load_lds((const unsigned*)((const char*)(gbase) + (voff)[_i]), (PG8_LAS unsigned*)(lds + (bufoff) + ldsw + _i * 8192), 16, 0, 0); } while (0)
; #define PG8_LDA(dst, b, h) do { _Pragma("unroll") for (int m = 0; m < 4; ++m) _Pragma("unroll") for (int k = 0; k < 2; ++k) dst[m][k] = *(const PG8_LAS bf16x8*)(lds + PG8_SA(b, h) + aoff + m * 2048 + k * 1024); } while (0)
; #define PG8_MMA(ai, bj, At, Bt) do { __builtin_amdgcn_s_setprio(1); _Pragma("unroll") for (int m = 0; m < 4; ++m) _Pragma("unroll") for (int n = 0; n < 2; ++n) _Pragma("unroll") for (int k = 0; k < 2; ++k) \
;         acc[ai][bj][m][n] = __builtin_amdgcn_mfma_f32_16x16x32_bf16(Bt[n][k], At[m][k], acc[ai][bj][m][n], 0, 0, 0); __builtin_amdgcn_s_setprio(0); } while (0)
; #define PG8_WAIT_V(n) asm volatile("s_waitcnt vmcnt(" #n ")" ::: "memory")
; #define PG8_WAIT_L(n) asm volatile("s_waitcnt lgkmcnt(" #n ")" ::: "memory")
; #define PG8_BAR __builtin_amdgcn_s_barrier()
; #define PG8_SCHED __builtin_amdgcn_sched_barrier(0)
;     __device__ __forceinline__ void operator()(const f32x4 (&acc)[2][2][4][2], const Unit& u, int wr, int wc, int fr, int fq) const {
;     ...
;             for (int n = 0; n < 2; ++n) gv[bj][n] = xg ? *(const f32x4*)(gn + col0 + bj * HALF + n * 16) : (f32x4){0.f, 0.f, 0.f, 0.f};
; template <class Epi, class Sched, bool ALIGN_EPI = false, bool SP2 = false>
; __device__ __forceinline__ void gemm_phase(PG8_LAS unsigned char* lds, const Gemm g, const Sched& S, const Epi& E) {
;     ...
;             PG8_LDA(At, 1, 1); PG8_STAGE(PG8_SB(1, 0), b3, voffB); PG8_STAGE(PG8_SB(1, 1), b3 + hstep, voffB); PG8_STAGE(PG8_SA(1, 0), a3, voffA);
;             PG8_WAIT_V(8); PG8_WAIT_L(0); PG8_BAR; PG8_MMA(1, 0, At, B0); PG8_MMA(1, 1, At, B1); PG8_BAR; PG8_SCHED;
	s_add_u32 vcc_lo, s34, s2
	s_addc_u32 vcc_hi, s35, s3
	s_add_i32 s30, s84, s49
	s_mov_b32 m0, s30
	ds_read_b128 v[186:189], v177 offset:49152
	ds_read_b128 v[190:193], v177 offset:50176
	ds_read_b128 v[194:197], v177 offset:51200
	ds_read_b128 v[198:201], v177 offset:52224
	ds_read_b128 v[202:205], v177 offset:53248
	ds_read_b128 v[230:233], v177 offset:54272
	ds_read_b128 v[234:237], v177 offset:55296
	ds_read_b128 v[238:241], v177 offset:56320
	global_load_lds_dwordx4 v2, vcc
	s_add_i32 m0, s30, 0x2000
	s_add_u32 s30, s34, 0x160080
	s_addc_u32 s31, s35, 0
	s_add_i32 s34, s86, s49
	global_load_lds_dwordx4 v0, vcc
	s_mov_b32 m0, s34
	s_nop 0
	global_load_lds_dwordx4 v2, s[30:31]
	s_add_i32 m0, s34, 0x2000
	s_nop 0
	global_load_lds_dwordx4 v0, s[30:31]
	s_add_u32 vcc_lo, s40, s2
	s_addc_u32 vcc_hi, s41, s3
	s_mov_b32 m0, s67
	s_nop 0
	global_load_lds_dwordx4 v2, vcc
	s_mov_b32 m0, s69
	s_nop 0
	global_load_lds_dwordx4 v0, vcc
	s_waitcnt vmcnt(8)
	s_waitcnt lgkmcnt(0)
	s_barrier
	s_setprio 1
	s_waitcnt lgkmcnt(0)
	v_mfma_f32_16x16x32_bf16 v[82:85], v[58:61], v[186:189], v[82:85]
	v_mfma_f32_16x16x32_bf16 v[78:81], v[70:73], v[186:189], v[78:81]
	v_mfma_f32_16x16x32_bf16 v[66:69], v[58:61], v[194:197], v[66:69]
	v_mfma_f32_16x16x32_bf16 v[46:49], v[70:73], v[194:197], v[46:49]
	v_mfma_f32_16x16x32_bf16 v[34:37], v[58:61], v[202:205], v[34:37]
	v_mfma_f32_16x16x32_bf16 v[30:33], v[70:73], v[202:205], v[30:33]
	v_mfma_f32_16x16x32_bf16 v[18:21], v[58:61], v[234:237], v[18:21]
	v_mfma_f32_16x16x32_bf16 v[14:17], v[70:73], v[234:237], v[14:17]
	v_mfma_f32_16x16x32_bf16 v[82:85], v[62:65], v[190:193], v[82:85]
	v_mfma_f32_16x16x32_bf16 v[78:81], v[74:77], v[190:193], v[78:81]
	v_mfma_f32_16x16x32_bf16 v[66:69], v[62:65], v[198:201], v[66:69]
	v_mfma_f32_16x16x32_bf16 v[46:49], v[74:77], v[198:201], v[46:49]
	v_mfma_f32_16x16x32_bf16 v[34:37], v[62:65], v[230:233], v[34:37]
	v_mfma_f32_16x16x32_bf16 v[30:33], v[74:77], v[230:233], v[30:33]
	v_mfma_f32_16x16x32_bf16 v[18:21], v[62:65], v[238:241], v[18:21]
	v_mfma_f32_16x16x32_bf16 v[14:17], v[74:77], v[238:241], v[14:17]
	v_mfma_f32_16x16x32_bf16 v[50:53], v[166:169], v[186:189], v[50:53]
	v_mfma_f32_16x16x32_bf16 v[74:77], v[170:173], v[190:193], v[50:53]
	v_mfma_f32_16x16x32_bf16 v[50:53], v[178:181], v[186:189], v[54:57]
	v_mfma_f32_16x16x32_bf16 v[42:45], v[166:169], v[194:197], v[42:45]
	v_mfma_f32_16x16x32_bf16 v[38:41], v[178:181], v[194:197], v[38:41]
	v_mfma_f32_16x16x32_bf16 v[26:29], v[166:169], v[202:205], v[26:29]
	v_mfma_f32_16x16x32_bf16 v[22:25], v[178:181], v[202:205], v[22:25]
	v_mfma_f32_16x16x32_bf16 v[10:13], v[166:169], v[234:237], v[10:13]
	v_mfma_f32_16x16x32_bf16 v[6:9], v[178:181], v[234:237], v[6:9]
	v_mfma_f32_16x16x32_bf16 v[70:73], v[182:185], v[190:193], v[50:53]
	v_mfma_f32_16x16x32_bf16 v[42:45], v[170:173], v[198:201], v[42:45]
	v_mfma_f32_16x16x32_bf16 v[38:41], v[182:185], v[198:201], v[38:41]
	v_mfma_f32_16x16x32_bf16 v[26:29], v[170:173], v[230:233], v[26:29]
	v_mfma_f32_16x16x32_bf16 v[22:25], v[182:185], v[230:233], v[22:25]
	v_mfma_f32_16x16x32_bf16 v[10:13], v[170:173], v[238:241], v[10:13]
	v_mfma_f32_16x16x32_bf16 v[6:9], v[182:185], v[238:241], v[6:9]
	s_setprio 0
	s_barrier
	s_add_i32 s83, s83, 2
	s_add_u32 s81, s81, 0x100
	s_addc_u32 s82, s82, 0
	s_cmpk_gt_u32 s83, 0x55
	s_mov_b64 s[30:31], s[10:11]
	s_cbranch_scc0 .LBB0_235
	v_lshl_or_b32 v170, s80, 8, v176
	v_ashrrev_i32_e32 v171, 31, v170
	v_mov_b32_e32 v54, 0
	v_cndmask_b32_e64 v50, 0, 1, s[20:21]
	v_lshl_add_u64 v[166:167], v[170:171], 2, s[24:25]
	v_cmp_ne_u32_e64 s[10:11], 1, v50
	s_andn2_b64 vcc, exec, s[20:21]
	v_mov_b32_e32 v62, 0
	v_mov_b32_e32 v63, v54
	v_mov_b32_e32 v64, 0
	v_mov_b32_e32 v65, 0
	s_cbranch_vccnz .LBB0_238
	global_load_dwordx4 v[62:65], v[166:167], off

; #define PG8_STAGE(bufoff, gbase, voff) do { _Pragma("unroll") for (int _i = 0; _i < 2; ++_i) \
;         __builtin_amdgcn_global_load_lds((const unsigned*)((const char*)(gbase) + (voff)[_i]), (PG8_LAS unsigned*)(lds + (bufoff) + ldsw + _i * 8192), 16, 0, 0); } while (0)
; #define PG8_LDA(dst, b, h) do { _Pragma("unroll") for (int m = 0; m < 4; ++m) _Pragma("unroll") for (int k = 0; k < 2; ++k) dst[m][k] = *(const PG8_LAS bf16x8*)(lds + PG8_SA(b, h) + aoff + m * 2048 + k * 1024); } while (0)
; #define PG8_LDB(dst, b, h) do { _Pragma("unroll") for (int n = 0; n < 2; ++n) _Pragma("unroll") for (int k = 0; k < 2; ++k) dst[n][k] = *(const PG8_LAS bf16x8*)(lds + PG8_SB(b, h) + boff + n * 2048 + k * 1024); } while (0)
; #define PG8_MMA(ai, bj, At, Bt) do { __builtin_amdgcn_s_setprio(1); _Pragma("unroll") for (int m = 0; m < 4; ++m) _Pragma("unroll") for (int n = 0; n < 2; ++n) _Pragma("unroll") for (int k = 0; k < 2; ++k) \
;         acc[ai][bj][m][n] = __builtin_amdgcn_mfma_f32_16x16x32_bf16(Bt[n][k], At[m][k], acc[ai][bj][m][n], 0, 0, 0); __builtin_amdgcn_s_setprio(0); } while (0)
; #define PG8_WAIT_V(n) asm volatile("s_waitcnt vmcnt(" #n ")" ::: "memory")
; #define PG8_WAIT_L(n) asm volatile("s_waitcnt lgkmcnt(" #n ")" ::: "memory")
; #define PG8_BAR __builtin_amdgcn_s_barrier()
; #define PG8_SCHED __builtin_amdgcn_sched_barrier(0)
; template <class Epi, class Sched, bool ALIGN_EPI = false, bool SP2 = false>
; __device__ __forceinline__ void gemm_phase(PG8_LAS unsigned char* lds, const Gemm g, const Sched& S, const Epi& E) {
;     ...
;             PG8_LDB(B0, 0, 0); PG8_LDB(B1, 0, 1); PG8_SCHED; PG8_LDA(At, 0, 0); PG8_STAGE(PG8_SA(1, 1), a1 + hstep, voffA);
;             PG8_WAIT_V(8); PG8_WAIT_L(0); PG8_BAR; PG8_MMA(0, 0, At, B0); PG8_MMA(0, 1, At, B1); PG8_BAR; PG8_SCHED;
;             PG8_LDA(At, 0, 1); PG8_STAGE(PG8_SB(0, 0), b2, voffB); PG8_STAGE(PG8_SB(0, 1), b2 + hstep, voffB); PG8_STAGE(PG8_SA(0, 0), a2, voffA);
;             PG8_WAIT_V(8); PG8_WAIT_L(0); PG8_BAR; PG8_MMA(1, 0, At, B0); PG8_MMA(1, 1, At, B1); PG8_BAR; PG8_SCHED;
.LBB0_396:
	s_add_u32 s30, s10, 0xfff80080
	s_addc_u32 s31, s11, -1
	s_add_i32 s78, 0, 0x10000
	s_cmp_eq_u32 s71, 28
	s_cselect_b32 s35, s23, s31
	s_cselect_b32 s34, s66, s30
	v_add_u32_e32 v2, s78, v141
	s_cselect_b32 s31, s21, s70
	s_cselect_b32 s30, s67, s69
	s_add_i32 s80, 0, 0x14000
	ds_read_b128 v[146:149], v2
	ds_read_b128 v[162:165], v2 offset:1024
	ds_read_b128 v[166:169], v2 offset:2048
	ds_read_b128 v[172:175], v2 offset:3072
	v_add_u32_e32 v2, s80, v141
	ds_read_b128 v[176:179], v2
	ds_read_b128 v[180:183], v2 offset:1024
	ds_read_b128 v[184:187], v2 offset:2048
	ds_read_b128 v[188:191], v2 offset:3072
	s_add_i32 m0, s45, 0xc000
	ds_read_b128 v[192:195], v170
	ds_read_b128 v[196:199], v170 offset:1024
	ds_read_b128 v[200:203], v170 offset:2048
	ds_read_b128 v[204:207], v170 offset:3072
	ds_read_b128 v[230:233], v170 offset:4096
	ds_read_b128 v[234:237], v170 offset:5120
	ds_read_b128 v[238:241], v170 offset:6144
	ds_read_b128 v[242:245], v170 offset:7168
	global_load_lds_dwordx4 v144, s[10:11]
	s_add_i32 m0, s45, 0xe000
	s_nop 0
	global_load_lds_dwordx4 v142, s[10:11]
	s_waitcnt vmcnt(8)
	s_waitcnt lgkmcnt(0)
	s_barrier
	s_setprio 1
	s_waitcnt lgkmcnt(0)
	v_mfma_f32_16x16x32_bf16 v[130:133], v[146:149], v[192:195], v[130:133]
	v_mfma_f32_16x16x32_bf16 v[126:129], v[166:169], v[192:195], v[126:129]
	v_mfma_f32_16x16x32_bf16 v[114:117], v[146:149], v[200:203], v[114:117]
	v_mfma_f32_16x16x32_bf16 v[110:113], v[166:169], v[200:203], v[110:113]
	v_mfma_f32_16x16x32_bf16 v[98:101], v[146:149], v[230:233], v[98:101]
	v_mfma_f32_16x16x32_bf16 v[94:97], v[166:169], v[230:233], v[94:97]
	v_mfma_f32_16x16x32_bf16 v[82:85], v[146:149], v[238:241], v[82:85]
	v_mfma_f32_16x16x32_bf16 v[78:81], v[166:169], v[238:241], v[78:81]
	v_mfma_f32_16x16x32_bf16 v[130:133], v[162:165], v[196:199], v[130:133]
	v_mfma_f32_16x16x32_bf16 v[126:129], v[172:175], v[196:199], v[126:129]
	v_mfma_f32_16x16x32_bf16 v[114:117], v[162:165], v[204:207], v[114:117]
	v_mfma_f32_16x16x32_bf16 v[110:113], v[172:175], v[204:207], v[110:113]
	v_mfma_f32_16x16x32_bf16 v[98:101], v[162:165], v[234:237], v[98:101]
	v_mfma_f32_16x16x32_bf16 v[94:97], v[172:175], v[234:237], v[94:97]
	v_mfma_f32_16x16x32_bf16 v[82:85], v[162:165], v[242:245], v[82:85]
	v_mfma_f32_16x16x32_bf16 v[78:81], v[172:175], v[242:245], v[78:81]
	v_mfma_f32_16x16x32_bf16 v[122:125], v[176:179], v[192:195], v[122:125]
	v_mfma_f32_16x16x32_bf16 v[118:121], v[184:187], v[192:195], v[118:121]
	v_mfma_f32_16x16x32_bf16 v[106:109], v[176:179], v[200:203], v[106:109]
	v_mfma_f32_16x16x32_bf16 v[102:105], v[184:187], v[200:203], v[102:105]
	v_mfma_f32_16x16x32_bf16 v[90:93], v[176:179], v[230:233], v[90:93]
	v_mfma_f32_16x16x32_bf16 v[86:89], v[184:187], v[230:233], v[86:89]
	v_mfma_f32_16x16x32_bf16 v[74:77], v[176:179], v[238:241], v[74:77]
	v_mfma_f32_16x16x32_bf16 v[70:73], v[184:187], v[238:241], v[70:73]
	v_mfma_f32_16x16x32_bf16 v[122:125], v[180:183], v[196:199], v[122:125]
	v_mfma_f32_16x16x32_bf16 v[118:121], v[188:191], v[196:199], v[118:121]
	v_mfma_f32_16x16x32_bf16 v[106:109], v[180:183], v[204:207], v[106:109]
	v_mfma_f32_16x16x32_bf16 v[102:105], v[188:191], v[204:207], v[102:105]
	v_mfma_f32_16x16x32_bf16 v[90:93], v[180:183], v[234:237], v[90:93]
	v_mfma_f32_16x16x32_bf16 v[86:89], v[188:191], v[234:237], v[86:89]
	v_mfma_f32_16x16x32_bf16 v[74:77], v[180:183], v[242:245], v[74:77]
	v_mfma_f32_16x16x32_bf16 v[70:73], v[188:191], v[242:245], v[70:73]
	s_setprio 0
	s_barrier
	s_add_i32 s78, s78, s40
	s_mov_b32 m0, s78
	ds_read_b128 v[192:195], v170 offset:16384
	ds_read_b128 v[196:199], v170 offset:17408
	ds_read_b128 v[200:203], v170 offset:18432
	ds_read_b128 v[204:207], v170 offset:19456
	ds_read_b128 v[230:233], v170 offset:20480
	ds_read_b128 v[234:237], v170 offset:21504
	ds_read_b128 v[238:241], v170 offset:22528
	ds_read_b128 v[242:245], v170 offset:23552
	global_load_lds_dwordx4 v136, s[30:31]
	s_add_i32 m0, s78, 0x2000
	s_add_u32 s78, s30, 0x80000
	s_addc_u32 s79, s31, 0
	s_add_i32 s80, s80, s40
	global_load_lds_dwordx4 v0, s[30:31]
	s_mov_b32 m0, s80
	v_lshl_add_u64 v[250:251], s[34:35], 0, v[134:135]
	global_load_lds_dwordx4 v136, s[78:79]
	s_add_i32 m0, s80, 0x2000
	s_nop 0
	global_load_lds_dwordx4 v0, s[78:79]
	v_lshl_add_u64 v[248:249], s[34:35], 0, v[138:139]
	s_mov_b32 m0, s45
	s_nop 0
	global_load_lds_dwordx4 v138, s[34:35]
	s_mov_b32 m0, s46
	s_nop 0
	global_load_lds_dwordx4 v134, s[34:35]
	s_waitcnt vmcnt(8)
	s_waitcnt lgkmcnt(0)
	s_barrier
	s_setprio 1
	s_waitcnt lgkmcnt(0)
	v_mfma_f32_16x16x32_bf16 v[66:69], v[146:149], v[192:195], v[66:69]
	v_mfma_f32_16x16x32_bf16 v[62:65], v[166:169], v[192:195], v[62:65]
	v_mfma_f32_16x16x32_bf16 v[50:53], v[146:149], v[200:203], v[50:53]
	v_mfma_f32_16x16x32_bf16 v[46:49], v[166:169], v[200:203], v[46:49]
	v_mfma_f32_16x16x32_bf16 v[34:37], v[146:149], v[230:233], v[34:37]
	v_mfma_f32_16x16x32_bf16 v[30:33], v[166:169], v[230:233], v[30:33]
	v_mfma_f32_16x16x32_bf16 v[18:21], v[146:149], v[238:241], v[18:21]
	v_mfma_f32_16x16x32_bf16 v[14:17], v[166:169], v[238:241], v[14:17]
	v_mfma_f32_16x16x32_bf16 v[66:69], v[162:165], v[196:199], v[66:69]
	v_mfma_f32_16x16x32_bf16 v[62:65], v[172:175], v[196:199], v[62:65]
	v_mfma_f32_16x16x32_bf16 v[50:53], v[162:165], v[204:207], v[50:53]
	v_mfma_f32_16x16x32_bf16 v[46:49], v[172:175], v[204:207], v[46:49]
	v_mfma_f32_16x16x32_bf16 v[34:37], v[162:165], v[234:237], v[34:37]
	v_mfma_f32_16x16x32_bf16 v[30:33], v[172:175], v[234:237], v[30:33]
	v_mfma_f32_16x16x32_bf16 v[18:21], v[162:165], v[242:245], v[18:21]
	v_mfma_f32_16x16x32_bf16 v[14:17], v[172:175], v[242:245], v[14:17]
	v_mfma_f32_16x16x32_bf16 v[58:61], v[176:179], v[192:195], v[58:61]
	v_mfma_f32_16x16x32_bf16 v[54:57], v[184:187], v[192:195], v[54:57]
	v_mfma_f32_16x16x32_bf16 v[42:45], v[176:179], v[200:203], v[42:45]
	v_mfma_f32_16x16x32_bf16 v[38:41], v[184:187], v[200:203], v[38:41]
	v_mfma_f32_16x16x32_bf16 v[26:29], v[176:179], v[230:233], v[26:29]
	v_mfma_f32_16x16x32_bf16 v[22:25], v[184:187], v[230:233], v[22:25]
	v_mfma_f32_16x16x32_bf16 v[10:13], v[176:179], v[238:241], v[10:13]
	v_mfma_f32_16x16x32_bf16 v[6:9], v[184:187], v[238:241], v[6:9]
	v_mfma_f32_16x16x32_bf16 v[58:61], v[180:183], v[196:199], v[58:61]
	v_mfma_f32_16x16x32_bf16 v[54:57], v[188:191], v[196:199], v[54:57]
	v_mfma_f32_16x16x32_bf16 v[42:45], v[180:183], v[204:207], v[42:45]
	v_mfma_f32_16x16x32_bf16 v[38:41], v[188:191], v[204:207], v[38:41]
	v_mfma_f32_16x16x32_bf16 v[26:29], v[180:183], v[234:237], v[26:29]
	v_mfma_f32_16x16x32_bf16 v[22:25], v[188:191], v[234:237], v[22:25]
	v_mfma_f32_16x16x32_bf16 v[10:13], v[180:183], v[242:245], v[10:13]
	v_mfma_f32_16x16x32_bf16 v[6:9], v[188:191], v[242:245], v[6:9]
	s_setprio 0
	s_barrier
; #define PG8_STAGE(bufoff, gbase, voff) do { _Pragma("unroll") for (int _i = 0; _i < 2; ++_i) \
;         __builtin_amdgcn_global_load_lds((const unsigned*)((const char*)(gbase) + (voff)[_i]), (PG8_LAS unsigned*)(lds + (bufoff) + ldsw + _i * 8192), 16, 0, 0); } while (0)
; #define PG8_LDA(dst, b, h) do { _Pragma("unroll") for (int m = 0; m < 4; ++m) _Pragma("unroll") for (int k = 0; k < 2; ++k) dst[m][k] = *(const PG8_LAS bf16x8*)(lds + PG8_SA(b, h) + aoff + m * 2048 + k * 1024); } while (0)
; #define PG8_LDB(dst, b, h) do { _Pragma("unroll") for (int n = 0; n < 2; ++n) _Pragma("unroll") for (int k = 0; k < 2; ++k) dst[n][k] = *(const PG8_LAS bf16x8*)(lds + PG8_SB(b, h) + boff + n * 2048 + k * 1024); } while (0)
; #define PG8_MMA(ai, bj, At, Bt) do { __builtin_amdgcn_s_setprio(1); _Pragma("unroll") for (int m = 0; m < 4; ++m) _Pragma("unroll") for (int n = 0; n < 2; ++n) _Pragma("unroll") for (int k = 0; k < 2; ++k) \
;         acc[ai][bj][m][n] = __builtin_amdgcn_mfma_f32_16x16x32_bf16(Bt[n][k], At[m][k], acc[ai][bj][m][n], 0, 0, 0); __builtin_amdgcn_s_setprio(0); } while (0)
; #define PG8_WAIT_V(n) asm volatile("s_waitcnt vmcnt(" #n ")" ::: "memory")
; #define PG8_WAIT_L(n) asm volatile("s_waitcnt lgkmcnt(" #n ")" ::: "memory")
; #define PG8_BAR __builtin_amdgcn_s_barrier()
; #define PG8_SCHED __builtin_amdgcn_sched_barrier(0)
; template <class Epi, class Sched, bool ALIGN_EPI = false, bool SP2 = false>
; __device__ __forceinline__ void gemm_phase(PG8_LAS unsigned char* lds, const Gemm g, const Sched& S, const Epi& E) {
;     ...
;             PG8_LDB(B0, 1, 0); PG8_LDB(B1, 1, 1); PG8_SCHED; PG8_LDA(At, 1, 0); PG8_STAGE(PG8_SA(0, 1), a2 + hstep, voffA);
;             PG8_WAIT_V(8); PG8_WAIT_L(0); PG8_BAR; PG8_MMA(0, 0, At, B0); PG8_MMA(0, 1, At, B1); PG8_BAR; PG8_SCHED;
;             PG8_LDA(At, 1, 1); PG8_STAGE(PG8_SB(1, 0), b3, voffB); PG8_STAGE(PG8_SB(1, 1), b3 + hstep, voffB); PG8_STAGE(PG8_SA(1, 0), a3, voffA);
;             PG8_WAIT_V(8); PG8_WAIT_L(0); PG8_BAR; PG8_MMA(1, 0, At, B0); PG8_MMA(1, 1, At, B1); PG8_BAR; PG8_SCHED;
	s_add_i32 s78, 0, 0x18000
	v_add_u32_e32 v2, s78, v141
	s_add_i32 s79, 0, 0x1c000
	ds_read_b128 v[146:149], v2
	ds_read_b128 v[162:165], v2 offset:1024
	ds_read_b128 v[166:169], v2 offset:2048
	ds_read_b128 v[172:175], v2 offset:3072
	v_add_u32_e32 v2, s79, v141
	ds_read_b128 v[176:179], v2
	ds_read_b128 v[180:183], v2 offset:1024
	ds_read_b128 v[184:187], v2 offset:2048
	ds_read_b128 v[188:191], v2 offset:3072
	s_add_u32 s34, s34, 0x80000
	s_addc_u32 s35, s35, 0
	s_mov_b32 m0, s47
	ds_read_b128 v[192:195], v170 offset:32768
	ds_read_b128 v[196:199], v170 offset:33792
	ds_read_b128 v[200:203], v170 offset:34816
	ds_read_b128 v[204:207], v170 offset:35840
	ds_read_b128 v[230:233], v170 offset:36864
	ds_read_b128 v[234:237], v170 offset:37888
	ds_read_b128 v[238:241], v170 offset:38912
	ds_read_b128 v[242:245], v170 offset:39936
	global_load_lds_dwordx4 v138, s[34:35]
	s_mov_b32 m0, s48
	s_nop 0
	global_load_lds_dwordx4 v134, s[34:35]
	s_waitcnt vmcnt(8)
	s_waitcnt lgkmcnt(0)
	s_barrier
	s_setprio 1
	s_waitcnt lgkmcnt(0)
	v_mfma_f32_16x16x32_bf16 v[130:133], v[146:149], v[192:195], v[130:133]
	v_mfma_f32_16x16x32_bf16 v[126:129], v[166:169], v[192:195], v[126:129]
	v_mfma_f32_16x16x32_bf16 v[114:117], v[146:149], v[200:203], v[114:117]
	v_mfma_f32_16x16x32_bf16 v[110:113], v[166:169], v[200:203], v[110:113]
	v_mfma_f32_16x16x32_bf16 v[98:101], v[146:149], v[230:233], v[98:101]
	v_mfma_f32_16x16x32_bf16 v[94:97], v[166:169], v[230:233], v[94:97]
	v_mfma_f32_16x16x32_bf16 v[82:85], v[146:149], v[238:241], v[82:85]
	v_mfma_f32_16x16x32_bf16 v[78:81], v[166:169], v[238:241], v[78:81]
	v_mfma_f32_16x16x32_bf16 v[130:133], v[162:165], v[196:199], v[130:133]
	v_mfma_f32_16x16x32_bf16 v[126:129], v[172:175], v[196:199], v[126:129]
	v_mfma_f32_16x16x32_bf16 v[114:117], v[162:165], v[204:207], v[114:117]
	v_mfma_f32_16x16x32_bf16 v[110:113], v[172:175], v[204:207], v[110:113]
	v_mfma_f32_16x16x32_bf16 v[98:101], v[162:165], v[234:237], v[98:101]
	v_mfma_f32_16x16x32_bf16 v[94:97], v[172:175], v[234:237], v[94:97]
	v_mfma_f32_16x16x32_bf16 v[82:85], v[162:165], v[242:245], v[82:85]
	v_mfma_f32_16x16x32_bf16 v[78:81], v[172:175], v[242:245], v[78:81]
	v_mfma_f32_16x16x32_bf16 v[122:125], v[176:179], v[192:195], v[122:125]
	v_mfma_f32_16x16x32_bf16 v[118:121], v[184:187], v[192:195], v[118:121]
	v_mfma_f32_16x16x32_bf16 v[106:109], v[176:179], v[200:203], v[106:109]
	v_mfma_f32_16x16x32_bf16 v[102:105], v[184:187], v[200:203], v[102:105]
	v_mfma_f32_16x16x32_bf16 v[90:93], v[176:179], v[230:233], v[90:93]
	v_mfma_f32_16x16x32_bf16 v[86:89], v[184:187], v[230:233], v[86:89]
	v_mfma_f32_16x16x32_bf16 v[74:77], v[176:179], v[238:241], v[74:77]
	v_mfma_f32_16x16x32_bf16 v[70:73], v[184:187], v[238:241], v[70:73]
	v_mfma_f32_16x16x32_bf16 v[122:125], v[180:183], v[196:199], v[122:125]
	v_mfma_f32_16x16x32_bf16 v[118:121], v[188:191], v[196:199], v[118:121]
	v_mfma_f32_16x16x32_bf16 v[106:109], v[180:183], v[204:207], v[106:109]
	v_mfma_f32_16x16x32_bf16 v[102:105], v[188:191], v[204:207], v[102:105]
	v_mfma_f32_16x16x32_bf16 v[90:93], v[180:183], v[234:237], v[90:93]
	v_mfma_f32_16x16x32_bf16 v[86:89], v[188:191], v[234:237], v[86:89]
	v_mfma_f32_16x16x32_bf16 v[74:77], v[180:183], v[242:245], v[74:77]
	v_mfma_f32_16x16x32_bf16 v[70:73], v[188:191], v[242:245], v[70:73]
	s_setprio 0
	s_barrier
	s_add_u32 vcc_lo, s30, s2
	s_addc_u32 vcc_hi, s31, s3
	s_add_i32 s34, s78, s40
	s_mov_b32 m0, s34
	ds_read_b128 v[192:195], v170 offset:49152
	ds_read_b128 v[196:199], v170 offset:50176
	ds_read_b128 v[200:203], v170 offset:51200
	ds_read_b128 v[204:207], v170 offset:52224
	ds_read_b128 v[230:233], v170 offset:53248
	ds_read_b128 v[234:237], v170 offset:54272
	ds_read_b128 v[238:241], v170 offset:55296
	ds_read_b128 v[242:245], v170 offset:56320
	global_load_lds_dwordx4 v136, vcc
	s_add_i32 m0, s34, 0x2000
	s_add_u32 s30, s30, 0x80080
	s_addc_u32 s31, s31, 0
	s_add_i32 s34, s79, s40
	global_load_lds_dwordx4 v0, vcc
	s_mov_b32 m0, s34
	s_nop 0
	global_load_lds_dwordx4 v136, s[30:31]
	s_add_i32 m0, s34, 0x2000
	s_nop 0
	global_load_lds_dwordx4 v0, s[30:31]
	v_lshl_add_u64 v[158:159], v[248:249], 0, s[2:3]
	s_mov_b32 m0, s49
	s_nop 0
	global_load_lds_dwordx4 v[158:159], off
	v_lshl_add_u64 v[158:159], v[250:251], 0, s[2:3]
	s_mov_b32 m0, s50
	s_nop 0
	global_load_lds_dwordx4 v[158:159], off
	s_waitcnt vmcnt(8)
	s_waitcnt lgkmcnt(0)
	s_barrier
	s_setprio 1
	s_waitcnt lgkmcnt(0)
	v_mfma_f32_16x16x32_bf16 v[66:69], v[146:149], v[192:195], v[66:69]
	v_mfma_f32_16x16x32_bf16 v[62:65], v[166:169], v[192:195], v[62:65]
	v_mfma_f32_16x16x32_bf16 v[50:53], v[146:149], v[200:203], v[50:53]
	v_mfma_f32_16x16x32_bf16 v[46:49], v[166:169], v[200:203], v[46:49]
	v_mfma_f32_16x16x32_bf16 v[34:37], v[146:149], v[230:233], v[34:37]
	v_mfma_f32_16x16x32_bf16 v[30:33], v[166:169], v[230:233], v[30:33]
	v_mfma_f32_16x16x32_bf16 v[18:21], v[146:149], v[238:241], v[18:21]
	v_mfma_f32_16x16x32_bf16 v[14:17], v[166:169], v[238:241], v[14:17]
	v_mfma_f32_16x16x32_bf16 v[66:69], v[162:165], v[196:199], v[66:69]
	v_mfma_f32_16x16x32_bf16 v[62:65], v[172:175], v[196:199], v[62:65]
	v_mfma_f32_16x16x32_bf16 v[50:53], v[162:165], v[204:207], v[50:53]
	v_mfma_f32_16x16x32_bf16 v[46:49], v[172:175], v[204:207], v[46:49]
	v_mfma_f32_16x16x32_bf16 v[34:37], v[162:165], v[234:237], v[34:37]
	v_mfma_f32_16x16x32_bf16 v[30:33], v[172:175], v[234:237], v[30:33]
	v_mfma_f32_16x16x32_bf16 v[18:21], v[162:165], v[242:245], v[18:21]
	v_mfma_f32_16x16x32_bf16 v[14:17], v[172:175], v[242:245], v[14:17]
	v_mfma_f32_16x16x32_bf16 v[58:61], v[176:179], v[192:195], v[58:61]
	v_mfma_f32_16x16x32_bf16 v[54:57], v[184:187], v[192:195], v[54:57]
	v_mfma_f32_16x16x32_bf16 v[42:45], v[176:179], v[200:203], v[42:45]
	v_mfma_f32_16x16x32_bf16 v[38:41], v[184:187], v[200:203], v[38:41]
	v_mfma_f32_16x16x32_bf16 v[26:29], v[176:179], v[230:233], v[26:29]
	v_mfma_f32_16x16x32_bf16 v[22:25], v[184:187], v[230:233], v[22:25]
	v_mfma_f32_16x16x32_bf16 v[10:13], v[176:179], v[238:241], v[10:13]
	v_mfma_f32_16x16x32_bf16 v[6:9], v[184:187], v[238:241], v[6:9]
	v_mfma_f32_16x16x32_bf16 v[58:61], v[180:183], v[196:199], v[58:61]
	v_mfma_f32_16x16x32_bf16 v[54:57], v[188:191], v[196:199], v[54:57]
	v_mfma_f32_16x16x32_bf16 v[42:45], v[180:183], v[204:207], v[42:45]
	v_mfma_f32_16x16x32_bf16 v[38:41], v[188:191], v[204:207], v[38:41]
	v_mfma_f32_16x16x32_bf16 v[26:29], v[180:183], v[234:237], v[26:29]
	v_mfma_f32_16x16x32_bf16 v[22:25], v[188:191], v[234:237], v[22:25]
	v_mfma_f32_16x16x32_bf16 v[10:13], v[180:183], v[242:245], v[10:13]
	v_mfma_f32_16x16x32_bf16 v[6:9], v[188:191], v[242:245], v[6:9]
	s_setprio 0
	s_barrier
	s_add_i32 s71, s71, 2
	s_add_u32 s69, s69, 0x100
	s_addc_u32 s70, s70, 0
	s_add_u32 s10, s10, 0x100
	s_addc_u32 s11, s11, 0
	s_cmp_gt_u32 s71, 29
	s_cbranch_scc0 .LBB0_396
	s_and_b64 vcc, exec, s[18:19]
	s_cbranch_vccz .LBB0_399
	s_barrier

; #define PG8_STAGE(bufoff, gbase, voff) do { _Pragma("unroll") for (int _i = 0; _i < 2; ++_i) \
;         __builtin_amdgcn_global_load_lds((const unsigned*)((const char*)(gbase) + (voff)[_i]), (PG8_LAS unsigned*)(lds + (bufoff) + ldsw + _i * 8192), 16, 0, 0); } while (0)
; #define PG8_LDA(dst, b, h) do { _Pragma("unroll") for (int m = 0; m < 4; ++m) _Pragma("unroll") for (int k = 0; k < 2; ++k) dst[m][k] = *(const PG8_LAS bf16x8*)(lds + PG8_SA(b, h) + aoff + m * 2048 + k * 1024); } while (0)
; #define PG8_LDB(dst, b, h) do { _Pragma("unroll") for (int n = 0; n < 2; ++n) _Pragma("unroll") for (int k = 0; k < 2; ++k) dst[n][k] = *(const PG8_LAS bf16x8*)(lds + PG8_SB(b, h) + boff + n * 2048 + k * 1024); } while (0)
; #define PG8_MMA(ai, bj, At, Bt) do { __builtin_amdgcn_s_setprio(1); _Pragma("unroll") for (int m = 0; m < 4; ++m) _Pragma("unroll") for (int n = 0; n < 2; ++n) _Pragma("unroll") for (int k = 0; k < 2; ++k) \
;         acc[ai][bj][m][n] = __builtin_amdgcn_mfma_f32_16x16x32_bf16(Bt[n][k], At[m][k], acc[ai][bj][m][n], 0, 0, 0); __builtin_amdgcn_s_setprio(0); } while (0)
; #define PG8_WAIT_V(n) asm volatile("s_waitcnt vmcnt(" #n ")" ::: "memory")
; #define PG8_WAIT_L(n) asm volatile("s_waitcnt lgkmcnt(" #n ")" ::: "memory")
; template <class Epi, class Sched, bool ALIGN_EPI = false, bool SP2 = false>
; __device__ __forceinline__ void gemm_phase(PG8_LAS unsigned char* lds, const Gemm g, const Sched& S, const Epi& E) {
;     ...
;             const bool last = (t == nt - 2);
;             const char* a1 = cA + (size_t)(t + 1) * kstep;
;             const char* a2 = last ? nA : cA + (size_t)(t + 2) * kstep; const char* b2 = last ? nB : cB + (size_t)(t + 2) * kstep;
;             const char* a3 = a2 + kstep; const char* b3 = b2 + kstep;
;             if (last && has_next) S.a_ready(nxt);
;             if constexpr (SP2) {
;             PG8_LDB(B0, 0, 0); PG8_LDB(B1, 0, 1); PG8_SCHED; PG8_LDA(At, 0, 0); PG8_STAGE(PG8_SA(1, 1), a1 + hstep, voffA);
;             PG8_WAIT_V(8); PG8_WAIT_L(0); PG8_BAR; PG8_MMA(0, 0, At, B0); PG8_MMA(0, 1, At, B1); PG8_BAR; PG8_SCHED;
;             PG8_LDA(At, 0, 1); PG8_STAGE(PG8_SB(0, 0), b2, voffB); PG8_STAGE(PG8_SB(0, 1), b2 + hstep, voffB); PG8_STAGE(PG8_SA(0, 0), a2, voffA);
;             PG8_WAIT_V(8); PG8_WAIT_L(0); PG8_BAR; PG8_MMA(1, 0, At, B0); PG8_MMA(1, 1, At, B1); PG8_BAR; PG8_SCHED;
.LBB0_818:
	s_add_u32 s30, s26, 0xfffc0080
	s_addc_u32 s31, s27, -1
	s_add_i32 s78, 0, 0x10000
	s_cmp_eq_u32 s71, 12
	s_cselect_b32 s35, s21, s31
	s_cselect_b32 s34, s66, s30
	v_add_u32_e32 v149, s78, v146
	s_cselect_b32 s31, s19, s70
	s_cselect_b32 s30, s67, s69
	s_add_i32 s80, 0, 0x14000
	ds_read_b128 v[142:145], v149
	ds_read_b128 v[162:165], v149 offset:1024
	ds_read_b128 v[166:169], v149 offset:2048
	ds_read_b128 v[170:173], v149 offset:3072
	v_add_u32_e32 v149, s80, v146
	ds_read_b128 v[174:177], v149
	ds_read_b128 v[178:181], v149 offset:1024
	ds_read_b128 v[182:185], v149 offset:2048
	ds_read_b128 v[186:189], v149 offset:3072
	s_add_i32 m0, s44, 0xc000
	ds_read_b128 v[190:193], v148
	ds_read_b128 v[194:197], v148 offset:1024
	ds_read_b128 v[198:201], v148 offset:2048
	ds_read_b128 v[202:205], v148 offset:3072
	ds_read_b128 v[230:233], v148 offset:4096
	ds_read_b128 v[234:237], v148 offset:5120
	ds_read_b128 v[238:241], v148 offset:6144
	ds_read_b128 v[242:245], v148 offset:7168
	global_load_lds_dwordx4 v140, s[26:27]
	s_add_i32 m0, s44, 0xe000
	s_nop 0
	global_load_lds_dwordx4 v138, s[26:27]
	s_waitcnt vmcnt(8)
	s_waitcnt lgkmcnt(0)
	s_barrier
	s_setprio 1
	s_waitcnt lgkmcnt(0)
	v_mfma_f32_16x16x32_bf16 v[130:133], v[142:145], v[190:193], v[130:133]
	v_mfma_f32_16x16x32_bf16 v[126:129], v[166:169], v[190:193], v[126:129]
	v_mfma_f32_16x16x32_bf16 v[118:121], v[142:145], v[198:201], v[118:121]
	v_mfma_f32_16x16x32_bf16 v[110:113], v[166:169], v[198:201], v[110:113]
	v_mfma_f32_16x16x32_bf16 v[98:101], v[142:145], v[230:233], v[98:101]
	v_mfma_f32_16x16x32_bf16 v[94:97], v[166:169], v[230:233], v[94:97]
	v_mfma_f32_16x16x32_bf16 v[82:85], v[142:145], v[238:241], v[82:85]
	v_mfma_f32_16x16x32_bf16 v[78:81], v[166:169], v[238:241], v[78:81]
	v_mfma_f32_16x16x32_bf16 v[130:133], v[162:165], v[194:197], v[130:133]
	v_mfma_f32_16x16x32_bf16 v[126:129], v[170:173], v[194:197], v[126:129]
	v_mfma_f32_16x16x32_bf16 v[118:121], v[162:165], v[202:205], v[118:121]
	v_mfma_f32_16x16x32_bf16 v[110:113], v[170:173], v[202:205], v[110:113]
	v_mfma_f32_16x16x32_bf16 v[98:101], v[162:165], v[234:237], v[98:101]
	v_mfma_f32_16x16x32_bf16 v[94:97], v[170:173], v[234:237], v[94:97]
	v_mfma_f32_16x16x32_bf16 v[82:85], v[162:165], v[242:245], v[82:85]
	v_mfma_f32_16x16x32_bf16 v[78:81], v[170:173], v[242:245], v[78:81]
	v_mfma_f32_16x16x32_bf16 v[122:125], v[174:177], v[190:193], v[122:125]
	v_mfma_f32_16x16x32_bf16 v[114:117], v[182:185], v[190:193], v[114:117]
	v_mfma_f32_16x16x32_bf16 v[106:109], v[174:177], v[198:201], v[106:109]
	v_mfma_f32_16x16x32_bf16 v[102:105], v[182:185], v[198:201], v[102:105]
	v_mfma_f32_16x16x32_bf16 v[90:93], v[174:177], v[230:233], v[90:93]
	v_mfma_f32_16x16x32_bf16 v[86:89], v[182:185], v[230:233], v[86:89]
	v_mfma_f32_16x16x32_bf16 v[74:77], v[174:177], v[238:241], v[74:77]
	v_mfma_f32_16x16x32_bf16 v[70:73], v[182:185], v[238:241], v[70:73]
	v_mfma_f32_16x16x32_bf16 v[122:125], v[178:181], v[194:197], v[122:125]
	v_mfma_f32_16x16x32_bf16 v[114:117], v[186:189], v[194:197], v[114:117]
	v_mfma_f32_16x16x32_bf16 v[106:109], v[178:181], v[202:205], v[106:109]
	v_mfma_f32_16x16x32_bf16 v[102:105], v[186:189], v[202:205], v[102:105]
	v_mfma_f32_16x16x32_bf16 v[90:93], v[178:181], v[234:237], v[90:93]
	v_mfma_f32_16x16x32_bf16 v[86:89], v[186:189], v[234:237], v[86:89]
	v_mfma_f32_16x16x32_bf16 v[74:77], v[178:181], v[242:245], v[74:77]
	v_mfma_f32_16x16x32_bf16 v[70:73], v[186:189], v[242:245], v[70:73]
	s_setprio 0
	s_barrier
	s_add_i32 s78, s78, s41
	s_mov_b32 m0, s78
	ds_read_b128 v[190:193], v148 offset:16384
	ds_read_b128 v[194:197], v148 offset:17408
	ds_read_b128 v[198:201], v148 offset:18432
	ds_read_b128 v[202:205], v148 offset:19456
	ds_read_b128 v[230:233], v148 offset:20480
	ds_read_b128 v[234:237], v148 offset:21504
	ds_read_b128 v[238:241], v148 offset:22528
	ds_read_b128 v[242:245], v148 offset:23552
	global_load_lds_dwordx4 v2, s[30:31]
	s_add_i32 m0, s78, 0x2000
	s_add_u32 s78, s30, 0x40000
	s_addc_u32 s79, s31, 0
	s_add_i32 s80, s80, s41
	global_load_lds_dwordx4 v0, s[30:31]
	s_mov_b32 m0, s80
	v_lshl_add_u64 v[246:247], s[34:35], 0, v[134:135]
	global_load_lds_dwordx4 v2, s[78:79]
	s_add_i32 m0, s80, 0x2000
	s_nop 0
	global_load_lds_dwordx4 v0, s[78:79]
	v_lshl_add_u64 v[206:207], s[34:35], 0, v[136:137]
	s_mov_b32 m0, s44
	s_nop 0
	global_load_lds_dwordx4 v136, s[34:35]
	s_mov_b32 m0, s45
	s_nop 0
	global_load_lds_dwordx4 v134, s[34:35]
	s_waitcnt vmcnt(8)
	s_waitcnt lgkmcnt(0)
	s_barrier
	s_setprio 1
	s_waitcnt lgkmcnt(0)
	v_mfma_f32_16x16x32_bf16 v[66:69], v[142:145], v[190:193], v[66:69]
	v_mfma_f32_16x16x32_bf16 v[62:65], v[166:169], v[190:193], v[62:65]
	v_mfma_f32_16x16x32_bf16 v[50:53], v[142:145], v[198:201], v[50:53]
	v_mfma_f32_16x16x32_bf16 v[46:49], v[166:169], v[198:201], v[46:49]
	v_mfma_f32_16x16x32_bf16 v[34:37], v[142:145], v[230:233], v[34:37]
	v_mfma_f32_16x16x32_bf16 v[30:33], v[166:169], v[230:233], v[30:33]
	v_mfma_f32_16x16x32_bf16 v[18:21], v[142:145], v[238:241], v[18:21]
	v_mfma_f32_16x16x32_bf16 v[14:17], v[166:169], v[238:241], v[14:17]
	v_mfma_f32_16x16x32_bf16 v[66:69], v[162:165], v[194:197], v[66:69]
	v_mfma_f32_16x16x32_bf16 v[62:65], v[170:173], v[194:197], v[62:65]
	v_mfma_f32_16x16x32_bf16 v[50:53], v[162:165], v[202:205], v[50:53]
	v_mfma_f32_16x16x32_bf16 v[46:49], v[170:173], v[202:205], v[46:49]
	v_mfma_f32_16x16x32_bf16 v[34:37], v[162:165], v[234:237], v[34:37]
	v_mfma_f32_16x16x32_bf16 v[30:33], v[170:173], v[234:237], v[30:33]
	v_mfma_f32_16x16x32_bf16 v[18:21], v[162:165], v[242:245], v[18:21]
	v_mfma_f32_16x16x32_bf16 v[14:17], v[170:173], v[242:245], v[14:17]
	v_mfma_f32_16x16x32_bf16 v[58:61], v[174:177], v[190:193], v[58:61]
	v_mfma_f32_16x16x32_bf16 v[54:57], v[182:185], v[190:193], v[54:57]
	v_mfma_f32_16x16x32_bf16 v[42:45], v[174:177], v[198:201], v[42:45]
	v_mfma_f32_16x16x32_bf16 v[38:41], v[182:185], v[198:201], v[38:41]
	v_mfma_f32_16x16x32_bf16 v[26:29], v[174:177], v[230:233], v[26:29]
	v_mfma_f32_16x16x32_bf16 v[22:25], v[182:185], v[230:233], v[22:25]
	v_mfma_f32_16x16x32_bf16 v[10:13], v[174:177], v[238:241], v[10:13]
	v_mfma_f32_16x16x32_bf16 v[6:9], v[182:185], v[238:241], v[6:9]
	v_mfma_f32_16x16x32_bf16 v[58:61], v[178:181], v[194:197], v[58:61]
	v_mfma_f32_16x16x32_bf16 v[54:57], v[186:189], v[194:197], v[54:57]
	v_mfma_f32_16x16x32_bf16 v[42:45], v[178:181], v[202:205], v[42:45]
	v_mfma_f32_16x16x32_bf16 v[38:41], v[186:189], v[202:205], v[38:41]
	v_mfma_f32_16x16x32_bf16 v[26:29], v[178:181], v[234:237], v[26:29]
	v_mfma_f32_16x16x32_bf16 v[22:25], v[186:189], v[234:237], v[22:25]
	v_mfma_f32_16x16x32_bf16 v[10:13], v[178:181], v[242:245], v[10:13]
	v_mfma_f32_16x16x32_bf16 v[6:9], v[186:189], v[242:245], v[6:9]
	s_setprio 0
	s_barrier
; #define PG8_STAGE(bufoff, gbase, voff) do { _Pragma("unroll") for (int _i = 0; _i < 2; ++_i) \
;         __builtin_amdgcn_global_load_lds((const unsigned*)((const char*)(gbase) + (voff)[_i]), (PG8_LAS unsigned*)(lds + (bufoff) + ldsw + _i * 8192), 16, 0, 0); } while (0)
; #define PG8_LDA(dst, b, h) do { _Pragma("unroll") for (int m = 0; m < 4; ++m) _Pragma("unroll") for (int k = 0; k < 2; ++k) dst[m][k] = *(const PG8_LAS bf16x8*)(lds + PG8_SA(b, h) + aoff + m * 2048 + k * 1024); } while (0)
; #define PG8_LDB(dst, b, h) do { _Pragma("unroll") for (int n = 0; n < 2; ++n) _Pragma("unroll") for (int k = 0; k < 2; ++k) dst[n][k] = *(const PG8_LAS bf16x8*)(lds + PG8_SB(b, h) + boff + n * 2048 + k * 1024); } while (0)
; #define PG8_MMA(ai, bj, At, Bt) do { __builtin_amdgcn_s_setprio(1); _Pragma("unroll") for (int m = 0; m < 4; ++m) _Pragma("unroll") for (int n = 0; n < 2; ++n) _Pragma("unroll") for (int k = 0; k < 2; ++k) \
;         acc[ai][bj][m][n] = __builtin_amdgcn_mfma_f32_16x16x32_bf16(Bt[n][k], At[m][k], acc[ai][bj][m][n], 0, 0, 0); __builtin_amdgcn_s_setprio(0); } while (0)
; #define PG8_WAIT_V(n) asm volatile("s_waitcnt vmcnt(" #n ")" ::: "memory")
; #define PG8_WAIT_L(n) asm volatile("s_waitcnt lgkmcnt(" #n ")" ::: "memory")
; #define PG8_BAR __builtin_amdgcn_s_barrier()
; #define PG8_SCHED __builtin_amdgcn_sched_barrier(0)
; template <class Epi, class Sched, bool ALIGN_EPI = false, bool SP2 = false>
; __device__ __forceinline__ void gemm_phase(PG8_LAS unsigned char* lds, const Gemm g, const Sched& S, const Epi& E) {
;     ...
;             PG8_LDB(B0, 1, 0); PG8_LDB(B1, 1, 1); PG8_SCHED; PG8_LDA(At, 1, 0); PG8_STAGE(PG8_SA(0, 1), a2 + hstep, voffA);
;             PG8_WAIT_V(8); PG8_WAIT_L(0); PG8_BAR; PG8_MMA(0, 0, At, B0); PG8_MMA(0, 1, At, B1); PG8_BAR; PG8_SCHED;
;             PG8_LDA(At, 1, 1); PG8_STAGE(PG8_SB(1, 0), b3, voffB); PG8_STAGE(PG8_SB(1, 1), b3 + hstep, voffB); PG8_STAGE(PG8_SA(1, 0), a3, voffA);
;             PG8_WAIT_V(8); PG8_WAIT_L(0); PG8_BAR; PG8_MMA(1, 0, At, B0); PG8_MMA(1, 1, At, B1); PG8_BAR; PG8_SCHED;
	s_add_i32 s78, 0, 0x18000
	v_add_u32_e32 v149, s78, v146
	s_add_i32 s79, 0, 0x1c000
	ds_read_b128 v[142:145], v149
	ds_read_b128 v[162:165], v149 offset:1024
	ds_read_b128 v[166:169], v149 offset:2048
	ds_read_b128 v[170:173], v149 offset:3072
	v_add_u32_e32 v149, s79, v146
	ds_read_b128 v[174:177], v149
	ds_read_b128 v[178:181], v149 offset:1024
	ds_read_b128 v[182:185], v149 offset:2048
	ds_read_b128 v[186:189], v149 offset:3072
	s_add_u32 s34, s34, 0x40000
	s_addc_u32 s35, s35, 0
	s_mov_b32 m0, s46
	ds_read_b128 v[190:193], v148 offset:32768
	ds_read_b128 v[194:197], v148 offset:33792
	ds_read_b128 v[198:201], v148 offset:34816
	ds_read_b128 v[202:205], v148 offset:35840
	ds_read_b128 v[230:233], v148 offset:36864
	ds_read_b128 v[234:237], v148 offset:37888
	ds_read_b128 v[238:241], v148 offset:38912
	ds_read_b128 v[242:245], v148 offset:39936
	global_load_lds_dwordx4 v136, s[34:35]
	s_mov_b32 m0, s47
	s_nop 0
	global_load_lds_dwordx4 v134, s[34:35]
	s_waitcnt vmcnt(8)
	s_waitcnt lgkmcnt(0)
	s_barrier
	s_setprio 1
	s_waitcnt lgkmcnt(0)
	v_mfma_f32_16x16x32_bf16 v[130:133], v[142:145], v[190:193], v[130:133]
	v_mfma_f32_16x16x32_bf16 v[126:129], v[166:169], v[190:193], v[126:129]
	v_mfma_f32_16x16x32_bf16 v[118:121], v[142:145], v[198:201], v[118:121]
	v_mfma_f32_16x16x32_bf16 v[110:113], v[166:169], v[198:201], v[110:113]
	v_mfma_f32_16x16x32_bf16 v[98:101], v[142:145], v[230:233], v[98:101]
	v_mfma_f32_16x16x32_bf16 v[94:97], v[166:169], v[230:233], v[94:97]
	v_mfma_f32_16x16x32_bf16 v[82:85], v[142:145], v[238:241], v[82:85]
	v_mfma_f32_16x16x32_bf16 v[78:81], v[166:169], v[238:241], v[78:81]
	v_mfma_f32_16x16x32_bf16 v[130:133], v[162:165], v[194:197], v[130:133]
	v_mfma_f32_16x16x32_bf16 v[126:129], v[170:173], v[194:197], v[126:129]
	v_mfma_f32_16x16x32_bf16 v[118:121], v[162:165], v[202:205], v[118:121]
	v_mfma_f32_16x16x32_bf16 v[110:113], v[170:173], v[202:205], v[110:113]
	v_mfma_f32_16x16x32_bf16 v[98:101], v[162:165], v[234:237], v[98:101]
	v_mfma_f32_16x16x32_bf16 v[94:97], v[170:173], v[234:237], v[94:97]
	v_mfma_f32_16x16x32_bf16 v[82:85], v[162:165], v[242:245], v[82:85]
	v_mfma_f32_16x16x32_bf16 v[78:81], v[170:173], v[242:245], v[78:81]
	v_mfma_f32_16x16x32_bf16 v[122:125], v[174:177], v[190:193], v[122:125]
	v_mfma_f32_16x16x32_bf16 v[114:117], v[182:185], v[190:193], v[114:117]
	v_mfma_f32_16x16x32_bf16 v[106:109], v[174:177], v[198:201], v[106:109]
	v_mfma_f32_16x16x32_bf16 v[102:105], v[182:185], v[198:201], v[102:105]
	v_mfma_f32_16x16x32_bf16 v[90:93], v[174:177], v[230:233], v[90:93]
	v_mfma_f32_16x16x32_bf16 v[86:89], v[182:185], v[230:233], v[86:89]
	v_mfma_f32_16x16x32_bf16 v[74:77], v[174:177], v[238:241], v[74:77]
	v_mfma_f32_16x16x32_bf16 v[70:73], v[182:185], v[238:241], v[70:73]
	v_mfma_f32_16x16x32_bf16 v[122:125], v[178:181], v[194:197], v[122:125]
	v_mfma_f32_16x16x32_bf16 v[114:117], v[186:189], v[194:197], v[114:117]
	v_mfma_f32_16x16x32_bf16 v[106:109], v[178:181], v[202:205], v[106:109]
	v_mfma_f32_16x16x32_bf16 v[102:105], v[186:189], v[202:205], v[102:105]
	v_mfma_f32_16x16x32_bf16 v[90:93], v[178:181], v[234:237], v[90:93]
	v_mfma_f32_16x16x32_bf16 v[86:89], v[186:189], v[234:237], v[86:89]
	v_mfma_f32_16x16x32_bf16 v[74:77], v[178:181], v[242:245], v[74:77]
	v_mfma_f32_16x16x32_bf16 v[70:73], v[186:189], v[242:245], v[70:73]
	s_setprio 0
	s_barrier
	s_add_u32 vcc_lo, s30, s2
	s_addc_u32 vcc_hi, s31, s3
	s_add_i32 s34, s78, s41
	s_mov_b32 m0, s34
	ds_read_b128 v[190:193], v148 offset:49152
	ds_read_b128 v[194:197], v148 offset:50176
	ds_read_b128 v[198:201], v148 offset:51200
	ds_read_b128 v[202:205], v148 offset:52224
	ds_read_b128 v[230:233], v148 offset:53248
	ds_read_b128 v[234:237], v148 offset:54272
	ds_read_b128 v[238:241], v148 offset:55296
	ds_read_b128 v[242:245], v148 offset:56320
	global_load_lds_dwordx4 v2, vcc
	s_add_i32 m0, s34, 0x2000
	s_add_u32 s30, s30, 0x40080
	s_addc_u32 s31, s31, 0
	s_add_i32 s34, s79, s41
	global_load_lds_dwordx4 v0, vcc
	s_mov_b32 m0, s34
	s_nop 0
	global_load_lds_dwordx4 v2, s[30:31]
	s_add_i32 m0, s34, 0x2000
	s_nop 0
	global_load_lds_dwordx4 v0, s[30:31]
	v_lshl_add_u64 v[158:159], v[206:207], 0, s[2:3]
	s_mov_b32 m0, s48
	s_nop 0
	global_load_lds_dwordx4 v[158:159], off
	v_lshl_add_u64 v[158:159], v[246:247], 0, s[2:3]
	s_mov_b32 m0, s49
	s_nop 0
	global_load_lds_dwordx4 v[158:159], off
	s_waitcnt vmcnt(8)
	s_waitcnt lgkmcnt(0)
	s_barrier
	s_setprio 1
	s_waitcnt lgkmcnt(0)
	v_mfma_f32_16x16x32_bf16 v[66:69], v[142:145], v[190:193], v[66:69]
	v_mfma_f32_16x16x32_bf16 v[62:65], v[166:169], v[190:193], v[62:65]
	v_mfma_f32_16x16x32_bf16 v[50:53], v[142:145], v[198:201], v[50:53]
	v_mfma_f32_16x16x32_bf16 v[46:49], v[166:169], v[198:201], v[46:49]
	v_mfma_f32_16x16x32_bf16 v[34:37], v[142:145], v[230:233], v[34:37]
	v_mfma_f32_16x16x32_bf16 v[30:33], v[166:169], v[230:233], v[30:33]
	v_mfma_f32_16x16x32_bf16 v[18:21], v[142:145], v[238:241], v[18:21]
	v_mfma_f32_16x16x32_bf16 v[14:17], v[166:169], v[238:241], v[14:17]
	v_mfma_f32_16x16x32_bf16 v[66:69], v[162:165], v[194:197], v[66:69]
	v_mfma_f32_16x16x32_bf16 v[62:65], v[170:173], v[194:197], v[62:65]
	v_mfma_f32_16x16x32_bf16 v[50:53], v[162:165], v[202:205], v[50:53]
	v_mfma_f32_16x16x32_bf16 v[46:49], v[170:173], v[202:205], v[46:49]
	v_mfma_f32_16x16x32_bf16 v[34:37], v[162:165], v[234:237], v[34:37]
	v_mfma_f32_16x16x32_bf16 v[30:33], v[170:173], v[234:237], v[30:33]
	v_mfma_f32_16x16x32_bf16 v[18:21], v[162:165], v[242:245], v[18:21]
	v_mfma_f32_16x16x32_bf16 v[14:17], v[170:173], v[242:245], v[14:17]
	v_mfma_f32_16x16x32_bf16 v[58:61], v[174:177], v[190:193], v[58:61]
	v_mfma_f32_16x16x32_bf16 v[54:57], v[182:185], v[190:193], v[54:57]
	v_mfma_f32_16x16x32_bf16 v[42:45], v[174:177], v[198:201], v[42:45]
	v_mfma_f32_16x16x32_bf16 v[38:41], v[182:185], v[198:201], v[38:41]
	v_mfma_f32_16x16x32_bf16 v[26:29], v[174:177], v[230:233], v[26:29]
	v_mfma_f32_16x16x32_bf16 v[22:25], v[182:185], v[230:233], v[22:25]
	v_mfma_f32_16x16x32_bf16 v[10:13], v[174:177], v[238:241], v[10:13]
	v_mfma_f32_16x16x32_bf16 v[6:9], v[182:185], v[238:241], v[6:9]
	v_mfma_f32_16x16x32_bf16 v[58:61], v[178:181], v[194:197], v[58:61]
	v_mfma_f32_16x16x32_bf16 v[54:57], v[186:189], v[194:197], v[54:57]
	v_mfma_f32_16x16x32_bf16 v[42:45], v[178:181], v[202:205], v[42:45]
	v_mfma_f32_16x16x32_bf16 v[38:41], v[186:189], v[202:205], v[38:41]
	v_mfma_f32_16x16x32_bf16 v[26:29], v[178:181], v[234:237], v[26:29]
	v_mfma_f32_16x16x32_bf16 v[22:25], v[186:189], v[234:237], v[22:25]
	v_mfma_f32_16x16x32_bf16 v[10:13], v[178:181], v[242:245], v[10:13]
	v_mfma_f32_16x16x32_bf16 v[6:9], v[186:189], v[242:245], v[6:9]
	s_setprio 0
	s_barrier
	s_add_i32 s71, s71, 2
	s_add_u32 s69, s69, 0x100
	s_addc_u32 s70, s70, 0
	s_add_u32 s26, s26, 0x100
	s_addc_u32 s27, s27, 0
	s_cmp_gt_u32 s71, 13
	s_cbranch_scc0 .LBB0_818
	s_and_b64 vcc, exec, s[16:17]
	s_cbranch_vccz .LBB0_821
	s_barrier

; #define PG8_STAGE(bufoff, gbase, voff) do { _Pragma("unroll") for (int _i = 0; _i < 2; ++_i) \
;         __builtin_amdgcn_global_load_lds((const unsigned*)((const char*)(gbase) + (voff)[_i]), (PG8_LAS unsigned*)(lds + (bufoff) + ldsw + _i * 8192), 16, 0, 0); } while (0)
; #define PG8_LDA(dst, b, h) do { _Pragma("unroll") for (int m = 0; m < 4; ++m) _Pragma("unroll") for (int k = 0; k < 2; ++k) dst[m][k] = *(const PG8_LAS bf16x8*)(lds + PG8_SA(b, h) + aoff + m * 2048 + k * 1024); } while (0)
; #define PG8_LDB(dst, b, h) do { _Pragma("unroll") for (int n = 0; n < 2; ++n) _Pragma("unroll") for (int k = 0; k < 2; ++k) dst[n][k] = *(const PG8_LAS bf16x8*)(lds + PG8_SB(b, h) + boff + n * 2048 + k * 1024); } while (0)
; #define PG8_MMA(ai, bj, At, Bt) do { __builtin_amdgcn_s_setprio(1); _Pragma("unroll") for (int m = 0; m < 4; ++m) _Pragma("unroll") for (int n = 0; n < 2; ++n) _Pragma("unroll") for (int k = 0; k < 2; ++k) \
;         acc[ai][bj][m][n] = __builtin_amdgcn_mfma_f32_16x16x32_bf16(Bt[n][k], At[m][k], acc[ai][bj][m][n], 0, 0, 0); __builtin_amdgcn_s_setprio(0); } while (0)
; #define PG8_WAIT_V(n) asm volatile("s_waitcnt vmcnt(" #n ")" ::: "memory")
; #define PG8_WAIT_L(n) asm volatile("s_waitcnt lgkmcnt(" #n ")" ::: "memory")
; template <class Epi, class Sched, bool ALIGN_EPI = false, bool SP2 = false>
; __device__ __forceinline__ void gemm_phase(PG8_LAS unsigned char* lds, const Gemm g, const Sched& S, const Epi& E) {
;     ...
;             const bool last = (t == nt - 2);
;             const char* a1 = cA + (size_t)(t + 1) * kstep;
;             const char* a2 = last ? nA : cA + (size_t)(t + 2) * kstep; const char* b2 = last ? nB : cB + (size_t)(t + 2) * kstep;
;             const char* a3 = a2 + kstep; const char* b3 = b2 + kstep;
;             if (last && has_next) S.a_ready(nxt);
;             if constexpr (SP2) {
;             PG8_LDB(B0, 0, 0); PG8_LDB(B1, 0, 1); PG8_SCHED; PG8_LDA(At, 0, 0); PG8_STAGE(PG8_SA(1, 1), a1 + hstep, voffA);
;             PG8_WAIT_V(8); PG8_WAIT_L(0); PG8_BAR; PG8_MMA(0, 0, At, B0); PG8_MMA(0, 1, At, B1); PG8_BAR; PG8_SCHED;
;             PG8_LDA(At, 0, 1); PG8_STAGE(PG8_SB(0, 0), b2, voffB); PG8_STAGE(PG8_SB(0, 1), b2 + hstep, voffB); PG8_STAGE(PG8_SA(0, 0), a2, voffA);
;             PG8_WAIT_V(8); PG8_WAIT_L(0); PG8_BAR; PG8_MMA(1, 0, At, B0); PG8_MMA(1, 1, At, B1); PG8_BAR; PG8_SCHED;
.LBB0_905:
	s_add_u32 s30, s26, 0x100
	s_addc_u32 s31, s27, 0
	s_add_i32 s83, 0, 0x10000
	s_cmp_eq_u32 s82, 28
	s_cselect_b32 s41, s21, s31
	s_cselect_b32 s40, s78, s30
	s_cselect_b32 s35, s19, s81
	s_cselect_b32 s34, s79, s80
	s_add_i32 s84, 0, 0x14000
	v_add_u32_e32 v98, s83, v152
	v_add_u32_e32 v158, s84, v152
	ds_read_b128 v[78:81], v98
	ds_read_b128 v[86:89], v98 offset:1024
	ds_read_b128 v[94:97], v98 offset:2048
	ds_read_b128 v[98:101], v98 offset:3072
	ds_read_b128 v[166:169], v158
	ds_read_b128 v[174:177], v158 offset:1024
	ds_read_b128 v[178:181], v158 offset:2048
	ds_read_b128 v[182:185], v158 offset:3072
	s_add_i32 m0, s49, 0xc000
	ds_read_b128 v[186:189], v173
	ds_read_b128 v[190:193], v173 offset:1024
	ds_read_b128 v[194:197], v173 offset:2048
	ds_read_b128 v[198:201], v173 offset:3072
	ds_read_b128 v[202:205], v173 offset:4096
	ds_read_b128 v[230:233], v173 offset:5120
	ds_read_b128 v[234:237], v173 offset:6144
	ds_read_b128 v[238:241], v173 offset:7168
	global_load_lds_dwordx4 v164, s[26:27]
	s_add_i32 m0, s49, 0xe000
	s_nop 0
	global_load_lds_dwordx4 v162, s[26:27]
	s_waitcnt vmcnt(8)
	s_waitcnt lgkmcnt(0)
	s_barrier
	s_setprio 1
	s_waitcnt lgkmcnt(0)
	v_mfma_f32_16x16x32_bf16 v[146:149], v[78:81], v[186:189], v[146:149]
	v_mfma_f32_16x16x32_bf16 v[142:145], v[94:97], v[186:189], v[142:145]
	v_mfma_f32_16x16x32_bf16 v[130:133], v[78:81], v[194:197], v[130:133]
	v_mfma_f32_16x16x32_bf16 v[126:129], v[94:97], v[194:197], v[126:129]
	v_mfma_f32_16x16x32_bf16 v[114:117], v[78:81], v[202:205], v[114:117]
	v_mfma_f32_16x16x32_bf16 v[110:113], v[94:97], v[202:205], v[110:113]
	v_mfma_f32_16x16x32_bf16 v[90:93], v[78:81], v[234:237], v[90:93]
	v_mfma_f32_16x16x32_bf16 v[82:85], v[94:97], v[234:237], v[82:85]
	v_mfma_f32_16x16x32_bf16 v[146:149], v[86:89], v[190:193], v[146:149]
	v_mfma_f32_16x16x32_bf16 v[142:145], v[98:101], v[190:193], v[142:145]
	v_mfma_f32_16x16x32_bf16 v[130:133], v[86:89], v[198:201], v[130:133]
	v_mfma_f32_16x16x32_bf16 v[126:129], v[98:101], v[198:201], v[126:129]
	v_mfma_f32_16x16x32_bf16 v[114:117], v[86:89], v[230:233], v[114:117]
	v_mfma_f32_16x16x32_bf16 v[110:113], v[98:101], v[230:233], v[110:113]
	v_mfma_f32_16x16x32_bf16 v[90:93], v[86:89], v[238:241], v[90:93]
	v_mfma_f32_16x16x32_bf16 v[82:85], v[98:101], v[238:241], v[82:85]
	v_mfma_f32_16x16x32_bf16 v[138:141], v[166:169], v[186:189], v[138:141]
	v_mfma_f32_16x16x32_bf16 v[134:137], v[178:181], v[186:189], v[134:137]
	v_mfma_f32_16x16x32_bf16 v[122:125], v[166:169], v[194:197], v[122:125]
	v_mfma_f32_16x16x32_bf16 v[118:121], v[178:181], v[194:197], v[118:121]
	v_mfma_f32_16x16x32_bf16 v[106:109], v[166:169], v[202:205], v[106:109]
	v_mfma_f32_16x16x32_bf16 v[102:105], v[178:181], v[202:205], v[102:105]
	v_mfma_f32_16x16x32_bf16 v[74:77], v[166:169], v[234:237], v[74:77]
	v_mfma_f32_16x16x32_bf16 v[70:73], v[178:181], v[234:237], v[70:73]
	v_mfma_f32_16x16x32_bf16 v[138:141], v[174:177], v[190:193], v[138:141]
	v_mfma_f32_16x16x32_bf16 v[134:137], v[182:185], v[190:193], v[134:137]
	v_mfma_f32_16x16x32_bf16 v[122:125], v[174:177], v[198:201], v[122:125]
	v_mfma_f32_16x16x32_bf16 v[118:121], v[182:185], v[198:201], v[118:121]
	v_mfma_f32_16x16x32_bf16 v[106:109], v[174:177], v[230:233], v[106:109]
	v_mfma_f32_16x16x32_bf16 v[102:105], v[182:185], v[230:233], v[102:105]
	v_mfma_f32_16x16x32_bf16 v[74:77], v[174:177], v[238:241], v[74:77]
	v_mfma_f32_16x16x32_bf16 v[70:73], v[182:185], v[238:241], v[70:73]
	s_setprio 0
	s_barrier
	s_add_i32 s26, s83, s48
	s_mov_b32 m0, s26
	ds_read_b128 v[186:189], v173 offset:16384
	ds_read_b128 v[190:193], v173 offset:17408
	ds_read_b128 v[194:197], v173 offset:18432
	ds_read_b128 v[198:201], v173 offset:19456
	ds_read_b128 v[202:205], v173 offset:20480
	ds_read_b128 v[230:233], v173 offset:21504
	ds_read_b128 v[234:237], v173 offset:22528
	ds_read_b128 v[238:241], v173 offset:23552
	global_load_lds_dwordx4 v2, s[34:35]
	s_add_i32 m0, s26, 0x2000
	s_add_u32 s26, s34, 0x80000
	s_addc_u32 s27, s35, 0
	s_add_i32 s83, s84, s48
	global_load_lds_dwordx4 v0, s[34:35]
	s_mov_b32 m0, s83
	s_nop 0
	global_load_lds_dwordx4 v2, s[26:27]
	s_add_i32 m0, s83, 0x2000
	s_nop 0
	global_load_lds_dwordx4 v0, s[26:27]
	s_mov_b32 m0, s49
	s_nop 0
	global_load_lds_dwordx4 v2, s[40:41]
	s_mov_b32 m0, s51
	s_nop 0
	global_load_lds_dwordx4 v0, s[40:41]
	s_waitcnt vmcnt(8)
	s_waitcnt lgkmcnt(0)
	s_barrier
	s_setprio 1
	s_waitcnt lgkmcnt(0)
	v_mfma_f32_16x16x32_bf16 v[66:69], v[78:81], v[186:189], v[66:69]
	v_mfma_f32_16x16x32_bf16 v[62:65], v[94:97], v[186:189], v[62:65]
	v_mfma_f32_16x16x32_bf16 v[50:53], v[78:81], v[194:197], v[50:53]
	v_mfma_f32_16x16x32_bf16 v[46:49], v[94:97], v[194:197], v[46:49]
	v_mfma_f32_16x16x32_bf16 v[34:37], v[78:81], v[202:205], v[34:37]
	v_mfma_f32_16x16x32_bf16 v[30:33], v[94:97], v[202:205], v[30:33]
	v_mfma_f32_16x16x32_bf16 v[18:21], v[78:81], v[234:237], v[18:21]
	v_mfma_f32_16x16x32_bf16 v[14:17], v[94:97], v[234:237], v[14:17]
	v_mfma_f32_16x16x32_bf16 v[66:69], v[86:89], v[190:193], v[66:69]
	v_mfma_f32_16x16x32_bf16 v[62:65], v[98:101], v[190:193], v[62:65]
	v_mfma_f32_16x16x32_bf16 v[50:53], v[86:89], v[198:201], v[50:53]
	v_mfma_f32_16x16x32_bf16 v[46:49], v[98:101], v[198:201], v[46:49]
	v_mfma_f32_16x16x32_bf16 v[34:37], v[86:89], v[230:233], v[34:37]
	v_mfma_f32_16x16x32_bf16 v[30:33], v[98:101], v[230:233], v[30:33]
	v_mfma_f32_16x16x32_bf16 v[18:21], v[86:89], v[238:241], v[18:21]
	v_mfma_f32_16x16x32_bf16 v[14:17], v[98:101], v[238:241], v[14:17]
	v_mfma_f32_16x16x32_bf16 v[58:61], v[166:169], v[186:189], v[58:61]
	v_mfma_f32_16x16x32_bf16 v[54:57], v[178:181], v[186:189], v[54:57]
	v_mfma_f32_16x16x32_bf16 v[42:45], v[166:169], v[194:197], v[42:45]
	v_mfma_f32_16x16x32_bf16 v[38:41], v[178:181], v[194:197], v[38:41]
	v_mfma_f32_16x16x32_bf16 v[26:29], v[166:169], v[202:205], v[26:29]
	v_mfma_f32_16x16x32_bf16 v[22:25], v[178:181], v[202:205], v[22:25]
	v_mfma_f32_16x16x32_bf16 v[10:13], v[166:169], v[234:237], v[10:13]
	v_mfma_f32_16x16x32_bf16 v[6:9], v[178:181], v[234:237], v[6:9]
	v_mfma_f32_16x16x32_bf16 v[58:61], v[174:177], v[190:193], v[58:61]
	v_mfma_f32_16x16x32_bf16 v[54:57], v[182:185], v[190:193], v[54:57]
	v_mfma_f32_16x16x32_bf16 v[42:45], v[174:177], v[198:201], v[42:45]
	v_mfma_f32_16x16x32_bf16 v[38:41], v[182:185], v[198:201], v[38:41]
	v_mfma_f32_16x16x32_bf16 v[26:29], v[174:177], v[230:233], v[26:29]
	v_mfma_f32_16x16x32_bf16 v[22:25], v[182:185], v[230:233], v[22:25]
	v_mfma_f32_16x16x32_bf16 v[10:13], v[174:177], v[238:241], v[10:13]
	v_mfma_f32_16x16x32_bf16 v[6:9], v[182:185], v[238:241], v[6:9]
	s_setprio 0
	s_barrier
; #define PG8_STAGE(bufoff, gbase, voff) do { _Pragma("unroll") for (int _i = 0; _i < 2; ++_i) \
;         __builtin_amdgcn_global_load_lds((const unsigned*)((const char*)(gbase) + (voff)[_i]), (PG8_LAS unsigned*)(lds + (bufoff) + ldsw + _i * 8192), 16, 0, 0); } while (0)
; #define PG8_LDA(dst, b, h) do { _Pragma("unroll") for (int m = 0; m < 4; ++m) _Pragma("unroll") for (int k = 0; k < 2; ++k) dst[m][k] = *(const PG8_LAS bf16x8*)(lds + PG8_SA(b, h) + aoff + m * 2048 + k * 1024); } while (0)
; #define PG8_LDB(dst, b, h) do { _Pragma("unroll") for (int n = 0; n < 2; ++n) _Pragma("unroll") for (int k = 0; k < 2; ++k) dst[n][k] = *(const PG8_LAS bf16x8*)(lds + PG8_SB(b, h) + boff + n * 2048 + k * 1024); } while (0)
; #define PG8_MMA(ai, bj, At, Bt) do { __builtin_amdgcn_s_setprio(1); _Pragma("unroll") for (int m = 0; m < 4; ++m) _Pragma("unroll") for (int n = 0; n < 2; ++n) _Pragma("unroll") for (int k = 0; k < 2; ++k) \
;         acc[ai][bj][m][n] = __builtin_amdgcn_mfma_f32_16x16x32_bf16(Bt[n][k], At[m][k], acc[ai][bj][m][n], 0, 0, 0); __builtin_amdgcn_s_setprio(0); } while (0)
; #define PG8_WAIT_V(n) asm volatile("s_waitcnt vmcnt(" #n ")" ::: "memory")
; #define PG8_WAIT_L(n) asm volatile("s_waitcnt lgkmcnt(" #n ")" ::: "memory")
; #define PG8_BAR __builtin_amdgcn_s_barrier()
; #define PG8_SCHED __builtin_amdgcn_sched_barrier(0)
; template <class Epi, class Sched, bool ALIGN_EPI = false, bool SP2 = false>
; __device__ __forceinline__ void gemm_phase(PG8_LAS unsigned char* lds, const Gemm g, const Sched& S, const Epi& E) {
;     ...
;             PG8_LDB(B0, 1, 0); PG8_LDB(B1, 1, 1); PG8_SCHED; PG8_LDA(At, 1, 0); PG8_STAGE(PG8_SA(0, 1), a2 + hstep, voffA);
;             PG8_WAIT_V(8); PG8_WAIT_L(0); PG8_BAR; PG8_MMA(0, 0, At, B0); PG8_MMA(0, 1, At, B1); PG8_BAR; PG8_SCHED;
;             PG8_LDA(At, 1, 1); PG8_STAGE(PG8_SB(1, 0), b3, voffB); PG8_STAGE(PG8_SB(1, 1), b3 + hstep, voffB); PG8_STAGE(PG8_SA(1, 0), a3, voffA);
;             PG8_WAIT_V(8); PG8_WAIT_L(0); PG8_BAR; PG8_MMA(1, 0, At, B0); PG8_MMA(1, 1, At, B1); PG8_BAR; PG8_SCHED;
	s_add_i32 s83, 0, 0x18000
	s_add_i32 s84, 0, 0x1c000
	v_add_u32_e32 v98, s83, v152
	v_add_u32_e32 v182, s84, v152
	ds_read_b128 v[78:81], v98
	ds_read_b128 v[86:89], v98 offset:1024
	ds_read_b128 v[94:97], v98 offset:2048
	ds_read_b128 v[98:101], v98 offset:3072
	ds_read_b128 v[166:169], v182
	ds_read_b128 v[174:177], v182 offset:1024
	ds_read_b128 v[178:181], v182 offset:2048
	ds_read_b128 v[182:185], v182 offset:3072
	s_add_u32 s26, s40, 0x80000
	s_addc_u32 s27, s41, 0
	s_mov_b32 m0, s52
	ds_read_b128 v[186:189], v173 offset:32768
	ds_read_b128 v[190:193], v173 offset:33792
	ds_read_b128 v[194:197], v173 offset:34816
	ds_read_b128 v[198:201], v173 offset:35840
	ds_read_b128 v[202:205], v173 offset:36864
	ds_read_b128 v[230:233], v173 offset:37888
	ds_read_b128 v[234:237], v173 offset:38912
	ds_read_b128 v[238:241], v173 offset:39936
	global_load_lds_dwordx4 v2, s[26:27]
	s_mov_b32 m0, s53
	s_nop 0
	global_load_lds_dwordx4 v0, s[26:27]
	s_waitcnt vmcnt(8)
	s_waitcnt lgkmcnt(0)
	s_barrier
	s_setprio 1
	s_waitcnt lgkmcnt(0)
	v_mfma_f32_16x16x32_bf16 v[146:149], v[78:81], v[186:189], v[146:149]
	v_mfma_f32_16x16x32_bf16 v[142:145], v[94:97], v[186:189], v[142:145]
	v_mfma_f32_16x16x32_bf16 v[130:133], v[78:81], v[194:197], v[130:133]
	v_mfma_f32_16x16x32_bf16 v[126:129], v[94:97], v[194:197], v[126:129]
	v_mfma_f32_16x16x32_bf16 v[114:117], v[78:81], v[202:205], v[114:117]
	v_mfma_f32_16x16x32_bf16 v[110:113], v[94:97], v[202:205], v[110:113]
	v_mfma_f32_16x16x32_bf16 v[90:93], v[78:81], v[234:237], v[90:93]
	v_mfma_f32_16x16x32_bf16 v[82:85], v[94:97], v[234:237], v[82:85]
	v_mfma_f32_16x16x32_bf16 v[146:149], v[86:89], v[190:193], v[146:149]
	v_mfma_f32_16x16x32_bf16 v[142:145], v[98:101], v[190:193], v[142:145]
	v_mfma_f32_16x16x32_bf16 v[130:133], v[86:89], v[198:201], v[130:133]
	v_mfma_f32_16x16x32_bf16 v[126:129], v[98:101], v[198:201], v[126:129]
	v_mfma_f32_16x16x32_bf16 v[114:117], v[86:89], v[230:233], v[114:117]
	v_mfma_f32_16x16x32_bf16 v[110:113], v[98:101], v[230:233], v[110:113]
	v_mfma_f32_16x16x32_bf16 v[90:93], v[86:89], v[238:241], v[90:93]
	v_mfma_f32_16x16x32_bf16 v[82:85], v[98:101], v[238:241], v[82:85]
	v_mfma_f32_16x16x32_bf16 v[138:141], v[166:169], v[186:189], v[138:141]
	v_mfma_f32_16x16x32_bf16 v[134:137], v[178:181], v[186:189], v[134:137]
	v_mfma_f32_16x16x32_bf16 v[122:125], v[166:169], v[194:197], v[122:125]
	v_mfma_f32_16x16x32_bf16 v[118:121], v[178:181], v[194:197], v[118:121]
	v_mfma_f32_16x16x32_bf16 v[106:109], v[166:169], v[202:205], v[106:109]
	v_mfma_f32_16x16x32_bf16 v[102:105], v[178:181], v[202:205], v[102:105]
	v_mfma_f32_16x16x32_bf16 v[74:77], v[166:169], v[234:237], v[74:77]
	v_mfma_f32_16x16x32_bf16 v[70:73], v[178:181], v[234:237], v[70:73]
	v_mfma_f32_16x16x32_bf16 v[138:141], v[174:177], v[190:193], v[138:141]
	v_mfma_f32_16x16x32_bf16 v[134:137], v[182:185], v[190:193], v[134:137]
	v_mfma_f32_16x16x32_bf16 v[122:125], v[174:177], v[198:201], v[122:125]
	v_mfma_f32_16x16x32_bf16 v[118:121], v[182:185], v[198:201], v[118:121]
	v_mfma_f32_16x16x32_bf16 v[106:109], v[174:177], v[230:233], v[106:109]
	v_mfma_f32_16x16x32_bf16 v[102:105], v[182:185], v[230:233], v[102:105]
	v_mfma_f32_16x16x32_bf16 v[74:77], v[174:177], v[238:241], v[74:77]
	v_mfma_f32_16x16x32_bf16 v[70:73], v[182:185], v[238:241], v[70:73]
	s_setprio 0
	s_barrier
	s_add_u32 vcc_lo, s34, s2
	s_addc_u32 vcc_hi, s35, s3
	s_add_i32 s26, s83, s48
	s_mov_b32 m0, s26
	ds_read_b128 v[186:189], v173 offset:49152
	ds_read_b128 v[190:193], v173 offset:50176
	ds_read_b128 v[194:197], v173 offset:51200
	ds_read_b128 v[198:201], v173 offset:52224
	ds_read_b128 v[202:205], v173 offset:53248
	ds_read_b128 v[230:233], v173 offset:54272
	ds_read_b128 v[234:237], v173 offset:55296
	ds_read_b128 v[238:241], v173 offset:56320
	global_load_lds_dwordx4 v2, vcc
	s_add_i32 m0, s26, 0x2000
	s_add_u32 s26, s34, 0x80080
	s_addc_u32 s27, s35, 0
	s_add_i32 s34, s84, s48
	global_load_lds_dwordx4 v0, vcc
	s_mov_b32 m0, s34
	s_nop 0
	global_load_lds_dwordx4 v2, s[26:27]
	s_add_i32 m0, s34, 0x2000
	s_nop 0
	global_load_lds_dwordx4 v0, s[26:27]
	s_add_u32 vcc_lo, s40, s2
	s_addc_u32 vcc_hi, s41, s3
	s_mov_b32 m0, s66
	s_nop 0
	global_load_lds_dwordx4 v2, vcc
	s_mov_b32 m0, s67
	s_nop 0
	global_load_lds_dwordx4 v0, vcc
	s_waitcnt vmcnt(8)
	s_waitcnt lgkmcnt(0)
	s_barrier
	s_setprio 1
	s_waitcnt lgkmcnt(0)
	v_mfma_f32_16x16x32_bf16 v[66:69], v[78:81], v[186:189], v[66:69]
	v_mfma_f32_16x16x32_bf16 v[62:65], v[94:97], v[186:189], v[62:65]
	v_mfma_f32_16x16x32_bf16 v[50:53], v[78:81], v[194:197], v[50:53]
	v_mfma_f32_16x16x32_bf16 v[46:49], v[94:97], v[194:197], v[46:49]
	v_mfma_f32_16x16x32_bf16 v[34:37], v[78:81], v[202:205], v[34:37]
	v_mfma_f32_16x16x32_bf16 v[30:33], v[94:97], v[202:205], v[30:33]
	v_mfma_f32_16x16x32_bf16 v[18:21], v[78:81], v[234:237], v[18:21]
	v_mfma_f32_16x16x32_bf16 v[14:17], v[94:97], v[234:237], v[14:17]
	v_mfma_f32_16x16x32_bf16 v[66:69], v[86:89], v[190:193], v[66:69]
	v_mfma_f32_16x16x32_bf16 v[62:65], v[98:101], v[190:193], v[62:65]
	v_mfma_f32_16x16x32_bf16 v[50:53], v[86:89], v[198:201], v[50:53]
	v_mfma_f32_16x16x32_bf16 v[46:49], v[98:101], v[198:201], v[46:49]
	v_mfma_f32_16x16x32_bf16 v[34:37], v[86:89], v[230:233], v[34:37]
	v_mfma_f32_16x16x32_bf16 v[30:33], v[98:101], v[230:233], v[30:33]
	v_mfma_f32_16x16x32_bf16 v[18:21], v[86:89], v[238:241], v[18:21]
	v_mfma_f32_16x16x32_bf16 v[14:17], v[98:101], v[238:241], v[14:17]
	v_mfma_f32_16x16x32_bf16 v[58:61], v[166:169], v[186:189], v[58:61]
	v_mfma_f32_16x16x32_bf16 v[54:57], v[178:181], v[186:189], v[54:57]
	v_mfma_f32_16x16x32_bf16 v[42:45], v[166:169], v[194:197], v[42:45]
	v_mfma_f32_16x16x32_bf16 v[38:41], v[178:181], v[194:197], v[38:41]
	v_mfma_f32_16x16x32_bf16 v[26:29], v[166:169], v[202:205], v[26:29]
	v_mfma_f32_16x16x32_bf16 v[22:25], v[178:181], v[202:205], v[22:25]
	v_mfma_f32_16x16x32_bf16 v[10:13], v[166:169], v[234:237], v[10:13]
	v_mfma_f32_16x16x32_bf16 v[6:9], v[178:181], v[234:237], v[6:9]
	v_mfma_f32_16x16x32_bf16 v[58:61], v[174:177], v[190:193], v[58:61]
	v_mfma_f32_16x16x32_bf16 v[54:57], v[182:185], v[190:193], v[54:57]
	v_mfma_f32_16x16x32_bf16 v[42:45], v[174:177], v[198:201], v[42:45]
	v_mfma_f32_16x16x32_bf16 v[38:41], v[182:185], v[198:201], v[38:41]
	v_mfma_f32_16x16x32_bf16 v[26:29], v[174:177], v[230:233], v[26:29]
	v_mfma_f32_16x16x32_bf16 v[22:25], v[182:185], v[230:233], v[22:25]
	v_mfma_f32_16x16x32_bf16 v[10:13], v[174:177], v[238:241], v[10:13]
	v_mfma_f32_16x16x32_bf16 v[6:9], v[182:185], v[238:241], v[6:9]
	s_setprio 0
	s_barrier
;     __device__ __forceinline__ void operator()(const f32x4 (&acc)[2][2][4][2], const Unit& u, int wr, int wc, int fr, int fq) const {
;         const int row0 = u.pm * BM + wr * 64 + fr; const int col0 = u.pn * BM + wc * 32 + 4 * fq;
;         f32x4 gv[2][2];
; #pragma unroll
;         for (int bj = 0; bj < 2; ++bj)
; #pragma unroll
;             for (int n = 0; n < 2; ++n) gv[bj][n] = xg ? *(const f32x4*)(gn + col0 + bj * HALF + n * 16) : (f32x4){0.f, 0.f, 0.f, 0.f};
; #pragma unroll
;         for (int ai = 0; ai < 2; ++ai)
; #pragma unroll
;             for (int m = 0; m < 4; ++m) { const size_t off = (size_t)(row0 + ai * HALF + m * 16) * ldc + col0; float ss = 0.f;
; #pragma unroll
;                 for (int bj = 0; bj < 2; ++bj)
; #pragma unroll
;                     for (int n = 0; n < 2; ++n) { const f32x4 bs = *(const f32x4*)(base + off + bj * HALF + n * 16); const f32x4 o = bs + acc[ai][bj][m][n] * scale;
;                         *(f32x4*)(out + off + bj * HALF + n * 16) = o;
;                         if (xg) { ss += (o[0] * o[0] + o[1] * o[1]) + (o[2] * o[2] + o[3] * o[3]); const f32x4 og = o * gv[bj][n];
;                             typedef unsigned u32x2v __attribute__((ext_vector_type(2))); u32x2v w; w.x = cvt_pk_bf16(og[0], og[1]); w.y = cvt_pk_bf16(og[2], og[3]); *(u32x2v*)(xg + off + bj * HALF + n * 16) = w; } }
;                 if (xg) { ss += __shfl_xor(ss, 16); ss += __shfl_xor(ss, 32); if (fq == 0) atomicAdd(rowss + row0 + ai * HALF + m * 16, (rowss_t)(ss * 16777216.0f)); } }
	s_add_i32 s82, s82, 2
	s_add_u32 s80, s80, 0x100
	s_addc_u32 s81, s81, 0
	s_cmp_gt_u32 s82, 29
	s_mov_b64 s[26:27], s[30:31]
	s_cbranch_scc0 .LBB0_905
	v_lshl_add_u32 v170, s70, 8, v5
	v_lshl_or_b32 v168, s71, 8, v172
	v_ashrrev_i32_e32 v171, 31, v170
	v_ashrrev_i32_e32 v169, 31, v168
	v_readlane_b32 s6, v252, 59
	v_lshlrev_b64 v[158:159], 11, v[170:171]
	v_readlane_b32 s7, v252, 60
	v_lshl_add_u64 v[166:167], v[158:159], 0, v[168:169]
	v_lshl_add_u64 v[158:159], v[166:167], 2, s[12:13]
	v_lshl_add_u64 v[78:79], v[168:169], 2, s[6:7]
	global_load_dwordx4 v[98:101], v[78:79], off
	global_load_dwordx4 v[94:97], v[78:79], off offset:64
	global_load_dwordx4 v[86:89], v[78:79], off offset:512
	s_nop 0
	global_load_dwordx4 v[78:81], v[78:79], off offset:576
	s_nop 0
	global_load_dwordx4 v[174:177], v[158:159], off
	global_load_dwordx4 v[182:185], v[158:159], off offset:64
	global_load_dwordx4 v[186:189], v[158:159], off offset:512
	global_load_dwordx4 v[190:193], v[158:159], off offset:576
	s_waitcnt vmcnt(3) lgkmcnt(0)
	v_pk_add_f32 v[148:149], v[148:149], v[176:177]
	v_pk_add_f32 v[146:147], v[146:147], v[174:175]
	v_mul_f32_e32 v161, v149, v149
	v_mul_f32_e32 v160, v147, v147
	global_store_dwordx4 v[158:159], v[146:149], off
	v_fmac_f32_e32 v160, v146, v146
	v_fmac_f32_e32 v161, v148, v148
	v_pk_mul_f32 v[148:149], v[100:101], v[148:149]
	v_pk_mul_f32 v[146:147], v[98:99], v[146:147]
	v_add_f32_e32 v174, v160, v161
	v_cvt_pk_bf16_f32 v146, v146, v147
	v_cvt_pk_bf16_f32 v147, v148, v149
	v_lshl_add_u64 v[160:161], v[166:167], 1, s[14:15]
	global_store_dwordx2 v[160:161], v[146:147], off
	s_waitcnt vmcnt(4) lgkmcnt(0)
	v_pk_add_f32 v[144:145], v[144:145], v[184:185]
	v_pk_add_f32 v[142:143], v[142:143], v[182:183]
	v_mul_f32_e32 v147, v145, v145
	v_mul_f32_e32 v146, v143, v143
	global_store_dwordx4 v[158:159], v[142:145], off offset:64
	v_fmac_f32_e32 v146, v142, v142
	v_fmac_f32_e32 v147, v144, v144
	v_pk_mul_f32 v[144:145], v[96:97], v[144:145]
	v_pk_mul_f32 v[142:143], v[94:95], v[142:143]
	v_add_f32_e32 v146, v146, v147
	v_cvt_pk_bf16_f32 v142, v142, v143
	v_cvt_pk_bf16_f32 v143, v144, v145
	global_store_dwordx2 v[160:161], v[142:143], off offset:32
	v_add_f32_e32 v146, v174, v146
	s_waitcnt vmcnt(5) lgkmcnt(0)
	v_pk_add_f32 v[140:141], v[140:141], v[188:189]
	v_pk_add_f32 v[138:139], v[138:139], v[186:187]
	v_mul_f32_e32 v143, v141, v141
	v_mul_f32_e32 v142, v139, v139
	global_store_dwordx4 v[158:159], v[138:141], off offset:512
	v_fmac_f32_e32 v142, v138, v138
	v_fmac_f32_e32 v143, v140, v140
	v_pk_mul_f32 v[140:141], v[88:89], v[140:141]
	v_pk_mul_f32 v[138:139], v[86:87], v[138:139]
	v_add_f32_e32 v142, v142, v143
	v_cvt_pk_bf16_f32 v138, v138, v139
	v_cvt_pk_bf16_f32 v139, v140, v141
	global_store_dwordx2 v[160:161], v[138:139], off offset:256
	v_add_f32_e32 v142, v146, v142
	s_waitcnt vmcnt(6) lgkmcnt(0)
	v_pk_add_f32 v[136:137], v[136:137], v[192:193]
	v_pk_add_f32 v[134:135], v[134:135], v[190:191]
	global_store_dwordx4 v[158:159], v[134:137], off offset:576
	v_pk_mul_f32 v[140:141], v[78:79], v[134:135]
	v_pk_mul_f32 v[138:139], v[80:81], v[136:137]
	v_mul_f32_e32 v135, v135, v135
	v_fmac_f32_e32 v135, v134, v134
	v_mul_f32_e32 v134, v137, v137
	v_fmac_f32_e32 v134, v136, v136
	v_and_b32_e32 v136, 64, v218
	v_add_f32_e32 v134, v135, v134
	v_xor_b32_e32 v135, 16, v218
	v_add_u32_e32 v137, 64, v136
	v_cmp_lt_i32_e32 vcc, v135, v137
	v_add_f32_e32 v134, v142, v134
	v_cvt_pk_bf16_f32 v140, v140, v141
	v_cndmask_b32_e32 v135, v218, v135, vcc
	v_lshlrev_b32_e32 v136, 2, v135
	ds_bpermute_b32 v135, v136, v134
	v_cvt_pk_bf16_f32 v141, v138, v139
	global_store_dwordx2 v[160:161], v[140:141], off offset:288
	s_waitcnt lgkmcnt(0)
	v_add_f32_e32 v138, v134, v135
	v_xor_b32_e32 v134, 32, v218
	v_cmp_lt_i32_e32 vcc, v134, v137
	s_nop 1
	v_cndmask_b32_e32 v134, v218, v134, vcc
	v_lshlrev_b32_e32 v137, 2, v134
	ds_bpermute_b32 v139, v137, v138
	v_lshl_add_u64 v[134:135], v[170:171], 3, s[16:17]
	s_and_saveexec_b64 s[26:27], s[8:9]
	s_cbranch_execz .LBB0_908
	s_waitcnt lgkmcnt(0)
	v_add_f32_e32 v138, v138, v139
	v_mul_f32_e32 v138, 0x4b800000, v138
	v_trunc_f32_e32 v138, v138
	v_mul_f32_e32 v139, 0x2f800000, v138
	v_floor_f32_e32 v139, v139
	v_fmac_f32_e32 v138, 0xcf800000, v139
	v_cvt_u32_f32_e32 v138, v138
	v_cvt_u32_f32_e32 v139, v139
	global_atomic_add_x2 v[134:135], v[138:139], off

; #define PG8_STAGE(bufoff, gbase, voff) do { _Pragma("unroll") for (int _i = 0; _i < 2; ++_i) \
;         __builtin_amdgcn_global_load_lds((const unsigned*)((const char*)(gbase) + (voff)[_i]), (PG8_LAS unsigned*)(lds + (bufoff) + ldsw + _i * 8192), 16, 0, 0); } while (0)
; #define PG8_LDA(dst, b, h) do { _Pragma("unroll") for (int m = 0; m < 4; ++m) _Pragma("unroll") for (int k = 0; k < 2; ++k) dst[m][k] = *(const PG8_LAS bf16x8*)(lds + PG8_SA(b, h) + aoff + m * 2048 + k * 1024); } while (0)
; #define PG8_LDB(dst, b, h) do { _Pragma("unroll") for (int n = 0; n < 2; ++n) _Pragma("unroll") for (int k = 0; k < 2; ++k) dst[n][k] = *(const PG8_LAS bf16x8*)(lds + PG8_SB(b, h) + boff + n * 2048 + k * 1024); } while (0)
; #define PG8_MMA(ai, bj, At, Bt) do { __builtin_amdgcn_s_setprio(1); _Pragma("unroll") for (int m = 0; m < 4; ++m) _Pragma("unroll") for (int n = 0; n < 2; ++n) _Pragma("unroll") for (int k = 0; k < 2; ++k) \
;         acc[ai][bj][m][n] = __builtin_amdgcn_mfma_f32_16x16x32_bf16(Bt[n][k], At[m][k], acc[ai][bj][m][n], 0, 0, 0); __builtin_amdgcn_s_setprio(0); } while (0)
; #define PG8_WAIT_V(n) asm volatile("s_waitcnt vmcnt(" #n ")" ::: "memory")
; #define PG8_WAIT_L(n) asm volatile("s_waitcnt lgkmcnt(" #n ")" ::: "memory")
; template <class Epi, class Sched, bool ALIGN_EPI = false, bool SP2 = false>
; __device__ __forceinline__ void gemm_phase(PG8_LAS unsigned char* lds, const Gemm g, const Sched& S, const Epi& E) {
;     ...
;             const bool last = (t == nt - 2);
;             const char* a1 = cA + (size_t)(t + 1) * kstep;
;             const char* a2 = last ? nA : cA + (size_t)(t + 2) * kstep; const char* b2 = last ? nB : cB + (size_t)(t + 2) * kstep;
;             const char* a3 = a2 + kstep; const char* b3 = b2 + kstep;
;             if (last && has_next) S.a_ready(nxt);
;             if constexpr (SP2) {
;             PG8_LDB(B0, 0, 0); PG8_LDB(B1, 0, 1); PG8_SCHED; PG8_LDA(At, 0, 0); PG8_STAGE(PG8_SA(1, 1), a1 + hstep, voffA);
;             PG8_WAIT_V(8); PG8_WAIT_L(0); PG8_BAR; PG8_MMA(0, 0, At, B0); PG8_MMA(0, 1, At, B1); PG8_BAR; PG8_SCHED;
;             PG8_LDA(At, 0, 1); PG8_STAGE(PG8_SB(0, 0), b2, voffB); PG8_STAGE(PG8_SB(0, 1), b2 + hstep, voffB); PG8_STAGE(PG8_SA(0, 0), a2, voffA);
;             PG8_WAIT_V(8); PG8_WAIT_L(0); PG8_BAR; PG8_MMA(1, 0, At, B0); PG8_MMA(1, 1, At, B1); PG8_BAR; PG8_SCHED;
.LBB0_1016:
	s_add_u32 s24, s22, 0xfff80080
	s_addc_u32 s25, s23, -1
	s_add_i32 s67, 0, 0x10000
	s_cmp_eq_u32 s66, 28
	s_cselect_b32 s27, s17, s25
	s_cselect_b32 s26, s50, s24
	v_add_u32_e32 v158, s67, v152
	s_cselect_b32 s25, s15, s53
	s_cselect_b32 s24, s51, s52
	s_add_i32 s69, 0, 0x14000
	ds_read_b128 v[142:145], v158
	ds_read_b128 v[146:149], v158 offset:1024
	ds_read_b128 v[164:167], v158 offset:2048
	ds_read_b128 v[168:171], v158 offset:3072
	v_add_u32_e32 v158, s69, v152
	ds_read_b128 v[172:175], v158
	ds_read_b128 v[176:179], v158 offset:1024
	ds_read_b128 v[180:183], v158 offset:2048
	ds_read_b128 v[184:187], v158 offset:3072
	s_add_i32 m0, s41, 0xc000
	ds_read_b128 v[188:191], v163
	ds_read_b128 v[192:195], v163 offset:1024
	ds_read_b128 v[196:199], v163 offset:2048
	ds_read_b128 v[200:203], v163 offset:3072
	ds_read_b128 v[204:207], v163 offset:4096
	ds_read_b128 v[230:233], v163 offset:5120
	ds_read_b128 v[234:237], v163 offset:6144
	ds_read_b128 v[238:241], v163 offset:7168
	global_load_lds_dwordx4 v140, s[22:23]
	s_add_i32 m0, s41, 0xe000
	s_nop 0
	global_load_lds_dwordx4 v138, s[22:23]
	s_waitcnt vmcnt(8)
	s_waitcnt lgkmcnt(0)
	s_barrier
	s_setprio 1
	s_waitcnt lgkmcnt(0)
	v_mfma_f32_16x16x32_bf16 v[130:133], v[142:145], v[188:191], v[130:133]
	v_mfma_f32_16x16x32_bf16 v[126:129], v[164:167], v[188:191], v[126:129]
	v_mfma_f32_16x16x32_bf16 v[114:117], v[142:145], v[196:199], v[114:117]
	v_mfma_f32_16x16x32_bf16 v[110:113], v[164:167], v[196:199], v[110:113]
	v_mfma_f32_16x16x32_bf16 v[98:101], v[142:145], v[204:207], v[98:101]
	v_mfma_f32_16x16x32_bf16 v[94:97], v[164:167], v[204:207], v[94:97]
	v_mfma_f32_16x16x32_bf16 v[82:85], v[142:145], v[234:237], v[82:85]
	v_mfma_f32_16x16x32_bf16 v[78:81], v[164:167], v[234:237], v[78:81]
	v_mfma_f32_16x16x32_bf16 v[130:133], v[146:149], v[192:195], v[130:133]
	v_mfma_f32_16x16x32_bf16 v[126:129], v[168:171], v[192:195], v[126:129]
	v_mfma_f32_16x16x32_bf16 v[114:117], v[146:149], v[200:203], v[114:117]
	v_mfma_f32_16x16x32_bf16 v[110:113], v[168:171], v[200:203], v[110:113]
	v_mfma_f32_16x16x32_bf16 v[98:101], v[146:149], v[230:233], v[98:101]
	v_mfma_f32_16x16x32_bf16 v[94:97], v[168:171], v[230:233], v[94:97]
	v_mfma_f32_16x16x32_bf16 v[82:85], v[146:149], v[238:241], v[82:85]
	v_mfma_f32_16x16x32_bf16 v[78:81], v[168:171], v[238:241], v[78:81]
	v_mfma_f32_16x16x32_bf16 v[122:125], v[172:175], v[188:191], v[122:125]
	v_mfma_f32_16x16x32_bf16 v[118:121], v[180:183], v[188:191], v[118:121]
	v_mfma_f32_16x16x32_bf16 v[106:109], v[172:175], v[196:199], v[106:109]
	v_mfma_f32_16x16x32_bf16 v[102:105], v[180:183], v[196:199], v[102:105]
	v_mfma_f32_16x16x32_bf16 v[90:93], v[172:175], v[204:207], v[90:93]
	v_mfma_f32_16x16x32_bf16 v[86:89], v[180:183], v[204:207], v[86:89]
	v_mfma_f32_16x16x32_bf16 v[74:77], v[172:175], v[234:237], v[74:77]
	v_mfma_f32_16x16x32_bf16 v[70:73], v[180:183], v[234:237], v[70:73]
	v_mfma_f32_16x16x32_bf16 v[122:125], v[176:179], v[192:195], v[122:125]
	v_mfma_f32_16x16x32_bf16 v[118:121], v[184:187], v[192:195], v[118:121]
	v_mfma_f32_16x16x32_bf16 v[106:109], v[176:179], v[200:203], v[106:109]
	v_mfma_f32_16x16x32_bf16 v[102:105], v[184:187], v[200:203], v[102:105]
	v_mfma_f32_16x16x32_bf16 v[90:93], v[176:179], v[230:233], v[90:93]
	v_mfma_f32_16x16x32_bf16 v[86:89], v[184:187], v[230:233], v[86:89]
	v_mfma_f32_16x16x32_bf16 v[74:77], v[176:179], v[238:241], v[74:77]
	v_mfma_f32_16x16x32_bf16 v[70:73], v[184:187], v[238:241], v[70:73]
	s_setprio 0
	s_barrier
	s_add_i32 s67, s67, s30
	s_mov_b32 m0, s67
	ds_read_b128 v[188:191], v163 offset:16384
	ds_read_b128 v[192:195], v163 offset:17408
	ds_read_b128 v[196:199], v163 offset:18432
	ds_read_b128 v[200:203], v163 offset:19456
	ds_read_b128 v[204:207], v163 offset:20480
	ds_read_b128 v[230:233], v163 offset:21504
	ds_read_b128 v[234:237], v163 offset:22528
	ds_read_b128 v[238:241], v163 offset:23552
	global_load_lds_dwordx4 v2, s[24:25]
	s_add_i32 m0, s67, 0x2000
	s_add_u32 s70, s24, 0x80000
	s_addc_u32 s71, s25, 0
	s_add_i32 s67, s69, s30
	global_load_lds_dwordx4 v0, s[24:25]
	s_mov_b32 m0, s67
	v_lshl_add_u64 v[246:247], s[26:27], 0, v[134:135]
	global_load_lds_dwordx4 v2, s[70:71]
	s_add_i32 m0, s67, 0x2000
	s_nop 0
	global_load_lds_dwordx4 v0, s[70:71]
	v_lshl_add_u64 v[244:245], s[26:27], 0, v[136:137]
	s_mov_b32 m0, s41
	s_nop 0
	global_load_lds_dwordx4 v136, s[26:27]
	s_mov_b32 m0, s42
	s_nop 0
	global_load_lds_dwordx4 v134, s[26:27]
	s_waitcnt vmcnt(8)
	s_waitcnt lgkmcnt(0)
	s_barrier
	s_setprio 1
	s_waitcnt lgkmcnt(0)
	v_mfma_f32_16x16x32_bf16 v[66:69], v[142:145], v[188:191], v[66:69]
	v_mfma_f32_16x16x32_bf16 v[62:65], v[164:167], v[188:191], v[62:65]
	v_mfma_f32_16x16x32_bf16 v[50:53], v[142:145], v[196:199], v[50:53]
	v_mfma_f32_16x16x32_bf16 v[46:49], v[164:167], v[196:199], v[46:49]
	v_mfma_f32_16x16x32_bf16 v[34:37], v[142:145], v[204:207], v[34:37]
	v_mfma_f32_16x16x32_bf16 v[30:33], v[164:167], v[204:207], v[30:33]
	v_mfma_f32_16x16x32_bf16 v[18:21], v[142:145], v[234:237], v[18:21]
	v_mfma_f32_16x16x32_bf16 v[14:17], v[164:167], v[234:237], v[14:17]
	v_mfma_f32_16x16x32_bf16 v[66:69], v[146:149], v[192:195], v[66:69]
	v_mfma_f32_16x16x32_bf16 v[62:65], v[168:171], v[192:195], v[62:65]
	v_mfma_f32_16x16x32_bf16 v[50:53], v[146:149], v[200:203], v[50:53]
	v_mfma_f32_16x16x32_bf16 v[46:49], v[168:171], v[200:203], v[46:49]
	v_mfma_f32_16x16x32_bf16 v[34:37], v[146:149], v[230:233], v[34:37]
	v_mfma_f32_16x16x32_bf16 v[30:33], v[168:171], v[230:233], v[30:33]
	v_mfma_f32_16x16x32_bf16 v[18:21], v[146:149], v[238:241], v[18:21]
	v_mfma_f32_16x16x32_bf16 v[14:17], v[168:171], v[238:241], v[14:17]
	v_mfma_f32_16x16x32_bf16 v[58:61], v[172:175], v[188:191], v[58:61]
	v_mfma_f32_16x16x32_bf16 v[54:57], v[180:183], v[188:191], v[54:57]
	v_mfma_f32_16x16x32_bf16 v[42:45], v[172:175], v[196:199], v[42:45]
	v_mfma_f32_16x16x32_bf16 v[38:41], v[180:183], v[196:199], v[38:41]
	v_mfma_f32_16x16x32_bf16 v[26:29], v[172:175], v[204:207], v[26:29]
	v_mfma_f32_16x16x32_bf16 v[22:25], v[180:183], v[204:207], v[22:25]
	v_mfma_f32_16x16x32_bf16 v[10:13], v[172:175], v[234:237], v[10:13]
	v_mfma_f32_16x16x32_bf16 v[6:9], v[180:183], v[234:237], v[6:9]
	v_mfma_f32_16x16x32_bf16 v[58:61], v[176:179], v[192:195], v[58:61]
	v_mfma_f32_16x16x32_bf16 v[54:57], v[184:187], v[192:195], v[54:57]
	v_mfma_f32_16x16x32_bf16 v[42:45], v[176:179], v[200:203], v[42:45]
	v_mfma_f32_16x16x32_bf16 v[38:41], v[184:187], v[200:203], v[38:41]
	v_mfma_f32_16x16x32_bf16 v[26:29], v[176:179], v[230:233], v[26:29]
	v_mfma_f32_16x16x32_bf16 v[22:25], v[184:187], v[230:233], v[22:25]
	v_mfma_f32_16x16x32_bf16 v[10:13], v[176:179], v[238:241], v[10:13]
	v_mfma_f32_16x16x32_bf16 v[6:9], v[184:187], v[238:241], v[6:9]
	s_setprio 0
	s_barrier
; #define PG8_STAGE(bufoff, gbase, voff) do { _Pragma("unroll") for (int _i = 0; _i < 2; ++_i) \
;         __builtin_amdgcn_global_load_lds((const unsigned*)((const char*)(gbase) + (voff)[_i]), (PG8_LAS unsigned*)(lds + (bufoff) + ldsw + _i * 8192), 16, 0, 0); } while (0)
; #define PG8_LDA(dst, b, h) do { _Pragma("unroll") for (int m = 0; m < 4; ++m) _Pragma("unroll") for (int k = 0; k < 2; ++k) dst[m][k] = *(const PG8_LAS bf16x8*)(lds + PG8_SA(b, h) + aoff + m * 2048 + k * 1024); } while (0)
; #define PG8_LDB(dst, b, h) do { _Pragma("unroll") for (int n = 0; n < 2; ++n) _Pragma("unroll") for (int k = 0; k < 2; ++k) dst[n][k] = *(const PG8_LAS bf16x8*)(lds + PG8_SB(b, h) + boff + n * 2048 + k * 1024); } while (0)
; #define PG8_MMA(ai, bj, At, Bt) do { __builtin_amdgcn_s_setprio(1); _Pragma("unroll") for (int m = 0; m < 4; ++m) _Pragma("unroll") for (int n = 0; n < 2; ++n) _Pragma("unroll") for (int k = 0; k < 2; ++k) \
;         acc[ai][bj][m][n] = __builtin_amdgcn_mfma_f32_16x16x32_bf16(Bt[n][k], At[m][k], acc[ai][bj][m][n], 0, 0, 0); __builtin_amdgcn_s_setprio(0); } while (0)
; #define PG8_WAIT_V(n) asm volatile("s_waitcnt vmcnt(" #n ")" ::: "memory")
; #define PG8_WAIT_L(n) asm volatile("s_waitcnt lgkmcnt(" #n ")" ::: "memory")
; #define PG8_BAR __builtin_amdgcn_s_barrier()
; #define PG8_SCHED __builtin_amdgcn_sched_barrier(0)
; template <class Epi, class Sched, bool ALIGN_EPI = false, bool SP2 = false>
; __device__ __forceinline__ void gemm_phase(PG8_LAS unsigned char* lds, const Gemm g, const Sched& S, const Epi& E) {
;     ...
;             PG8_LDB(B0, 1, 0); PG8_LDB(B1, 1, 1); PG8_SCHED; PG8_LDA(At, 1, 0); PG8_STAGE(PG8_SA(0, 1), a2 + hstep, voffA);
;             PG8_WAIT_V(8); PG8_WAIT_L(0); PG8_BAR; PG8_MMA(0, 0, At, B0); PG8_MMA(0, 1, At, B1); PG8_BAR; PG8_SCHED;
;             PG8_LDA(At, 1, 1); PG8_STAGE(PG8_SB(1, 0), b3, voffB); PG8_STAGE(PG8_SB(1, 1), b3 + hstep, voffB); PG8_STAGE(PG8_SA(1, 0), a3, voffA);
;             PG8_WAIT_V(8); PG8_WAIT_L(0); PG8_BAR; PG8_MMA(1, 0, At, B0); PG8_MMA(1, 1, At, B1); PG8_BAR; PG8_SCHED;
	s_add_i32 s67, 0, 0x18000
	v_add_u32_e32 v160, s67, v152
	s_add_i32 s69, 0, 0x1c000
	ds_read_b128 v[142:145], v160
	ds_read_b128 v[146:149], v160 offset:1024
	ds_read_b128 v[164:167], v160 offset:2048
	ds_read_b128 v[168:171], v160 offset:3072
	v_add_u32_e32 v160, s69, v152
	ds_read_b128 v[172:175], v160
	ds_read_b128 v[176:179], v160 offset:1024
	ds_read_b128 v[180:183], v160 offset:2048
	ds_read_b128 v[184:187], v160 offset:3072
	s_add_u32 s26, s26, 0x80000
	s_addc_u32 s27, s27, 0
	s_mov_b32 m0, s43
	ds_read_b128 v[188:191], v163 offset:32768
	ds_read_b128 v[192:195], v163 offset:33792
	ds_read_b128 v[196:199], v163 offset:34816
	ds_read_b128 v[200:203], v163 offset:35840
	ds_read_b128 v[204:207], v163 offset:36864
	ds_read_b128 v[230:233], v163 offset:37888
	ds_read_b128 v[234:237], v163 offset:38912
	ds_read_b128 v[238:241], v163 offset:39936
	global_load_lds_dwordx4 v136, s[26:27]
	s_mov_b32 m0, s44
	s_nop 0
	global_load_lds_dwordx4 v134, s[26:27]
	s_waitcnt vmcnt(8)
	s_waitcnt lgkmcnt(0)
	s_barrier
	s_setprio 1
	s_waitcnt lgkmcnt(0)
	v_mfma_f32_16x16x32_bf16 v[130:133], v[142:145], v[188:191], v[130:133]
	v_mfma_f32_16x16x32_bf16 v[126:129], v[164:167], v[188:191], v[126:129]
	v_mfma_f32_16x16x32_bf16 v[114:117], v[142:145], v[196:199], v[114:117]
	v_mfma_f32_16x16x32_bf16 v[110:113], v[164:167], v[196:199], v[110:113]
	v_mfma_f32_16x16x32_bf16 v[98:101], v[142:145], v[204:207], v[98:101]
	v_mfma_f32_16x16x32_bf16 v[94:97], v[164:167], v[204:207], v[94:97]
	v_mfma_f32_16x16x32_bf16 v[82:85], v[142:145], v[234:237], v[82:85]
	v_mfma_f32_16x16x32_bf16 v[78:81], v[164:167], v[234:237], v[78:81]
	v_mfma_f32_16x16x32_bf16 v[130:133], v[146:149], v[192:195], v[130:133]
	v_mfma_f32_16x16x32_bf16 v[126:129], v[168:171], v[192:195], v[126:129]
	v_mfma_f32_16x16x32_bf16 v[114:117], v[146:149], v[200:203], v[114:117]
	v_mfma_f32_16x16x32_bf16 v[110:113], v[168:171], v[200:203], v[110:113]
	v_mfma_f32_16x16x32_bf16 v[98:101], v[146:149], v[230:233], v[98:101]
	v_mfma_f32_16x16x32_bf16 v[94:97], v[168:171], v[230:233], v[94:97]
	v_mfma_f32_16x16x32_bf16 v[82:85], v[146:149], v[238:241], v[82:85]
	v_mfma_f32_16x16x32_bf16 v[78:81], v[168:171], v[238:241], v[78:81]
	v_mfma_f32_16x16x32_bf16 v[122:125], v[172:175], v[188:191], v[122:125]
	v_mfma_f32_16x16x32_bf16 v[118:121], v[180:183], v[188:191], v[118:121]
	v_mfma_f32_16x16x32_bf16 v[106:109], v[172:175], v[196:199], v[106:109]
	v_mfma_f32_16x16x32_bf16 v[102:105], v[180:183], v[196:199], v[102:105]
	v_mfma_f32_16x16x32_bf16 v[90:93], v[172:175], v[204:207], v[90:93]
	v_mfma_f32_16x16x32_bf16 v[86:89], v[180:183], v[204:207], v[86:89]
	v_mfma_f32_16x16x32_bf16 v[74:77], v[172:175], v[234:237], v[74:77]
	v_mfma_f32_16x16x32_bf16 v[70:73], v[180:183], v[234:237], v[70:73]
	v_mfma_f32_16x16x32_bf16 v[122:125], v[176:179], v[192:195], v[122:125]
	v_mfma_f32_16x16x32_bf16 v[118:121], v[184:187], v[192:195], v[118:121]
	v_mfma_f32_16x16x32_bf16 v[106:109], v[176:179], v[200:203], v[106:109]
	v_mfma_f32_16x16x32_bf16 v[102:105], v[184:187], v[200:203], v[102:105]
	v_mfma_f32_16x16x32_bf16 v[90:93], v[176:179], v[230:233], v[90:93]
	v_mfma_f32_16x16x32_bf16 v[86:89], v[184:187], v[230:233], v[86:89]
	v_mfma_f32_16x16x32_bf16 v[74:77], v[176:179], v[238:241], v[74:77]
	v_mfma_f32_16x16x32_bf16 v[70:73], v[184:187], v[238:241], v[70:73]
	s_setprio 0
	s_barrier
	s_add_u32 vcc_lo, s24, s2
	s_addc_u32 vcc_hi, s25, s3
	s_add_i32 s26, s67, s30
	s_mov_b32 m0, s26
	ds_read_b128 v[188:191], v163 offset:49152
	ds_read_b128 v[192:195], v163 offset:50176
	ds_read_b128 v[196:199], v163 offset:51200
	ds_read_b128 v[200:203], v163 offset:52224
	ds_read_b128 v[204:207], v163 offset:53248
	ds_read_b128 v[230:233], v163 offset:54272
	ds_read_b128 v[234:237], v163 offset:55296
	ds_read_b128 v[238:241], v163 offset:56320
	global_load_lds_dwordx4 v2, vcc
	s_add_i32 m0, s26, 0x2000
	s_add_u32 s24, s24, 0x80080
	s_addc_u32 s25, s25, 0
	s_add_i32 s26, s69, s30
	global_load_lds_dwordx4 v0, vcc
	s_mov_b32 m0, s26
	s_nop 0
	global_load_lds_dwordx4 v2, s[24:25]
	s_add_i32 m0, s26, 0x2000
	s_nop 0
	global_load_lds_dwordx4 v0, s[24:25]
	v_lshl_add_u64 v[158:159], v[244:245], 0, s[2:3]
	s_mov_b32 m0, s45
	s_nop 0
	global_load_lds_dwordx4 v[158:159], off
	v_lshl_add_u64 v[158:159], v[246:247], 0, s[2:3]
	s_mov_b32 m0, s46
	s_nop 0
	global_load_lds_dwordx4 v[158:159], off
	s_waitcnt vmcnt(8)
	s_waitcnt lgkmcnt(0)
	s_barrier
	s_setprio 1
	s_waitcnt lgkmcnt(0)
	v_mfma_f32_16x16x32_bf16 v[66:69], v[142:145], v[188:191], v[66:69]
	v_mfma_f32_16x16x32_bf16 v[62:65], v[164:167], v[188:191], v[62:65]
	v_mfma_f32_16x16x32_bf16 v[50:53], v[142:145], v[196:199], v[50:53]
	v_mfma_f32_16x16x32_bf16 v[46:49], v[164:167], v[196:199], v[46:49]
	v_mfma_f32_16x16x32_bf16 v[34:37], v[142:145], v[204:207], v[34:37]
	v_mfma_f32_16x16x32_bf16 v[30:33], v[164:167], v[204:207], v[30:33]
	v_mfma_f32_16x16x32_bf16 v[18:21], v[142:145], v[234:237], v[18:21]
	v_mfma_f32_16x16x32_bf16 v[14:17], v[164:167], v[234:237], v[14:17]
	v_mfma_f32_16x16x32_bf16 v[66:69], v[146:149], v[192:195], v[66:69]
	v_mfma_f32_16x16x32_bf16 v[62:65], v[168:171], v[192:195], v[62:65]
	v_mfma_f32_16x16x32_bf16 v[50:53], v[146:149], v[200:203], v[50:53]
	v_mfma_f32_16x16x32_bf16 v[46:49], v[168:171], v[200:203], v[46:49]
	v_mfma_f32_16x16x32_bf16 v[34:37], v[146:149], v[230:233], v[34:37]
	v_mfma_f32_16x16x32_bf16 v[30:33], v[168:171], v[230:233], v[30:33]
	v_mfma_f32_16x16x32_bf16 v[18:21], v[146:149], v[238:241], v[18:21]
	v_mfma_f32_16x16x32_bf16 v[14:17], v[168:171], v[238:241], v[14:17]
	v_mfma_f32_16x16x32_bf16 v[58:61], v[172:175], v[188:191], v[58:61]
	v_mfma_f32_16x16x32_bf16 v[54:57], v[180:183], v[188:191], v[54:57]
	v_mfma_f32_16x16x32_bf16 v[42:45], v[172:175], v[196:199], v[42:45]
	v_mfma_f32_16x16x32_bf16 v[38:41], v[180:183], v[196:199], v[38:41]
	v_mfma_f32_16x16x32_bf16 v[26:29], v[172:175], v[204:207], v[26:29]
	v_mfma_f32_16x16x32_bf16 v[22:25], v[180:183], v[204:207], v[22:25]
	v_mfma_f32_16x16x32_bf16 v[10:13], v[172:175], v[234:237], v[10:13]
	v_mfma_f32_16x16x32_bf16 v[6:9], v[180:183], v[234:237], v[6:9]
	v_mfma_f32_16x16x32_bf16 v[58:61], v[176:179], v[192:195], v[58:61]
	v_mfma_f32_16x16x32_bf16 v[54:57], v[184:187], v[192:195], v[54:57]
	v_mfma_f32_16x16x32_bf16 v[42:45], v[176:179], v[200:203], v[42:45]
	v_mfma_f32_16x16x32_bf16 v[38:41], v[184:187], v[200:203], v[38:41]
	v_mfma_f32_16x16x32_bf16 v[26:29], v[176:179], v[230:233], v[26:29]
	v_mfma_f32_16x16x32_bf16 v[22:25], v[184:187], v[230:233], v[22:25]
	v_mfma_f32_16x16x32_bf16 v[10:13], v[176:179], v[238:241], v[10:13]
	v_mfma_f32_16x16x32_bf16 v[6:9], v[184:187], v[238:241], v[6:9]
	s_setprio 0
	s_barrier
	s_add_i32 s66, s66, 2
	s_add_u32 s52, s52, 0x100
	s_addc_u32 s53, s53, 0
	s_add_u32 s22, s22, 0x100
	s_addc_u32 s23, s23, 0
	s_cmp_gt_u32 s66, 29
	s_cbranch_scc0 .LBB0_1016
	s_and_b64 vcc, exec, s[12:13]
	s_cbranch_vccz .LBB0_1019
	s_barrier

; #define PG8_STAGE(bufoff, gbase, voff) do { _Pragma("unroll") for (int _i = 0; _i < 2; ++_i) \
;         __builtin_amdgcn_global_load_lds((const unsigned*)((const char*)(gbase) + (voff)[_i]), (PG8_LAS unsigned*)(lds + (bufoff) + ldsw + _i * 8192), 16, 0, 0); } while (0)
; #define PG8_LDA(dst, b, h) do { _Pragma("unroll") for (int m = 0; m < 4; ++m) _Pragma("unroll") for (int k = 0; k < 2; ++k) dst[m][k] = *(const PG8_LAS bf16x8*)(lds + PG8_SA(b, h) + aoff + m * 2048 + k * 1024); } while (0)
; #define PG8_LDB(dst, b, h) do { _Pragma("unroll") for (int n = 0; n < 2; ++n) _Pragma("unroll") for (int k = 0; k < 2; ++k) dst[n][k] = *(const PG8_LAS bf16x8*)(lds + PG8_SB(b, h) + boff + n * 2048 + k * 1024); } while (0)
; #define PG8_MMA(ai, bj, At, Bt) do { __builtin_amdgcn_s_setprio(1); _Pragma("unroll") for (int m = 0; m < 4; ++m) _Pragma("unroll") for (int n = 0; n < 2; ++n) _Pragma("unroll") for (int k = 0; k < 2; ++k) \
;         acc[ai][bj][m][n] = __builtin_amdgcn_mfma_f32_16x16x32_bf16(Bt[n][k], At[m][k], acc[ai][bj][m][n], 0, 0, 0); __builtin_amdgcn_s_setprio(0); } while (0)
; #define PG8_WAIT_V(n) asm volatile("s_waitcnt vmcnt(" #n ")" ::: "memory")
; #define PG8_WAIT_L(n) asm volatile("s_waitcnt lgkmcnt(" #n ")" ::: "memory")
; template <class Epi, class Sched, bool ALIGN_EPI = false, bool SP2 = false>
; __device__ __forceinline__ void gemm_phase(PG8_LAS unsigned char* lds, const Gemm g, const Sched& S, const Epi& E) {
;     ...
;             const bool last = (t == nt - 2);
;             const char* a1 = cA + (size_t)(t + 1) * kstep;
;             const char* a2 = last ? nA : cA + (size_t)(t + 2) * kstep; const char* b2 = last ? nB : cB + (size_t)(t + 2) * kstep;
;             const char* a3 = a2 + kstep; const char* b3 = b2 + kstep;
;             if (last && has_next) S.a_ready(nxt);
;             if constexpr (SP2) {
;             PG8_LDB(B0, 0, 0); PG8_LDB(B1, 0, 1); PG8_SCHED; PG8_LDA(At, 0, 0); PG8_STAGE(PG8_SA(1, 1), a1 + hstep, voffA);
;             PG8_WAIT_V(8); PG8_WAIT_L(0); PG8_BAR; PG8_MMA(0, 0, At, B0); PG8_MMA(0, 1, At, B1); PG8_BAR; PG8_SCHED;
;             PG8_LDA(At, 0, 1); PG8_STAGE(PG8_SB(0, 0), b2, voffB); PG8_STAGE(PG8_SB(0, 1), b2 + hstep, voffB); PG8_STAGE(PG8_SA(0, 0), a2, voffA);
;             PG8_WAIT_V(8); PG8_WAIT_L(0); PG8_BAR; PG8_MMA(1, 0, At, B0); PG8_MMA(1, 1, At, B1); PG8_BAR; PG8_SCHED;
.LBB0_1630:
	s_add_u32 s26, s24, 0x100
	s_addc_u32 s27, s25, 0
	s_add_i32 s78, 0, 0x10000
	s_cmp_eq_u32 s71, 28
	s_cselect_b32 s31, s19, s27
	s_cselect_b32 s30, s66, s26
	s_cselect_b32 s29, s17, s70
	s_cselect_b32 s28, s67, s69
	s_add_i32 s79, 0, 0x14000
	v_add_u32_e32 v98, s78, v152
	v_add_u32_e32 v158, s79, v152
	ds_read_b128 v[78:81], v98
	ds_read_b128 v[90:93], v98 offset:1024
	ds_read_b128 v[94:97], v98 offset:2048
	ds_read_b128 v[98:101], v98 offset:3072
	ds_read_b128 v[166:169], v158
	ds_read_b128 v[174:177], v158 offset:1024
	ds_read_b128 v[178:181], v158 offset:2048
	ds_read_b128 v[182:185], v158 offset:3072
	s_add_i32 m0, s45, 0xc000
	ds_read_b128 v[186:189], v173
	ds_read_b128 v[190:193], v173 offset:1024
	ds_read_b128 v[194:197], v173 offset:2048
	ds_read_b128 v[198:201], v173 offset:3072
	ds_read_b128 v[202:205], v173 offset:4096
	ds_read_b128 v[230:233], v173 offset:5120
	ds_read_b128 v[234:237], v173 offset:6144
	ds_read_b128 v[238:241], v173 offset:7168
	global_load_lds_dwordx4 v164, s[24:25]
	s_add_i32 m0, s45, 0xe000
	s_nop 0
	global_load_lds_dwordx4 v162, s[24:25]
	s_waitcnt vmcnt(8)
	s_waitcnt lgkmcnt(0)
	s_barrier
	s_setprio 1
	s_waitcnt lgkmcnt(0)
	v_mfma_f32_16x16x32_bf16 v[146:149], v[78:81], v[186:189], v[146:149]
	v_mfma_f32_16x16x32_bf16 v[142:145], v[94:97], v[186:189], v[142:145]
	v_mfma_f32_16x16x32_bf16 v[130:133], v[78:81], v[194:197], v[130:133]
	v_mfma_f32_16x16x32_bf16 v[126:129], v[94:97], v[194:197], v[126:129]
	v_mfma_f32_16x16x32_bf16 v[114:117], v[78:81], v[202:205], v[114:117]
	v_mfma_f32_16x16x32_bf16 v[110:113], v[94:97], v[202:205], v[110:113]
	v_mfma_f32_16x16x32_bf16 v[86:89], v[78:81], v[234:237], v[86:89]
	v_mfma_f32_16x16x32_bf16 v[82:85], v[94:97], v[234:237], v[82:85]
	v_mfma_f32_16x16x32_bf16 v[146:149], v[90:93], v[190:193], v[146:149]
	v_mfma_f32_16x16x32_bf16 v[142:145], v[98:101], v[190:193], v[142:145]
	v_mfma_f32_16x16x32_bf16 v[130:133], v[90:93], v[198:201], v[130:133]
	v_mfma_f32_16x16x32_bf16 v[126:129], v[98:101], v[198:201], v[126:129]
	v_mfma_f32_16x16x32_bf16 v[114:117], v[90:93], v[230:233], v[114:117]
	v_mfma_f32_16x16x32_bf16 v[110:113], v[98:101], v[230:233], v[110:113]
	v_mfma_f32_16x16x32_bf16 v[86:89], v[90:93], v[238:241], v[86:89]
	v_mfma_f32_16x16x32_bf16 v[82:85], v[98:101], v[238:241], v[82:85]
	v_mfma_f32_16x16x32_bf16 v[138:141], v[166:169], v[186:189], v[138:141]
	v_mfma_f32_16x16x32_bf16 v[134:137], v[178:181], v[186:189], v[134:137]
	v_mfma_f32_16x16x32_bf16 v[122:125], v[166:169], v[194:197], v[122:125]
	v_mfma_f32_16x16x32_bf16 v[118:121], v[178:181], v[194:197], v[118:121]
	v_mfma_f32_16x16x32_bf16 v[106:109], v[166:169], v[202:205], v[106:109]
	v_mfma_f32_16x16x32_bf16 v[102:105], v[178:181], v[202:205], v[102:105]
	v_mfma_f32_16x16x32_bf16 v[74:77], v[166:169], v[234:237], v[74:77]
	v_mfma_f32_16x16x32_bf16 v[70:73], v[178:181], v[234:237], v[70:73]
	v_mfma_f32_16x16x32_bf16 v[138:141], v[174:177], v[190:193], v[138:141]
	v_mfma_f32_16x16x32_bf16 v[134:137], v[182:185], v[190:193], v[134:137]
	v_mfma_f32_16x16x32_bf16 v[122:125], v[174:177], v[198:201], v[122:125]
	v_mfma_f32_16x16x32_bf16 v[118:121], v[182:185], v[198:201], v[118:121]
	v_mfma_f32_16x16x32_bf16 v[106:109], v[174:177], v[230:233], v[106:109]
	v_mfma_f32_16x16x32_bf16 v[102:105], v[182:185], v[230:233], v[102:105]
	v_mfma_f32_16x16x32_bf16 v[74:77], v[174:177], v[238:241], v[74:77]
	v_mfma_f32_16x16x32_bf16 v[70:73], v[182:185], v[238:241], v[70:73]
	s_setprio 0
	s_barrier
	s_add_i32 s24, s78, s44
	s_mov_b32 m0, s24
	ds_read_b128 v[186:189], v173 offset:16384
	ds_read_b128 v[190:193], v173 offset:17408
	ds_read_b128 v[194:197], v173 offset:18432
	ds_read_b128 v[198:201], v173 offset:19456
	ds_read_b128 v[202:205], v173 offset:20480
	ds_read_b128 v[230:233], v173 offset:21504
	ds_read_b128 v[234:237], v173 offset:22528
	ds_read_b128 v[238:241], v173 offset:23552
	global_load_lds_dwordx4 v2, s[28:29]
	s_add_i32 m0, s24, 0x2000
	s_add_u32 s24, s28, 0x80000
	s_addc_u32 s25, s29, 0
	s_add_i32 s78, s79, s44
	global_load_lds_dwordx4 v0, s[28:29]
	s_mov_b32 m0, s78
	s_nop 0
	global_load_lds_dwordx4 v2, s[24:25]
	s_add_i32 m0, s78, 0x2000
	s_nop 0
	global_load_lds_dwordx4 v0, s[24:25]
	s_mov_b32 m0, s45
	s_nop 0
	global_load_lds_dwordx4 v2, s[30:31]
	s_mov_b32 m0, s46
	s_nop 0
	global_load_lds_dwordx4 v0, s[30:31]
	s_waitcnt vmcnt(8)
	s_waitcnt lgkmcnt(0)
	s_barrier
	s_setprio 1
	s_waitcnt lgkmcnt(0)
	v_mfma_f32_16x16x32_bf16 v[66:69], v[78:81], v[186:189], v[66:69]
	v_mfma_f32_16x16x32_bf16 v[62:65], v[94:97], v[186:189], v[62:65]
	v_mfma_f32_16x16x32_bf16 v[50:53], v[78:81], v[194:197], v[50:53]
	v_mfma_f32_16x16x32_bf16 v[46:49], v[94:97], v[194:197], v[46:49]
	v_mfma_f32_16x16x32_bf16 v[34:37], v[78:81], v[202:205], v[34:37]
	v_mfma_f32_16x16x32_bf16 v[30:33], v[94:97], v[202:205], v[30:33]
	v_mfma_f32_16x16x32_bf16 v[18:21], v[78:81], v[234:237], v[18:21]
	v_mfma_f32_16x16x32_bf16 v[14:17], v[94:97], v[234:237], v[14:17]
	v_mfma_f32_16x16x32_bf16 v[66:69], v[90:93], v[190:193], v[66:69]
	v_mfma_f32_16x16x32_bf16 v[62:65], v[98:101], v[190:193], v[62:65]
	v_mfma_f32_16x16x32_bf16 v[50:53], v[90:93], v[198:201], v[50:53]
	v_mfma_f32_16x16x32_bf16 v[46:49], v[98:101], v[198:201], v[46:49]
	v_mfma_f32_16x16x32_bf16 v[34:37], v[90:93], v[230:233], v[34:37]
	v_mfma_f32_16x16x32_bf16 v[30:33], v[98:101], v[230:233], v[30:33]
	v_mfma_f32_16x16x32_bf16 v[18:21], v[90:93], v[238:241], v[18:21]
	v_mfma_f32_16x16x32_bf16 v[14:17], v[98:101], v[238:241], v[14:17]
	v_mfma_f32_16x16x32_bf16 v[58:61], v[166:169], v[186:189], v[58:61]
	v_mfma_f32_16x16x32_bf16 v[54:57], v[178:181], v[186:189], v[54:57]
	v_mfma_f32_16x16x32_bf16 v[42:45], v[166:169], v[194:197], v[42:45]
	v_mfma_f32_16x16x32_bf16 v[38:41], v[178:181], v[194:197], v[38:41]
	v_mfma_f32_16x16x32_bf16 v[26:29], v[166:169], v[202:205], v[26:29]
	v_mfma_f32_16x16x32_bf16 v[22:25], v[178:181], v[202:205], v[22:25]
	v_mfma_f32_16x16x32_bf16 v[10:13], v[166:169], v[234:237], v[10:13]
	v_mfma_f32_16x16x32_bf16 v[6:9], v[178:181], v[234:237], v[6:9]
	v_mfma_f32_16x16x32_bf16 v[58:61], v[174:177], v[190:193], v[58:61]
	v_mfma_f32_16x16x32_bf16 v[54:57], v[182:185], v[190:193], v[54:57]
	v_mfma_f32_16x16x32_bf16 v[42:45], v[174:177], v[198:201], v[42:45]
	v_mfma_f32_16x16x32_bf16 v[38:41], v[182:185], v[198:201], v[38:41]
	v_mfma_f32_16x16x32_bf16 v[26:29], v[174:177], v[230:233], v[26:29]
	v_mfma_f32_16x16x32_bf16 v[22:25], v[182:185], v[230:233], v[22:25]
	v_mfma_f32_16x16x32_bf16 v[10:13], v[174:177], v[238:241], v[10:13]
	v_mfma_f32_16x16x32_bf16 v[6:9], v[182:185], v[238:241], v[6:9]
	s_setprio 0
	s_barrier
; #define PG8_STAGE(bufoff, gbase, voff) do { _Pragma("unroll") for (int _i = 0; _i < 2; ++_i) \
;         __builtin_amdgcn_global_load_lds((const unsigned*)((const char*)(gbase) + (voff)[_i]), (PG8_LAS unsigned*)(lds + (bufoff) + ldsw + _i * 8192), 16, 0, 0); } while (0)
; #define PG8_LDA(dst, b, h) do { _Pragma("unroll") for (int m = 0; m < 4; ++m) _Pragma("unroll") for (int k = 0; k < 2; ++k) dst[m][k] = *(const PG8_LAS bf16x8*)(lds + PG8_SA(b, h) + aoff + m * 2048 + k * 1024); } while (0)
; #define PG8_LDB(dst, b, h) do { _Pragma("unroll") for (int n = 0; n < 2; ++n) _Pragma("unroll") for (int k = 0; k < 2; ++k) dst[n][k] = *(const PG8_LAS bf16x8*)(lds + PG8_SB(b, h) + boff + n * 2048 + k * 1024); } while (0)
; #define PG8_MMA(ai, bj, At, Bt) do { __builtin_amdgcn_s_setprio(1); _Pragma("unroll") for (int m = 0; m < 4; ++m) _Pragma("unroll") for (int n = 0; n < 2; ++n) _Pragma("unroll") for (int k = 0; k < 2; ++k) \
;         acc[ai][bj][m][n] = __builtin_amdgcn_mfma_f32_16x16x32_bf16(Bt[n][k], At[m][k], acc[ai][bj][m][n], 0, 0, 0); __builtin_amdgcn_s_setprio(0); } while (0)
; #define PG8_WAIT_V(n) asm volatile("s_waitcnt vmcnt(" #n ")" ::: "memory")
; #define PG8_WAIT_L(n) asm volatile("s_waitcnt lgkmcnt(" #n ")" ::: "memory")
; #define PG8_BAR __builtin_amdgcn_s_barrier()
; #define PG8_SCHED __builtin_amdgcn_sched_barrier(0)
; template <class Epi, class Sched, bool ALIGN_EPI = false, bool SP2 = false>
; __device__ __forceinline__ void gemm_phase(PG8_LAS unsigned char* lds, const Gemm g, const Sched& S, const Epi& E) {
;     ...
;             PG8_LDB(B0, 1, 0); PG8_LDB(B1, 1, 1); PG8_SCHED; PG8_LDA(At, 1, 0); PG8_STAGE(PG8_SA(0, 1), a2 + hstep, voffA);
;             PG8_WAIT_V(8); PG8_WAIT_L(0); PG8_BAR; PG8_MMA(0, 0, At, B0); PG8_MMA(0, 1, At, B1); PG8_BAR; PG8_SCHED;
;             PG8_LDA(At, 1, 1); PG8_STAGE(PG8_SB(1, 0), b3, voffB); PG8_STAGE(PG8_SB(1, 1), b3 + hstep, voffB); PG8_STAGE(PG8_SA(1, 0), a3, voffA);
;             PG8_WAIT_V(8); PG8_WAIT_L(0); PG8_BAR; PG8_MMA(1, 0, At, B0); PG8_MMA(1, 1, At, B1); PG8_BAR; PG8_SCHED;
	s_add_i32 s78, 0, 0x18000
	s_add_i32 s79, 0, 0x1c000
	v_add_u32_e32 v98, s78, v152
	v_add_u32_e32 v160, s79, v152
	ds_read_b128 v[78:81], v98
	ds_read_b128 v[90:93], v98 offset:1024
	ds_read_b128 v[94:97], v98 offset:2048
	ds_read_b128 v[98:101], v98 offset:3072
	ds_read_b128 v[166:169], v160
	ds_read_b128 v[174:177], v160 offset:1024
	ds_read_b128 v[178:181], v160 offset:2048
	ds_read_b128 v[182:185], v160 offset:3072
	s_add_u32 s24, s30, 0x80000
	s_addc_u32 s25, s31, 0
	s_mov_b32 m0, s47
	ds_read_b128 v[186:189], v173 offset:32768
	ds_read_b128 v[190:193], v173 offset:33792
	ds_read_b128 v[194:197], v173 offset:34816
	ds_read_b128 v[198:201], v173 offset:35840
	ds_read_b128 v[202:205], v173 offset:36864
	ds_read_b128 v[230:233], v173 offset:37888
	ds_read_b128 v[234:237], v173 offset:38912
	ds_read_b128 v[238:241], v173 offset:39936
	global_load_lds_dwordx4 v2, s[24:25]
	s_mov_b32 m0, s48
	s_nop 0
	global_load_lds_dwordx4 v0, s[24:25]
	s_waitcnt vmcnt(8)
	s_waitcnt lgkmcnt(0)
	s_barrier
	s_setprio 1
	s_waitcnt lgkmcnt(0)
	v_mfma_f32_16x16x32_bf16 v[146:149], v[78:81], v[186:189], v[146:149]
	v_mfma_f32_16x16x32_bf16 v[142:145], v[94:97], v[186:189], v[142:145]
	v_mfma_f32_16x16x32_bf16 v[130:133], v[78:81], v[194:197], v[130:133]
	v_mfma_f32_16x16x32_bf16 v[126:129], v[94:97], v[194:197], v[126:129]
	v_mfma_f32_16x16x32_bf16 v[114:117], v[78:81], v[202:205], v[114:117]
	v_mfma_f32_16x16x32_bf16 v[110:113], v[94:97], v[202:205], v[110:113]
	v_mfma_f32_16x16x32_bf16 v[86:89], v[78:81], v[234:237], v[86:89]
	v_mfma_f32_16x16x32_bf16 v[82:85], v[94:97], v[234:237], v[82:85]
	v_mfma_f32_16x16x32_bf16 v[146:149], v[90:93], v[190:193], v[146:149]
	v_mfma_f32_16x16x32_bf16 v[142:145], v[98:101], v[190:193], v[142:145]
	v_mfma_f32_16x16x32_bf16 v[130:133], v[90:93], v[198:201], v[130:133]
	v_mfma_f32_16x16x32_bf16 v[126:129], v[98:101], v[198:201], v[126:129]
	v_mfma_f32_16x16x32_bf16 v[114:117], v[90:93], v[230:233], v[114:117]
	v_mfma_f32_16x16x32_bf16 v[110:113], v[98:101], v[230:233], v[110:113]
	v_mfma_f32_16x16x32_bf16 v[86:89], v[90:93], v[238:241], v[86:89]
	v_mfma_f32_16x16x32_bf16 v[82:85], v[98:101], v[238:241], v[82:85]
	v_mfma_f32_16x16x32_bf16 v[138:141], v[166:169], v[186:189], v[138:141]
	v_mfma_f32_16x16x32_bf16 v[134:137], v[178:181], v[186:189], v[134:137]
	v_mfma_f32_16x16x32_bf16 v[122:125], v[166:169], v[194:197], v[122:125]
	v_mfma_f32_16x16x32_bf16 v[118:121], v[178:181], v[194:197], v[118:121]
	v_mfma_f32_16x16x32_bf16 v[106:109], v[166:169], v[202:205], v[106:109]
	v_mfma_f32_16x16x32_bf16 v[102:105], v[178:181], v[202:205], v[102:105]
	v_mfma_f32_16x16x32_bf16 v[74:77], v[166:169], v[234:237], v[74:77]
	v_mfma_f32_16x16x32_bf16 v[70:73], v[178:181], v[234:237], v[70:73]
	v_mfma_f32_16x16x32_bf16 v[138:141], v[174:177], v[190:193], v[138:141]
	v_mfma_f32_16x16x32_bf16 v[134:137], v[182:185], v[190:193], v[134:137]
	v_mfma_f32_16x16x32_bf16 v[122:125], v[174:177], v[198:201], v[122:125]
	v_mfma_f32_16x16x32_bf16 v[118:121], v[182:185], v[198:201], v[118:121]
	v_mfma_f32_16x16x32_bf16 v[106:109], v[174:177], v[230:233], v[106:109]
	v_mfma_f32_16x16x32_bf16 v[102:105], v[182:185], v[230:233], v[102:105]
	v_mfma_f32_16x16x32_bf16 v[74:77], v[174:177], v[238:241], v[74:77]
	v_mfma_f32_16x16x32_bf16 v[70:73], v[182:185], v[238:241], v[70:73]
	s_setprio 0
	s_barrier
	s_add_u32 vcc_lo, s28, s2
	s_addc_u32 vcc_hi, s29, s3
	s_add_i32 s24, s78, s44
	s_mov_b32 m0, s24
	ds_read_b128 v[186:189], v173 offset:49152
	ds_read_b128 v[190:193], v173 offset:50176
	ds_read_b128 v[194:197], v173 offset:51200
	ds_read_b128 v[198:201], v173 offset:52224
	ds_read_b128 v[202:205], v173 offset:53248
	ds_read_b128 v[230:233], v173 offset:54272
	ds_read_b128 v[234:237], v173 offset:55296
	ds_read_b128 v[238:241], v173 offset:56320
	global_load_lds_dwordx4 v2, vcc
	s_add_i32 m0, s24, 0x2000
	s_add_u32 s24, s28, 0x80080
	s_addc_u32 s25, s29, 0
	s_add_i32 s28, s79, s44
	global_load_lds_dwordx4 v0, vcc
	s_mov_b32 m0, s28
	s_nop 0
	global_load_lds_dwordx4 v2, s[24:25]
	s_add_i32 m0, s28, 0x2000
	s_nop 0
	global_load_lds_dwordx4 v0, s[24:25]
	s_add_u32 vcc_lo, s30, s2
	s_addc_u32 vcc_hi, s31, s3
	s_mov_b32 m0, s49
	s_nop 0
	global_load_lds_dwordx4 v2, vcc
	s_mov_b32 m0, s50
	s_nop 0
	global_load_lds_dwordx4 v0, vcc
	s_waitcnt vmcnt(8)
	s_waitcnt lgkmcnt(0)
	s_barrier
	s_setprio 1
	s_waitcnt lgkmcnt(0)
	v_mfma_f32_16x16x32_bf16 v[66:69], v[78:81], v[186:189], v[66:69]
	v_mfma_f32_16x16x32_bf16 v[62:65], v[94:97], v[186:189], v[62:65]
	v_mfma_f32_16x16x32_bf16 v[50:53], v[78:81], v[194:197], v[50:53]
	v_mfma_f32_16x16x32_bf16 v[46:49], v[94:97], v[194:197], v[46:49]
	v_mfma_f32_16x16x32_bf16 v[34:37], v[78:81], v[202:205], v[34:37]
	v_mfma_f32_16x16x32_bf16 v[30:33], v[94:97], v[202:205], v[30:33]
	v_mfma_f32_16x16x32_bf16 v[18:21], v[78:81], v[234:237], v[18:21]
	v_mfma_f32_16x16x32_bf16 v[14:17], v[94:97], v[234:237], v[14:17]
	v_mfma_f32_16x16x32_bf16 v[66:69], v[90:93], v[190:193], v[66:69]
	v_mfma_f32_16x16x32_bf16 v[62:65], v[98:101], v[190:193], v[62:65]
	v_mfma_f32_16x16x32_bf16 v[50:53], v[90:93], v[198:201], v[50:53]
	v_mfma_f32_16x16x32_bf16 v[46:49], v[98:101], v[198:201], v[46:49]
	v_mfma_f32_16x16x32_bf16 v[34:37], v[90:93], v[230:233], v[34:37]
	v_mfma_f32_16x16x32_bf16 v[30:33], v[98:101], v[230:233], v[30:33]
	v_mfma_f32_16x16x32_bf16 v[18:21], v[90:93], v[238:241], v[18:21]
	v_mfma_f32_16x16x32_bf16 v[14:17], v[98:101], v[238:241], v[14:17]
	v_mfma_f32_16x16x32_bf16 v[58:61], v[166:169], v[186:189], v[58:61]
	v_mfma_f32_16x16x32_bf16 v[54:57], v[178:181], v[186:189], v[54:57]
	v_mfma_f32_16x16x32_bf16 v[42:45], v[166:169], v[194:197], v[42:45]
	v_mfma_f32_16x16x32_bf16 v[38:41], v[178:181], v[194:197], v[38:41]
	v_mfma_f32_16x16x32_bf16 v[26:29], v[166:169], v[202:205], v[26:29]
	v_mfma_f32_16x16x32_bf16 v[22:25], v[178:181], v[202:205], v[22:25]
	v_mfma_f32_16x16x32_bf16 v[10:13], v[166:169], v[234:237], v[10:13]
	v_mfma_f32_16x16x32_bf16 v[6:9], v[178:181], v[234:237], v[6:9]
	v_mfma_f32_16x16x32_bf16 v[58:61], v[174:177], v[190:193], v[58:61]
	v_mfma_f32_16x16x32_bf16 v[54:57], v[182:185], v[190:193], v[54:57]
	v_mfma_f32_16x16x32_bf16 v[42:45], v[174:177], v[198:201], v[42:45]
	v_mfma_f32_16x16x32_bf16 v[38:41], v[182:185], v[198:201], v[38:41]
	v_mfma_f32_16x16x32_bf16 v[26:29], v[174:177], v[230:233], v[26:29]
	v_mfma_f32_16x16x32_bf16 v[22:25], v[182:185], v[230:233], v[22:25]
	v_mfma_f32_16x16x32_bf16 v[10:13], v[174:177], v[238:241], v[10:13]
	v_mfma_f32_16x16x32_bf16 v[6:9], v[182:185], v[238:241], v[6:9]
	s_setprio 0
	s_barrier
;     __device__ __forceinline__ void operator()(const f32x4 (&acc)[2][2][4][2], const Unit& u, int wr, int wc, int fr, int fq) const {
;         const int row0 = u.pm * BM + wr * 64 + fr; const int col0 = u.pn * BM + wc * 32 + 4 * fq;
;         f32x4 gv[2][2];
; #pragma unroll
;         for (int bj = 0; bj < 2; ++bj)
; #pragma unroll
;             for (int n = 0; n < 2; ++n) gv[bj][n] = xg ? *(const f32x4*)(gn + col0 + bj * HALF + n * 16) : (f32x4){0.f, 0.f, 0.f, 0.f};
; #pragma unroll
;         for (int ai = 0; ai < 2; ++ai)
; #pragma unroll
;             for (int m = 0; m < 4; ++m) { const size_t off = (size_t)(row0 + ai * HALF + m * 16) * ldc + col0; float ss = 0.f;
; #pragma unroll
;                 for (int bj = 0; bj < 2; ++bj)
; #pragma unroll
;                     for (int n = 0; n < 2; ++n) { const f32x4 bs = *(const f32x4*)(base + off + bj * HALF + n * 16); const f32x4 o = bs + acc[ai][bj][m][n] * scale;
;                         *(f32x4*)(out + off + bj * HALF + n * 16) = o;
;                         if (xg) { ss += (o[0] * o[0] + o[1] * o[1]) + (o[2] * o[2] + o[3] * o[3]); const f32x4 og = o * gv[bj][n];
;                             typedef unsigned u32x2v __attribute__((ext_vector_type(2))); u32x2v w; w.x = cvt_pk_bf16(og[0], og[1]); w.y = cvt_pk_bf16(og[2], og[3]); *(u32x2v*)(xg + off + bj * HALF + n * 16) = w; } }
;                 if (xg) { ss += __shfl_xor(ss, 16); ss += __shfl_xor(ss, 32); if (fq == 0) atomicAdd(rowss + row0 + ai * HALF + m * 16, (rowss_t)(ss * 16777216.0f)); } }
	s_add_i32 s71, s71, 2
	s_add_u32 s69, s69, 0x100
	s_addc_u32 s70, s70, 0
	s_cmp_gt_u32 s71, 29
	s_mov_b64 s[24:25], s[26:27]
	s_cbranch_scc0 .LBB0_1630
	v_lshl_add_u32 v170, s52, 8, v5
	v_lshl_or_b32 v168, s53, 8, v172
	v_ashrrev_i32_e32 v171, 31, v170
	v_ashrrev_i32_e32 v169, 31, v168
	v_readlane_b32 s72, v254, 12
	v_lshlrev_b64 v[158:159], 11, v[170:171]
	v_readlane_b32 s82, v254, 22
	v_readlane_b32 s83, v254, 23
	v_lshl_add_u64 v[166:167], v[158:159], 0, v[168:169]
	v_lshl_add_u64 v[158:159], v[166:167], 2, s[10:11]
	v_lshl_add_u64 v[78:79], v[168:169], 2, s[82:83]
	global_load_dwordx4 v[98:101], v[78:79], off
	global_load_dwordx4 v[94:97], v[78:79], off offset:64
	global_load_dwordx4 v[90:93], v[78:79], off offset:512
	s_nop 0
	global_load_dwordx4 v[78:81], v[78:79], off offset:576
	v_readlane_b32 s73, v254, 13
	global_load_dwordx4 v[174:177], v[158:159], off
	global_load_dwordx4 v[182:185], v[158:159], off offset:64
	global_load_dwordx4 v[186:189], v[158:159], off offset:512
	global_load_dwordx4 v[190:193], v[158:159], off offset:576
	v_readlane_b32 s74, v254, 14
	v_readlane_b32 s75, v254, 15
	v_readlane_b32 s76, v254, 16
	v_readlane_b32 s77, v254, 17
	v_readlane_b32 s78, v254, 18
	v_readlane_b32 s79, v254, 19
	v_readlane_b32 s80, v254, 20
	v_readlane_b32 s81, v254, 21
	v_readlane_b32 s84, v254, 24
	v_readlane_b32 s85, v254, 25
	v_readlane_b32 s86, v254, 26
	v_readlane_b32 s87, v254, 27
	s_waitcnt vmcnt(3) lgkmcnt(0)
	v_pk_add_f32 v[148:149], v[148:149], v[176:177]
	v_pk_add_f32 v[146:147], v[146:147], v[174:175]
	v_mul_f32_e32 v161, v149, v149
	v_mul_f32_e32 v160, v147, v147
	global_store_dwordx4 v[158:159], v[146:149], off
	v_fmac_f32_e32 v160, v146, v146
	v_fmac_f32_e32 v161, v148, v148
	v_pk_mul_f32 v[148:149], v[100:101], v[148:149]
	v_pk_mul_f32 v[146:147], v[98:99], v[146:147]
	v_lshl_add_u64 v[174:175], v[166:167], 1, s[12:13]
	v_cvt_pk_bf16_f32 v146, v146, v147
	v_cvt_pk_bf16_f32 v147, v148, v149
	global_store_dwordx2 v[174:175], v[146:147], off
	v_add_f32_e32 v160, v160, v161
	s_waitcnt vmcnt(4) lgkmcnt(0)
	v_pk_add_f32 v[144:145], v[144:145], v[184:185]
	v_pk_add_f32 v[142:143], v[142:143], v[182:183]
	v_mul_f32_e32 v147, v145, v145
	v_mul_f32_e32 v146, v143, v143
	global_store_dwordx4 v[158:159], v[142:145], off offset:64
	v_fmac_f32_e32 v146, v142, v142
	v_fmac_f32_e32 v147, v144, v144
	v_pk_mul_f32 v[144:145], v[96:97], v[144:145]
	v_pk_mul_f32 v[142:143], v[94:95], v[142:143]
	v_add_f32_e32 v146, v146, v147
	v_cvt_pk_bf16_f32 v142, v142, v143
	v_cvt_pk_bf16_f32 v143, v144, v145
	global_store_dwordx2 v[174:175], v[142:143], off offset:32
	v_add_f32_e32 v146, v160, v146
	s_waitcnt vmcnt(5) lgkmcnt(0)
	v_pk_add_f32 v[140:141], v[140:141], v[188:189]
	v_pk_add_f32 v[138:139], v[138:139], v[186:187]
	v_mul_f32_e32 v143, v141, v141
	v_mul_f32_e32 v142, v139, v139
	global_store_dwordx4 v[158:159], v[138:141], off offset:512
	v_fmac_f32_e32 v142, v138, v138
	v_fmac_f32_e32 v143, v140, v140
	v_pk_mul_f32 v[140:141], v[92:93], v[140:141]
	v_pk_mul_f32 v[138:139], v[90:91], v[138:139]
	v_add_f32_e32 v142, v142, v143
	v_cvt_pk_bf16_f32 v138, v138, v139
	v_cvt_pk_bf16_f32 v139, v140, v141
	global_store_dwordx2 v[174:175], v[138:139], off offset:256
	v_add_f32_e32 v142, v146, v142
	s_waitcnt vmcnt(6) lgkmcnt(0)
	v_pk_add_f32 v[136:137], v[136:137], v[192:193]
	v_pk_add_f32 v[134:135], v[134:135], v[190:191]
	global_store_dwordx4 v[158:159], v[134:137], off offset:576
	v_pk_mul_f32 v[140:141], v[78:79], v[134:135]
	v_pk_mul_f32 v[138:139], v[80:81], v[136:137]
	v_mul_f32_e32 v135, v135, v135
	v_fmac_f32_e32 v135, v134, v134
	v_mul_f32_e32 v134, v137, v137
	v_fmac_f32_e32 v134, v136, v136
	v_and_b32_e32 v136, 64, v218
	v_add_f32_e32 v134, v135, v134
	v_xor_b32_e32 v135, 16, v218
	v_add_u32_e32 v137, 64, v136
	v_cmp_lt_i32_e32 vcc, v135, v137
	v_add_f32_e32 v134, v142, v134
	v_cvt_pk_bf16_f32 v140, v140, v141
	v_cndmask_b32_e32 v135, v218, v135, vcc
	v_lshlrev_b32_e32 v136, 2, v135
	ds_bpermute_b32 v135, v136, v134
	v_cvt_pk_bf16_f32 v141, v138, v139
	global_store_dwordx2 v[174:175], v[140:141], off offset:288
	s_waitcnt lgkmcnt(0)
	v_add_f32_e32 v138, v134, v135
	v_xor_b32_e32 v134, 32, v218
	v_cmp_lt_i32_e32 vcc, v134, v137
	s_nop 1
	v_cndmask_b32_e32 v134, v218, v134, vcc
	v_lshlrev_b32_e32 v137, 2, v134
	ds_bpermute_b32 v139, v137, v138
	v_lshl_add_u64 v[134:135], v[170:171], 3, s[14:15]
	s_and_saveexec_b64 s[24:25], s[6:7]
	s_cbranch_execz .LBB0_1633
	s_waitcnt lgkmcnt(0)
	v_add_f32_e32 v138, v138, v139
	v_mul_f32_e32 v138, 0x4b800000, v138
	v_trunc_f32_e32 v138, v138
	v_mul_f32_e32 v139, 0x2f800000, v138
	v_floor_f32_e32 v139, v139
	v_fmac_f32_e32 v138, 0xcf800000, v139
	v_cvt_u32_f32_e32 v138, v138
	v_cvt_u32_f32_e32 v139, v139
	global_atomic_add_x2 v[134:135], v[138:139], off
